# speedup vs baseline: 1.0078x; 1.0078x over previous
; __device__ __forceinline__ bool tile_coords(int it, int nM, int nN, int& pm, int& pn) {
;   const int G = gridDim.x, per = G >> 3;
;   int local = (G & 7) ? (int)blockIdx.x : ((int)(blockIdx.x & 7) * per + (int)(blockIdx.x >> 3));
;   int id = it * G + local;
;   if (id >= nM * nN) return false;
;   const int nig = 8 * nN; int gid = id / nig, fm = gid * 8, gsz = min(nM - fm, 8);
;   pm = fm + ((id % nig) % gsz); pn = (id % nig) / gsz;
;   return true;
; }
; __device__ void attn_phase(const Params& p, int layer, char* shm, int wv) {
;   const bool xcd_ok = (gridDim.x & 7) == 0;
;   const int per = gridDim.x >> 3, xcd = blockIdx.x & 7, j = blockIdx.x >> 3;
;   {
;     AttnPre R0, R1; AttnTab Tb; bool have = false;
;     const int n8 = 2048 / 8;
;     for (int k = xcd_ok ? j : (int)blockIdx.x; k < (xcd_ok ? n8 : 2048); k += (xcd_ok ? per : (int)gridDim.x)) {
;       const int it = xcd_ok ? xcd * n8 + k : k;
;       const int kn = k + (xcd_ok ? per : (int)gridDim.x); const int nidx = (kn < (xcd_ok ? n8 : 2048)) ? (xcd_ok ? xcd * n8 + kn : kn) : -1;
;       attn_item<false>(p, layer, it, shm, wv, R0, R1, Tb, have, nidx); have = nidx >= 0; }
;   }
;   {
;     AttnPre R0, R1; AttnTab Tb; bool have = false;
;     const int n8 = 3072 / 8;
;     for (int k = xcd_ok ? j : (int)blockIdx.x; k < (xcd_ok ? n8 : 3072); k += (xcd_ok ? per : (int)gridDim.x)) {
;       const int it = xcd_ok ? xcd * n8 + k : k;
;       const int kn = k + (xcd_ok ? per : (int)gridDim.x); const int nidx = (kn < (xcd_ok ? n8 : 3072)) ? (xcd_ok ? xcd * n8 + kn : kn) : -1;
;       attn_item<true>(p, layer, it, shm, wv, R0, R1, Tb, have, nidx); have = nidx >= 0; }
;   }
.LBB0_47:
	s_or_b64 exec, exec, s[0:1]
	s_and_b32 s0, s57, 7
	s_and_b32 s1, s34, 7
	s_lshr_b32 s4, s57, 3
	s_cmp_eq_u32 s0, 0
	s_cselect_b32 s52, s4, s57
	s_movk_i32 s4, 0x180
	s_cselect_b32 s20, s4, 0xc00
	s_mul_i32 s4, s1, 0x180
	s_cselect_b32 s4, s4, 0
	v_writelane_b32 v253, s4, 27
	s_lshl_b32 s4, s1, 8
	s_cmp_eq_u32 s0, 0
	s_movk_i32 s30, 0x100
	s_cselect_b32 s4, s4, 0
	s_cselect_b32 s21, s30, 0x800
	v_writelane_b32 v253, s4, 28
	s_lshr_b32 s4, s34, 3
	s_cmp_eq_u32 s0, 0
	s_cselect_b32 s22, s4, s34
	s_ashr_i32 s5, s57, 3
	s_mul_i32 s1, s5, s1
	s_add_i32 s1, s1, s4
	s_cmp_eq_u32 s0, 0
	s_cselect_b32 s33, s1, s34
	s_add_u32 s58, s38, 0x3e740000
	s_addc_u32 s59, s39, 0
	s_lshl_b32 s0, s57, 3
	v_writelane_b32 v253, s0, 29
	s_lshl_b32 s0, s34, 3
	s_add_u32 s54, s38, 0x8000000
	s_addc_u32 s55, s39, 0
	s_cmpk_lt_i32 s34, 0x1700
	v_writelane_b32 v253, s0, 30
	s_cselect_b64 s[0:1], -1, 0
	v_writelane_b32 v253, s0, 31
	v_mov_b32_e32 v0, 0
	s_waitcnt lgkmcnt(0)
	v_writelane_b32 v253, s1, 32
	s_mul_hi_i32 s0, s34, 0xb21642c9
	s_add_i32 s0, s0, s34
	s_lshr_b32 s1, s0, 31
	s_ashr_i32 s0, s0, 7
	s_add_i32 s0, s0, s1
	s_lshl_b32 s1, s0, 6
	s_mulk_i32 s0, 0xb8
	v_writelane_b32 v253, s1, 33
	s_sub_i32 s0, s34, s0
	s_lshl_b32 s0, s0, 6
	v_readlane_b32 s4, v253, 11
	s_ashr_i32 s1, s0, 31
	v_readlane_b32 s6, v253, 13
	v_readlane_b32 s7, v253, 14
	v_readlane_b32 s5, v253, 12
	s_cmp_lg_u64 s[6:7], 0
	s_cselect_b64 s[4:5], -1, 0
	v_readlane_b32 s8, v253, 15
	v_readlane_b32 s9, v253, 16
	v_readlane_b32 s10, v253, 17
	v_readlane_b32 s11, v253, 18
	v_readlane_b32 s12, v253, 19
	v_readlane_b32 s13, v253, 20
	v_readlane_b32 s14, v253, 21
	v_readlane_b32 s15, v253, 22
	v_readlane_b32 s16, v253, 23
	v_readlane_b32 s17, v253, 24
	v_readlane_b32 s18, v253, 25
	v_readlane_b32 s19, v253, 26
	v_writelane_b32 v253, s4, 34
	s_barrier
	s_nop 0
	v_writelane_b32 v253, s5, 35
	s_add_u32 s4, s38, 0x2e00000
	s_addc_u32 s5, s39, 0
	v_writelane_b32 v253, s4, 36
	s_cmpk_lt_i32 s34, 0x100
	ds_read_b96 v[2:4], v0
	v_writelane_b32 v253, s5, 37
	s_cselect_b64 s[4:5], -1, 0
	v_writelane_b32 v253, s4, 38
	s_mov_b32 s63, 0
	s_mov_b32 s94, 0xfff40000
	v_writelane_b32 v253, s5, 39
	s_ashr_i32 s4, s34, 31
	s_lshr_b32 s5, s4, 27
	s_add_i32 s5, s34, s5
	s_lshl_b32 s6, s5, 1
	s_and_b32 s5, s5, 0x3ffffe0
	s_andn2_b32 s6, s6, 63
	s_sub_i32 s5, s34, s5
	v_writelane_b32 v253, s6, 40
	s_lshl_b32 s6, s5, 6
	s_ashr_i32 s7, s6, 31
	v_writelane_b32 v253, s6, 41
	v_mov_b32_e32 v195, 1
	v_mov_b32_e32 v194, 0x358637bd
	v_writelane_b32 v253, s7, 42
	s_add_u32 s6, s38, 0x3000000
	s_addc_u32 s7, s39, 0
	v_writelane_b32 v253, s6, 43
	s_cmpk_lt_i32 s34, 0x200
	v_mov_b32_e32 v244, 0x18000
	v_writelane_b32 v253, s7, 44
	s_cselect_b64 s[6:7], -1, 0
	s_add_u32 s12, s38, 0x3400000
	v_writelane_b32 v253, s6, 45
	s_addc_u32 s13, s39, 0
	s_cmpk_lt_i32 s34, 0x400
	v_writelane_b32 v253, s7, 46
	v_writelane_b32 v253, s12, 47
	s_cselect_b64 s[6:7], -1, 0
	s_add_u32 s14, s38, 0x3c00000
	v_writelane_b32 v253, s13, 48
	s_addc_u32 s15, s39, 0
	v_writelane_b32 v253, s6, 49
	s_cmpk_lt_i32 s34, 0x1000
	v_mov_b32_e32 v245, 0x8000
	v_writelane_b32 v253, s7, 50
	s_cselect_b64 s[6:7], -1, 0
	s_lshr_b32 s4, s4, 25
	v_writelane_b32 v253, s14, 51
	s_add_i32 s4, s34, s4
	s_ashr_i32 s5, s4, 7
	v_writelane_b32 v253, s15, 52
	s_and_b32 s4, s4, 0x3ffff80
	v_writelane_b32 v253, s6, 53
	s_sub_i32 s4, s34, s4
	s_lshl_b32 s5, s5, 6
	v_writelane_b32 v253, s7, 54
	s_lshl_b32 s4, s4, 6
	v_writelane_b32 v253, s5, 55
	s_ashr_i32 s5, s4, 31
	v_writelane_b32 v253, s4, 56
	v_mov_b32_e32 v246, 0x60
	v_mov_b32_e32 v247, 0x3000000
	v_writelane_b32 v253, s5, 57
	v_mov_b32_e32 v248, 0xff800000
	v_readlane_b32 s4, v253, 0
	v_readlane_b32 s6, v253, 2
	v_readlane_b32 s7, v253, 3
	v_readlane_b32 s5, v253, 1
	s_cmp_lg_u64 s[6:7], 0
	s_cselect_b64 s[4:5], -1, 0
	v_readlane_b32 s8, v253, 4
	v_readlane_b32 s9, v253, 5
	v_readlane_b32 s10, v253, 6
	v_readlane_b32 s11, v253, 7
	v_writelane_b32 v253, s4, 58
	s_add_u32 s10, s38, 0x5c00000
	s_addc_u32 s11, s39, 0
	v_writelane_b32 v253, s5, 59
	s_waitcnt lgkmcnt(0)
	v_readfirstlane_b32 s4, v2
	s_lshl_b32 s8, s4, 6
	s_mov_b32 s5, 0
	s_add_i32 s4, s8, 0x500
	s_lshl_b64 s[6:7], s[4:5], 2
	s_add_u32 s6, s2, s6
	s_addc_u32 s7, s3, s7
	s_add_i32 s4, s8, 0x900
	s_lshl_b64 s[4:5], s[4:5], 2
	s_add_u32 s2, s2, s4
	s_addc_u32 s3, s3, s5
	v_writelane_b32 v254, s2, 0
	v_writelane_b32 v253, s10, 60
	s_movk_i32 s85, 0x800
	v_writelane_b32 v254, s3, 1
	s_add_u32 s2, s38, 0x3e600200
	s_addc_u32 s3, s39, 0
	v_writelane_b32 v254, s2, 2
	v_writelane_b32 v253, s11, 61
	v_writelane_b32 v253, s6, 62
	v_writelane_b32 v254, s3, 3
	s_add_u32 s2, s38, 0x3e603400
	s_addc_u32 s3, s39, 0
	v_writelane_b32 v254, s2, 4
	v_writelane_b32 v253, s7, 63
	s_mov_b32 s53, 0x8000
	v_writelane_b32 v254, s3, 5
	s_add_u32 s2, s38, 0x3e603500
	s_addc_u32 s3, s39, 0
	v_writelane_b32 v254, s2, 6
	s_movk_i32 s97, 0x1800
	s_mov_b32 s80, 0x800000
	v_writelane_b32 v254, s3, 7
	s_add_u32 s2, s38, 0x2e000000
	s_addc_u32 s3, s39, 0
	v_writelane_b32 v254, s2, 8
	s_movk_i32 s81, 0x2400
	s_mov_b32 s40, 0xc3070000
	v_writelane_b32 v254, s3, 9
	s_add_u32 s2, s38, 0x22000000
	s_addc_u32 s3, s39, 0
	s_add_u32 s86, s38, 0x10000000
	v_writelane_b32 v254, s2, 10
	s_addc_u32 s87, s39, 0
	s_cmp_lt_i32 s22, s21
	v_writelane_b32 v254, s3, 11
	v_writelane_b32 v254, s21, 12
	s_cselect_b64 s[2:3], -1, 0
	v_writelane_b32 v254, s2, 13
	s_cmp_lt_i32 s22, s20
	s_mov_b32 s42, 0xff800000
	v_writelane_b32 v254, s3, 14
	v_writelane_b32 v254, s20, 15
	v_writelane_b32 v254, s22, 16
	s_cselect_b64 s[2:3], -1, 0
	v_writelane_b32 v254, s2, 17
; __device__ __forceinline__ bool tile_coords(int it, int nM, int nN, int& pm, int& pn) {
;   const int G = gridDim.x, per = G >> 3;
;   int local = (G & 7) ? (int)blockIdx.x : ((int)(blockIdx.x & 7) * per + (int)(blockIdx.x >> 3));
;   int id = it * G + local;
;   if (id >= nM * nN) return false;
;   const int nig = 8 * nN; int gid = id / nig, fm = gid * 8, gsz = min(nM - fm, 8);
;   pm = fm + ((id % nig) % gsz); pn = (id % nig) / gsz;
;   return true;
; }
; template <int EPI>
; __device__ void gemm_phase(const bf16* A, int lda, const bf16* Bt, int K, int N, const Params& p, bool last, bf16* dstb, bf16* shm, unsigned long long* SSQ, int wv, const float* gbias = nullptr) {
;     ...
;         unsigned char* gt = (unsigned char*)(p.ws + OFF_G) + ((size_t)(brow / BM) * 16 + (c0 >> 8)) * 65536 + tid * 4;
;         asm volatile("s_waitcnt vmcnt(0)" ::: "memory");
;         _Pragma("unroll") for (int ai = 0; ai < 2; ++ai) _Pragma("unroll") for (int m = 0; m < 4; ++m) {
;           const float rs = rsv[ai][m];
;           _Pragma("unroll") for (int bj = 0; bj < 2; ++bj) _Pragma("unroll") for (int n = 0; n < 2; ++n) {
;             const f32x4 bb = gbv[bj][n];
;             f32x4 v = acc[ai][bj][m][n] * rs + bb; unsigned q = 0;
;             for (int j = 0; j < 4; ++j) {
;               const float gsig = __builtin_amdgcn_rcpf(1.f + __builtin_amdgcn_exp2f(-1.4426950408889634f * v[j]));
;               q |= (unsigned)(gsig * 255.f + 0.5f) << (8 * j); }
	s_movk_i32 s43, 0x7e
	s_mov_b32 s22, 0
	v_writelane_b32 v254, s3, 18
	s_add_u32 s2, s38, 0x3e400000
	s_addc_u32 s3, s39, 0
	v_writelane_b32 v254, s2, 19
	s_mov_b64 s[18:19], -1
	s_mov_b32 s90, 0x437f0000
	v_writelane_b32 v254, s3, 20
	s_add_u32 s2, s38, 0x3e700000
	s_addc_u32 s3, s39, 0
	v_writelane_b32 v254, s2, 21
	s_mov_b32 s95, -1
	s_brev_b32 s84, 60
	v_writelane_b32 v254, s3, 22
	s_lshl_b32 s2, s57, 9
	s_add_u32 s8, s38, 0x36000000
	v_writelane_b32 v254, s2, 23
	s_addc_u32 s9, s39, 0
	v_writelane_b32 v254, s8, 24
	s_cmpk_lt_i32 s33, 0x400
	v_writelane_b32 v254, s9, 25
	s_cselect_b64 s[2:3], -1, 0
	v_writelane_b32 v254, s2, 26
	s_mov_b32 s56, 0x3b808081
	s_mov_b32 s20, s63
	v_writelane_b32 v254, s3, 27
	s_ashr_i32 s2, s33, 31
	s_lshr_b32 s3, s2, 26
	s_add_i32 s3, s33, s3
	s_and_b32 s4, s3, 0xffc0
	s_sub_i32 s4, s33, s4
	s_bfe_i32 s5, s4, 0x80000
	s_bfe_u32 s5, s5, 0x3000c
	s_add_i32 s5, s4, s5
	s_and_b32 s6, s5, 0xf8
	s_sub_i32 s4, s4, s6
	s_ashr_i32 s3, s3, 6
	s_lshl_b32 s3, s3, 3
	s_sext_i32_i8 s4, s4
	s_add_i32 s6, s3, s4
	s_bfe_i32 s3, s5, 0x80000
	s_sext_i32_i16 s3, s3
	s_ashr_i32 s7, s3, 3
	s_cmpk_lt_i32 s33, 0x1000
	s_cselect_b64 s[4:5], -1, 0
	s_lshr_b32 s2, s2, 24
	s_add_i32 s2, s33, s2
	s_and_b32 s3, s2, 0xff00
	v_writelane_b32 v254, s4, 28
	s_sub_i32 s3, s33, s3
	s_ashr_i32 s2, s2, 8
	v_writelane_b32 v254, s5, 29
	s_sext_i32_i16 s4, s3
	s_bfe_u32 s4, s4, 0x3001c
	s_add_i32 s4, s3, s4
	s_and_b32 s5, s4, 0xfff8
	s_sub_i32 s3, s3, s5
	s_lshl_b32 s2, s2, 3
	s_sext_i32_i16 s3, s3
	s_add_i32 s3, s2, s3
	s_sext_i32_i16 s2, s4
	s_ashr_i32 s4, s2, 3
	s_lshl_b32 s2, s3, 8
	v_writelane_b32 v254, s3, 30
	s_ashr_i32 s3, s2, 31
	s_lshl_b64 s[2:3], s[2:3], 12
	v_writelane_b32 v254, s4, 31
	s_lshl_b32 s4, s4, 8
	s_add_u32 s16, s54, s2
	s_addc_u32 s17, s55, s3
	s_ashr_i32 s5, s4, 31
	s_lshl_b64 s[2:3], s[4:5], 12
	s_add_u32 s2, s14, s2
	s_addc_u32 s3, s15, s3
	s_add_u32 s4, s2, 0x80000
	v_writelane_b32 v254, s2, 32
	s_addc_u32 s5, s3, 0
	s_nop 0
	v_writelane_b32 v254, s3, 33
	v_writelane_b32 v254, s4, 34
	s_add_u32 s2, s16, 0x80000
	s_barrier
	v_writelane_b32 v254, s5, 35
	v_writelane_b32 v254, s16, 36
	s_addc_u32 s3, s17, 0
	s_cmpk_lt_i32 s33, 0x1700
	v_writelane_b32 v254, s17, 37
	v_writelane_b32 v254, s2, 38
	s_cselect_b64 s[4:5], -1, 0
	s_nop 0
	v_writelane_b32 v254, s3, 39
	s_mul_hi_i32 s2, s33, 0xb21642c9
	s_add_i32 s2, s2, s33
	s_lshr_b32 s3, s2, 31
	s_ashr_i32 s2, s2, 8
	s_add_i32 s2, s2, s3
	s_mul_i32 s3, s2, 0x170
	v_writelane_b32 v254, s4, 40
	s_sub_i32 s3, s33, s3
	s_lshl_b32 s2, s2, 3
	v_writelane_b32 v254, s5, 41
	s_bfe_u32 s4, s3, 0x3001c
	s_add_i32 s4, s3, s4
	s_and_b32 s5, s4, 0xfff8
	s_sub_i32 s3, s3, s5
	s_sext_i32_i16 s3, s3
	s_add_i32 s3, s2, s3
	s_sext_i32_i16 s2, s4
	s_ashr_i32 s4, s2, 3
	s_lshl_b32 s2, s3, 8
	v_writelane_b32 v254, s3, 42
	s_ashr_i32 s3, s2, 31
	s_lshl_b64 s[2:3], s[2:3], 12
	v_writelane_b32 v254, s4, 43
	s_lshl_b32 s4, s4, 8
	s_add_u32 s14, s54, s2
	s_addc_u32 s15, s55, s3
	s_ashr_i32 s5, s4, 31
	s_lshl_b64 s[2:3], s[4:5], 12
	s_add_u32 s2, s38, s2
	s_addc_u32 s3, s39, s3
	s_add_u32 s4, s2, 0x80000
	v_writelane_b32 v254, s2, 44
	s_addc_u32 s5, s3, 0
	s_nop 0
	v_writelane_b32 v254, s3, 45
	v_writelane_b32 v254, s4, 46
	s_add_u32 s2, s14, 0x80000
	s_nop 0
	v_writelane_b32 v254, s5, 47
	v_writelane_b32 v254, s14, 48
	s_addc_u32 s3, s15, 0
	s_lshl_b32 s4, s7, 8
	v_writelane_b32 v254, s15, 49
	v_writelane_b32 v254, s2, 50
	s_nop 1
	v_writelane_b32 v254, s3, 51
	s_lshl_b32 s2, s6, 8
	v_writelane_b32 v254, s6, 52
	s_ashr_i32 s3, s2, 31
	v_writelane_b32 v254, s7, 53
	s_lshl_b64 s[6:7], s[2:3], 12
	s_add_u32 s8, s8, s6
	s_addc_u32 s9, s9, s7
	s_ashr_i32 s5, s4, 31
	s_lshl_b64 s[6:7], s[4:5], 12
	s_add_u32 s6, s12, s6
	s_addc_u32 s7, s13, s7
	s_add_u32 s12, s6, 0x80000
	v_writelane_b32 v254, s6, 54
	s_addc_u32 s13, s7, 0
	s_nop 0
	v_writelane_b32 v254, s7, 55
	v_writelane_b32 v254, s12, 56
	s_add_u32 s6, s8, 0x80000
	s_nop 0
	v_writelane_b32 v254, s13, 57
	v_writelane_b32 v254, s8, 58
	s_addc_u32 s7, s9, 0
	s_lshl_b64 s[2:3], s[2:3], 14
	v_writelane_b32 v254, s9, 59
	v_writelane_b32 v254, s6, 60
	s_nop 1
	v_writelane_b32 v254, s7, 61
	s_add_u32 s6, s86, s2
	s_addc_u32 s7, s87, s3
	s_lshl_b64 s[2:3], s[4:5], 14
	s_add_u32 s2, s10, s2
	s_addc_u32 s3, s11, s3
	s_add_u32 s4, s2, 0x200000
	v_writelane_b32 v254, s2, 62
	s_addc_u32 s5, s3, 0
	v_writelane_b32 v252, s4, 0
	v_writelane_b32 v254, s3, 63
	s_add_u32 s2, s6, 0x200000
	v_writelane_b32 v252, s5, 1
	v_writelane_b32 v252, s6, 2
	s_addc_u32 s3, s7, 0
	s_nop 0
	v_writelane_b32 v252, s7, 3
	v_writelane_b32 v252, s2, 4
	s_nop 1
	v_writelane_b32 v252, s3, 5
	s_lshl_b32 s2, s34, 6
	v_writelane_b32 v252, s2, 6
	s_add_u32 s2, s38, 0x21f40000
	v_writelane_b32 v252, s2, 7
	s_addc_u32 s2, s39, 0
	v_writelane_b32 v252, s2, 8
	s_lshl_b64 s[0:1], s[0:1], 2
	v_writelane_b32 v252, s0, 9
	s_add_i32 s46, 0, 0x18000
	s_add_i32 s92, 0, 0x1c000
	v_writelane_b32 v252, s1, 10
	v_readfirstlane_b32 s0, v3
	s_add_i32 s93, 0, 0x10000
	s_add_i32 s96, 0, 0x14000
	v_writelane_b32 v252, s0, 11
	v_readfirstlane_b32 s0, v4
	s_add_i32 s41, 0, 0x10010
	s_mov_b64 s[2:3], 0x2000
	v_writelane_b32 v252, s0, 12
	s_lshl_b32 s0, s34, 12
	v_writelane_b32 v252, s0, 13
	s_lshl_b32 s0, s57, 13
	v_writelane_b32 v252, s0, 14
	v_writelane_b32 v252, s44, 15
	s_nop 1
	v_writelane_b32 v252, s45, 16
	v_writelane_b32 v252, s36, 17
	s_nop 1
	v_writelane_b32 v252, s37, 18
	v_writelane_b32 v252, s38, 19
	v_writelane_b32 v252, s39, 20
	v_writelane_b32 v252, s54, 21
	s_nop 1
	v_writelane_b32 v252, s55, 22
	v_writelane_b32 v252, s34, 23
	s_branch .LBB0_51

;   #define LDA(dst,b,h) for(int m=0;m<4;++m)for(int k=0;k<2;++k) \
;     dst[m][k]=*reinterpret_cast<const bf16x8*>((char*)SA(b,h)+lds_byte(wr*64+m*16+fr,k*32+fq*8))
;   #define LDB(dst,b,h) for(int n=0;n<2;++n)for(int k=0;k<2;++k) \
;     dst[n][k]=*reinterpret_cast<const bf16x8*>((char*)SB(b,h)+lds_byte(wc*32+n*16+fr,k*32+fq*8))
;   #define MMA(ai,bj,At,Bt_) do{__builtin_amdgcn_s_setprio(1); \
;     for(int m=0;m<4;++m)for(int n=0;n<2;++n)for(int k=0;k<2;++k) \
;       acc[ai][bj][m][n]=__builtin_amdgcn_mfma_f32_16x16x32_bf16(Bt_[n][k],At[m][k],acc[ai][bj][m][n],0,0,0); \
;     __builtin_amdgcn_s_setprio(0);}while(0)
;   #define WAIT_V(n) asm volatile("s_waitcnt vmcnt(" #n ")":::"memory")
;   #define WAIT_L(n) asm volatile("s_waitcnt lgkmcnt(" #n ")":::"memory")
;   #define BAR __builtin_amdgcn_s_barrier()
;   #define SCHED __builtin_amdgcn_sched_barrier(0)
; template <bool TWO, class MID> ...
;     ...
;     LDB(B0,0,0); SCHED; LDA(At,0,0); STAGE_A(SA(1,1),1,t+1);
;     WAIT_L(8); BAR; WAIT_L(0); MMA(0,0,At,B0); BAR; SCHED;
;     LDB(B1,0,1); STAGE_B(SB(0,0),0,t+2);
;     BAR; WAIT_L(0); MMA(0,1,At,B1); BAR;
;     LDA(At,0,1); STAGE_A(SA(0,0),0,t+2);
;     BAR; WAIT_L(0); MMA(1,0,At,B0); BAR; SCHED;
;     STAGE_B(SB(0,1),1,t+2);
;     WAIT_V(6); BAR; MMA(1,1,At,B1); BAR;
;     LDB(B0,1,0); SCHED; LDA(At,1,0); STAGE_A(SA(0,1),1,t+2);
;     WAIT_L(8); BAR; WAIT_L(0); MMA(0,0,At,B0); BAR; SCHED;
.LBB0_169:
	ds_read_b128 v[170:173], v143
	ds_read_b128 v[174:177], v143 offset:1024
	ds_read_b128 v[178:181], v143 offset:2048
	ds_read_b128 v[182:185], v143 offset:3072
	ds_read_b128 v[186:189], v168
	ds_read_b128 v[190:193], v168 offset:1024
	ds_read_b128 v[196:199], v167
	ds_read_b128 v[200:203], v167 offset:1024
	ds_read_b128 v[204:207], v166
	ds_read_b128 v[208:211], v166 offset:1024
	ds_read_b128 v[212:215], v147
	ds_read_b128 v[216:219], v147 offset:1024
	s_add_u32 s17, s0, s12
	s_addc_u32 s18, s1, s13
	s_add_u32 s20, s17, 0x8080080
	s_addc_u32 s21, s18, 0
	v_lshl_add_u64 v[220:221], s[20:21], 0, v[132:133]
	v_readfirstlane_b32 s19, v148
	s_mov_b32 m0, s19
	global_load_lds_dwordx4 v[220:221], off
	v_lshl_add_u64 v[220:221], s[20:21], 0, v[130:131]
	v_readfirstlane_b32 s19, v156
	s_mov_b32 m0, s19
	global_load_lds_dwordx4 v[220:221], off
	s_waitcnt lgkmcnt(8)
	s_barrier
	s_waitcnt lgkmcnt(0)
	s_setprio 1
	v_mfma_f32_16x16x32_bf16 v[126:129], v[170:173], v[186:189], v[126:129]
	v_mfma_f32_16x16x32_bf16 v[122:125], v[178:181], v[186:189], v[122:125]
	v_mfma_f32_16x16x32_bf16 v[118:121], v[170:173], v[196:199], v[118:121]
	v_mfma_f32_16x16x32_bf16 v[114:117], v[178:181], v[196:199], v[114:117]
	v_mfma_f32_16x16x32_bf16 v[110:113], v[170:173], v[204:207], v[110:113]
	v_mfma_f32_16x16x32_bf16 v[106:109], v[178:181], v[204:207], v[106:109]
	v_mfma_f32_16x16x32_bf16 v[102:105], v[170:173], v[212:215], v[102:105]
	v_mfma_f32_16x16x32_bf16 v[98:101], v[178:181], v[212:215], v[98:101]
	v_mfma_f32_16x16x32_bf16 v[126:129], v[174:177], v[190:193], v[126:129]
	v_mfma_f32_16x16x32_bf16 v[122:125], v[182:185], v[190:193], v[122:125]
	v_mfma_f32_16x16x32_bf16 v[118:121], v[174:177], v[200:203], v[118:121]
	v_mfma_f32_16x16x32_bf16 v[114:117], v[182:185], v[200:203], v[114:117]
	v_mfma_f32_16x16x32_bf16 v[110:113], v[174:177], v[208:211], v[110:113]
	v_mfma_f32_16x16x32_bf16 v[106:109], v[182:185], v[208:211], v[106:109]
	v_mfma_f32_16x16x32_bf16 v[102:105], v[174:177], v[216:219], v[102:105]
	v_mfma_f32_16x16x32_bf16 v[98:101], v[182:185], v[216:219], v[98:101]
	s_setprio 0
	s_barrier
	s_add_u32 s19, s0, s14
	ds_read_b128 v[220:223], v141
	ds_read_b128 v[224:227], v141 offset:1024
	ds_read_b128 v[228:231], v141 offset:2048
	ds_read_b128 v[232:235], v141 offset:3072
	s_addc_u32 s20, s1, s15
	s_add_u32 s26, s19, 0x100
	s_addc_u32 s27, s20, 0
	v_lshl_add_u64 v[236:237], s[26:27], 0, v[132:133]
	v_readfirstlane_b32 s21, v150
	s_mov_b32 m0, s21
	global_load_lds_dwordx4 v[236:237], off
	v_lshl_add_u64 v[236:237], s[26:27], 0, v[130:131]
	v_readfirstlane_b32 s21, v158
	s_mov_b32 m0, s21
	global_load_lds_dwordx4 v[236:237], off
	s_barrier
	s_waitcnt lgkmcnt(0)
	s_setprio 1
	v_mfma_f32_16x16x32_bf16 v[94:97], v[220:223], v[186:189], v[94:97]
	v_mfma_f32_16x16x32_bf16 v[90:93], v[228:231], v[186:189], v[90:93]
	v_mfma_f32_16x16x32_bf16 v[86:89], v[220:223], v[196:199], v[86:89]
	v_mfma_f32_16x16x32_bf16 v[82:85], v[228:231], v[196:199], v[82:85]
	v_mfma_f32_16x16x32_bf16 v[78:81], v[220:223], v[204:207], v[78:81]
	v_mfma_f32_16x16x32_bf16 v[74:77], v[228:231], v[204:207], v[74:77]
	v_mfma_f32_16x16x32_bf16 v[70:73], v[220:223], v[212:215], v[70:73]
	v_mfma_f32_16x16x32_bf16 v[66:69], v[228:231], v[212:215], v[66:69]
	v_mfma_f32_16x16x32_bf16 v[94:97], v[224:227], v[190:193], v[94:97]
	v_mfma_f32_16x16x32_bf16 v[90:93], v[232:235], v[190:193], v[90:93]
	v_mfma_f32_16x16x32_bf16 v[86:89], v[224:227], v[200:203], v[86:89]
	v_mfma_f32_16x16x32_bf16 v[82:85], v[232:235], v[200:203], v[82:85]
	v_mfma_f32_16x16x32_bf16 v[78:81], v[224:227], v[208:211], v[78:81]
	v_mfma_f32_16x16x32_bf16 v[74:77], v[232:235], v[208:211], v[74:77]
	v_mfma_f32_16x16x32_bf16 v[70:73], v[224:227], v[216:219], v[70:73]
	v_mfma_f32_16x16x32_bf16 v[66:69], v[232:235], v[216:219], v[66:69]
	s_setprio 0
	s_barrier
	ds_read_b128 v[186:189], v168 offset:16384
	ds_read_b128 v[190:193], v168 offset:17408
	ds_read_b128 v[196:199], v167 offset:16384
	ds_read_b128 v[200:203], v167 offset:17408
	ds_read_b128 v[204:207], v166 offset:16384
	ds_read_b128 v[208:211], v166 offset:17408
	ds_read_b128 v[212:215], v147 offset:16384
	ds_read_b128 v[216:219], v147 offset:17408
	s_add_u32 s26, s17, 0x8000100
	s_addc_u32 s27, s18, 0
	v_lshl_add_u64 v[236:237], s[26:27], 0, v[132:133]
	v_readfirstlane_b32 s21, v138
	s_mov_b32 m0, s21
	global_load_lds_dwordx4 v[236:237], off
	v_lshl_add_u64 v[236:237], s[26:27], 0, v[130:131]
	v_readfirstlane_b32 s21, v160
	s_mov_b32 m0, s21
	global_load_lds_dwordx4 v[236:237], off
	s_barrier
	s_waitcnt lgkmcnt(0)
	s_setprio 1
	v_mfma_f32_16x16x32_bf16 v[62:65], v[170:173], v[186:189], v[62:65]
	v_mfma_f32_16x16x32_bf16 v[58:61], v[178:181], v[186:189], v[58:61]
	v_mfma_f32_16x16x32_bf16 v[54:57], v[170:173], v[196:199], v[54:57]
	v_mfma_f32_16x16x32_bf16 v[50:53], v[178:181], v[196:199], v[50:53]
	v_mfma_f32_16x16x32_bf16 v[46:49], v[170:173], v[204:207], v[46:49]
	v_mfma_f32_16x16x32_bf16 v[42:45], v[178:181], v[204:207], v[42:45]
	v_mfma_f32_16x16x32_bf16 v[38:41], v[170:173], v[212:215], v[38:41]
	v_mfma_f32_16x16x32_bf16 v[34:37], v[178:181], v[212:215], v[34:37]
	v_mfma_f32_16x16x32_bf16 v[62:65], v[174:177], v[190:193], v[62:65]
	v_mfma_f32_16x16x32_bf16 v[58:61], v[182:185], v[190:193], v[58:61]
	v_mfma_f32_16x16x32_bf16 v[54:57], v[174:177], v[200:203], v[54:57]
	v_mfma_f32_16x16x32_bf16 v[50:53], v[182:185], v[200:203], v[50:53]
	v_mfma_f32_16x16x32_bf16 v[46:49], v[174:177], v[208:211], v[46:49]
	v_mfma_f32_16x16x32_bf16 v[42:45], v[182:185], v[208:211], v[42:45]
	v_mfma_f32_16x16x32_bf16 v[38:41], v[174:177], v[216:219], v[38:41]
	v_mfma_f32_16x16x32_bf16 v[34:37], v[182:185], v[216:219], v[34:37]
	s_setprio 0
	s_barrier
;   #define LDA(dst,b,h) for(int m=0;m<4;++m)for(int k=0;k<2;++k) \
;     dst[m][k]=*reinterpret_cast<const bf16x8*>((char*)SA(b,h)+lds_byte(wr*64+m*16+fr,k*32+fq*8))
;   #define LDB(dst,b,h) for(int n=0;n<2;++n)for(int k=0;k<2;++k) \
;     dst[n][k]=*reinterpret_cast<const bf16x8*>((char*)SB(b,h)+lds_byte(wc*32+n*16+fr,k*32+fq*8))
;   #define MMA(ai,bj,At,Bt_) do{__builtin_amdgcn_s_setprio(1); \
;     for(int m=0;m<4;++m)for(int n=0;n<2;++n)for(int k=0;k<2;++k) \
;       acc[ai][bj][m][n]=__builtin_amdgcn_mfma_f32_16x16x32_bf16(Bt_[n][k],At[m][k],acc[ai][bj][m][n],0,0,0); \
;     __builtin_amdgcn_s_setprio(0);}while(0)
;   #define WAIT_V(n) asm volatile("s_waitcnt vmcnt(" #n ")":::"memory")
;   #define WAIT_L(n) asm volatile("s_waitcnt lgkmcnt(" #n ")":::"memory")
;   #define BAR __builtin_amdgcn_s_barrier()
;   #define SCHED __builtin_amdgcn_sched_barrier(0)
; template <bool TWO, class MID> ...
;     ...
;     STAGE_B(SB(0,1),1,t+2);
;     WAIT_V(6); BAR; MMA(1,1,At,B1); BAR;
;     LDB(B0,1,0); SCHED; LDA(At,1,0); STAGE_A(SA(0,1),1,t+2);
;     WAIT_L(8); BAR; WAIT_L(0); MMA(0,0,At,B0); BAR; SCHED;
;     LDB(B1,1,1); STAGE_B(SB(1,0),0,t+3);
;     BAR; WAIT_L(0); MMA(0,1,At,B1); BAR;
;     LDA(At,1,1); STAGE_A(SA(1,0),0,t+3);
;     BAR; WAIT_L(0); MMA(1,0,At,B0); BAR; SCHED;
	s_add_u32 s26, s19, 0x80100
	s_addc_u32 s27, s20, 0
	v_lshl_add_u64 v[170:171], s[26:27], 0, v[132:133]
	v_readfirstlane_b32 s21, v152
	s_mov_b32 m0, s21
	global_load_lds_dwordx4 v[170:171], off
	v_lshl_add_u64 v[170:171], s[26:27], 0, v[130:131]
	v_readfirstlane_b32 s21, v162
	s_mov_b32 m0, s21
	global_load_lds_dwordx4 v[170:171], off
	s_waitcnt vmcnt(6)
	s_barrier
	s_setprio 1
	v_mfma_f32_16x16x32_bf16 v[30:33], v[220:223], v[186:189], v[30:33]
	v_mfma_f32_16x16x32_bf16 v[26:29], v[228:231], v[186:189], v[26:29]
	v_mfma_f32_16x16x32_bf16 v[22:25], v[220:223], v[196:199], v[22:25]
	v_mfma_f32_16x16x32_bf16 v[18:21], v[228:231], v[196:199], v[18:21]
	v_mfma_f32_16x16x32_bf16 v[14:17], v[220:223], v[204:207], v[14:17]
	v_mfma_f32_16x16x32_bf16 v[10:13], v[228:231], v[204:207], v[10:13]
	v_mfma_f32_16x16x32_bf16 v[6:9], v[220:223], v[212:215], v[6:9]
	v_mfma_f32_16x16x32_bf16 v[2:5], v[228:231], v[212:215], v[2:5]
	v_mfma_f32_16x16x32_bf16 v[30:33], v[224:227], v[190:193], v[30:33]
	v_mfma_f32_16x16x32_bf16 v[26:29], v[232:235], v[190:193], v[26:29]
	v_mfma_f32_16x16x32_bf16 v[22:25], v[224:227], v[200:203], v[22:25]
	v_mfma_f32_16x16x32_bf16 v[18:21], v[232:235], v[200:203], v[18:21]
	v_mfma_f32_16x16x32_bf16 v[14:17], v[224:227], v[208:211], v[14:17]
	v_mfma_f32_16x16x32_bf16 v[10:13], v[232:235], v[208:211], v[10:13]
	v_mfma_f32_16x16x32_bf16 v[6:9], v[224:227], v[216:219], v[6:9]
	v_mfma_f32_16x16x32_bf16 v[2:5], v[232:235], v[216:219], v[2:5]
	s_setprio 0
	s_barrier
	ds_read_b128 v[170:173], v137
	ds_read_b128 v[174:177], v137 offset:1024
	ds_read_b128 v[178:181], v137 offset:2048
	ds_read_b128 v[182:185], v137 offset:3072
	ds_read_b128 v[186:189], v168 offset:32768
	ds_read_b128 v[190:193], v168 offset:33792
	ds_read_b128 v[196:199], v167 offset:32768
	ds_read_b128 v[200:203], v167 offset:33792
	ds_read_b128 v[204:207], v166 offset:32768
	ds_read_b128 v[208:211], v166 offset:33792
	ds_read_b128 v[212:215], v147 offset:32768
	ds_read_b128 v[216:219], v147 offset:33792
	s_add_u32 s26, s17, 0x8080100
	s_addc_u32 s27, s18, 0
	v_lshl_add_u64 v[220:221], s[26:27], 0, v[132:133]
	v_readfirstlane_b32 s21, v154
	s_mov_b32 m0, s21
	global_load_lds_dwordx4 v[220:221], off
	v_lshl_add_u64 v[220:221], s[26:27], 0, v[130:131]
	v_readfirstlane_b32 s21, v164
	s_mov_b32 m0, s21
	global_load_lds_dwordx4 v[220:221], off
	s_waitcnt lgkmcnt(8)
	s_barrier
	s_waitcnt lgkmcnt(0)
	s_setprio 1
	v_mfma_f32_16x16x32_bf16 v[126:129], v[170:173], v[186:189], v[126:129]
	v_mfma_f32_16x16x32_bf16 v[122:125], v[178:181], v[186:189], v[122:125]
	v_mfma_f32_16x16x32_bf16 v[118:121], v[170:173], v[196:199], v[118:121]
	v_mfma_f32_16x16x32_bf16 v[114:117], v[178:181], v[196:199], v[114:117]
	v_mfma_f32_16x16x32_bf16 v[110:113], v[170:173], v[204:207], v[110:113]
	v_mfma_f32_16x16x32_bf16 v[106:109], v[178:181], v[204:207], v[106:109]
	v_mfma_f32_16x16x32_bf16 v[102:105], v[170:173], v[212:215], v[102:105]
	v_mfma_f32_16x16x32_bf16 v[98:101], v[178:181], v[212:215], v[98:101]
	v_mfma_f32_16x16x32_bf16 v[126:129], v[174:177], v[190:193], v[126:129]
	v_mfma_f32_16x16x32_bf16 v[122:125], v[182:185], v[190:193], v[122:125]
	v_mfma_f32_16x16x32_bf16 v[118:121], v[174:177], v[200:203], v[118:121]
	v_mfma_f32_16x16x32_bf16 v[114:117], v[182:185], v[200:203], v[114:117]
	v_mfma_f32_16x16x32_bf16 v[110:113], v[174:177], v[208:211], v[110:113]
	v_mfma_f32_16x16x32_bf16 v[106:109], v[182:185], v[208:211], v[106:109]
	v_mfma_f32_16x16x32_bf16 v[102:105], v[174:177], v[216:219], v[102:105]
	v_mfma_f32_16x16x32_bf16 v[98:101], v[182:185], v[216:219], v[98:101]
	s_setprio 0
	s_barrier
	ds_read_b128 v[220:223], v135
	ds_read_b128 v[224:227], v135 offset:1024
	ds_read_b128 v[228:231], v135 offset:2048
	ds_read_b128 v[232:235], v135 offset:3072
	s_add_u32 s26, s19, 0x180
	s_addc_u32 s27, s20, 0
	v_lshl_add_u64 v[236:237], s[26:27], 0, v[132:133]
	v_readfirstlane_b32 s21, v134
	s_mov_b32 m0, s21
	global_load_lds_dwordx4 v[236:237], off
	v_lshl_add_u64 v[236:237], s[26:27], 0, v[130:131]
	v_readfirstlane_b32 s21, v136
	s_mov_b32 m0, s21
	global_load_lds_dwordx4 v[236:237], off
	s_barrier
	s_waitcnt lgkmcnt(0)
	s_setprio 1
	v_mfma_f32_16x16x32_bf16 v[94:97], v[220:223], v[186:189], v[94:97]
	v_mfma_f32_16x16x32_bf16 v[90:93], v[228:231], v[186:189], v[90:93]
	v_mfma_f32_16x16x32_bf16 v[86:89], v[220:223], v[196:199], v[86:89]
	v_mfma_f32_16x16x32_bf16 v[82:85], v[228:231], v[196:199], v[82:85]
	v_mfma_f32_16x16x32_bf16 v[78:81], v[220:223], v[204:207], v[78:81]
	v_mfma_f32_16x16x32_bf16 v[74:77], v[228:231], v[204:207], v[74:77]
	v_mfma_f32_16x16x32_bf16 v[70:73], v[220:223], v[212:215], v[70:73]
	v_mfma_f32_16x16x32_bf16 v[66:69], v[228:231], v[212:215], v[66:69]
	v_mfma_f32_16x16x32_bf16 v[94:97], v[224:227], v[190:193], v[94:97]
	v_mfma_f32_16x16x32_bf16 v[90:93], v[232:235], v[190:193], v[90:93]
	v_mfma_f32_16x16x32_bf16 v[86:89], v[224:227], v[200:203], v[86:89]
	v_mfma_f32_16x16x32_bf16 v[82:85], v[232:235], v[200:203], v[82:85]
	v_mfma_f32_16x16x32_bf16 v[78:81], v[224:227], v[208:211], v[78:81]
	v_mfma_f32_16x16x32_bf16 v[74:77], v[232:235], v[208:211], v[74:77]
	v_mfma_f32_16x16x32_bf16 v[70:73], v[224:227], v[216:219], v[70:73]
	v_mfma_f32_16x16x32_bf16 v[66:69], v[232:235], v[216:219], v[66:69]
	s_setprio 0
	s_barrier
	ds_read_b128 v[186:189], v168 offset:49152
	ds_read_b128 v[190:193], v168 offset:50176
	ds_read_b128 v[196:199], v167 offset:49152
	ds_read_b128 v[200:203], v167 offset:50176
	ds_read_b128 v[204:207], v166 offset:49152
	ds_read_b128 v[208:211], v166 offset:50176
	ds_read_b128 v[212:215], v147 offset:49152
	ds_read_b128 v[216:219], v147 offset:50176
	s_add_u32 s26, s17, 0x8000180
	s_addc_u32 s27, s18, 0
	v_lshl_add_u64 v[236:237], s[26:27], 0, v[132:133]
	v_readfirstlane_b32 s17, v140
	s_mov_b32 m0, s17
	global_load_lds_dwordx4 v[236:237], off
	v_lshl_add_u64 v[236:237], s[26:27], 0, v[130:131]
	v_readfirstlane_b32 s17, v142
	s_mov_b32 m0, s17
	global_load_lds_dwordx4 v[236:237], off
	s_barrier
;   #define LDA(dst,b,h) for(int m=0;m<4;++m)for(int k=0;k<2;++k) \
;     dst[m][k]=*reinterpret_cast<const bf16x8*>((char*)SA(b,h)+lds_byte(wr*64+m*16+fr,k*32+fq*8))
;   #define LDB(dst,b,h) for(int n=0;n<2;++n)for(int k=0;k<2;++k) \
;     dst[n][k]=*reinterpret_cast<const bf16x8*>((char*)SB(b,h)+lds_byte(wc*32+n*16+fr,k*32+fq*8))
;   #define MMA(ai,bj,At,Bt_) do{__builtin_amdgcn_s_setprio(1); \
;     for(int m=0;m<4;++m)for(int n=0;n<2;++n)for(int k=0;k<2;++k) \
;       acc[ai][bj][m][n]=__builtin_amdgcn_mfma_f32_16x16x32_bf16(Bt_[n][k],At[m][k],acc[ai][bj][m][n],0,0,0); \
;     __builtin_amdgcn_s_setprio(0);}while(0)
;   #define WAIT_V(n) asm volatile("s_waitcnt vmcnt(" #n ")":::"memory")
;   #define WAIT_L(n) asm volatile("s_waitcnt lgkmcnt(" #n ")":::"memory")
;   #define BAR __builtin_amdgcn_s_barrier()
;   #define SCHED __builtin_amdgcn_sched_barrier(0)
; template <bool TWO, class MID> ...
;     ...
;     BAR; WAIT_L(0); MMA(1,0,At,B0); BAR; SCHED;
;     STAGE_B(SB(1,1),1,t+3);
;     WAIT_V(6); BAR; MMA(1,1,At,B1); BAR;
;   }
;   { LDB(B0,0,0); LDA(At,0,0); STAGE_A(SA(1,1),1,nt-1);
;     BAR; WAIT_L(0); MMA(0,0,At,B0); BAR;
;     LDB(B1,0,1); BAR; WAIT_L(0); MMA(0,1,At,B1); BAR;
	s_waitcnt lgkmcnt(0)
	s_setprio 1
	v_mfma_f32_16x16x32_bf16 v[62:65], v[170:173], v[186:189], v[62:65]
	v_mfma_f32_16x16x32_bf16 v[58:61], v[178:181], v[186:189], v[58:61]
	v_mfma_f32_16x16x32_bf16 v[54:57], v[170:173], v[196:199], v[54:57]
	v_mfma_f32_16x16x32_bf16 v[50:53], v[178:181], v[196:199], v[50:53]
	v_mfma_f32_16x16x32_bf16 v[46:49], v[170:173], v[204:207], v[46:49]
	v_mfma_f32_16x16x32_bf16 v[42:45], v[178:181], v[204:207], v[42:45]
	v_mfma_f32_16x16x32_bf16 v[38:41], v[170:173], v[212:215], v[38:41]
	v_mfma_f32_16x16x32_bf16 v[34:37], v[178:181], v[212:215], v[34:37]
	v_mfma_f32_16x16x32_bf16 v[62:65], v[174:177], v[190:193], v[62:65]
	v_mfma_f32_16x16x32_bf16 v[58:61], v[182:185], v[190:193], v[58:61]
	v_mfma_f32_16x16x32_bf16 v[54:57], v[174:177], v[200:203], v[54:57]
	v_mfma_f32_16x16x32_bf16 v[50:53], v[182:185], v[200:203], v[50:53]
	v_mfma_f32_16x16x32_bf16 v[46:49], v[174:177], v[208:211], v[46:49]
	v_mfma_f32_16x16x32_bf16 v[42:45], v[182:185], v[208:211], v[42:45]
	v_mfma_f32_16x16x32_bf16 v[38:41], v[174:177], v[216:219], v[38:41]
	v_mfma_f32_16x16x32_bf16 v[34:37], v[182:185], v[216:219], v[34:37]
	s_setprio 0
	s_barrier
	s_add_u32 s18, s19, 0x80180
	s_addc_u32 s19, s20, 0
	v_lshl_add_u64 v[170:171], s[18:19], 0, v[132:133]
	v_readfirstlane_b32 s17, v144
	s_mov_b32 m0, s17
	global_load_lds_dwordx4 v[170:171], off
	v_lshl_add_u64 v[170:171], s[18:19], 0, v[130:131]
	v_readfirstlane_b32 s17, v146
	s_mov_b32 m0, s17
	global_load_lds_dwordx4 v[170:171], off
	s_waitcnt vmcnt(6)
	s_barrier
	s_setprio 1
	v_mfma_f32_16x16x32_bf16 v[30:33], v[220:223], v[186:189], v[30:33]
	v_mfma_f32_16x16x32_bf16 v[26:29], v[228:231], v[186:189], v[26:29]
	v_mfma_f32_16x16x32_bf16 v[22:25], v[220:223], v[196:199], v[22:25]
	v_mfma_f32_16x16x32_bf16 v[18:21], v[228:231], v[196:199], v[18:21]
	v_mfma_f32_16x16x32_bf16 v[14:17], v[220:223], v[204:207], v[14:17]
	v_mfma_f32_16x16x32_bf16 v[10:13], v[228:231], v[204:207], v[10:13]
	v_mfma_f32_16x16x32_bf16 v[6:9], v[220:223], v[212:215], v[6:9]
	v_mfma_f32_16x16x32_bf16 v[2:5], v[228:231], v[212:215], v[2:5]
	v_mfma_f32_16x16x32_bf16 v[30:33], v[224:227], v[190:193], v[30:33]
	v_mfma_f32_16x16x32_bf16 v[26:29], v[232:235], v[190:193], v[26:29]
	v_mfma_f32_16x16x32_bf16 v[22:25], v[224:227], v[200:203], v[22:25]
	v_mfma_f32_16x16x32_bf16 v[18:21], v[232:235], v[200:203], v[18:21]
	v_mfma_f32_16x16x32_bf16 v[14:17], v[224:227], v[208:211], v[14:17]
	v_mfma_f32_16x16x32_bf16 v[10:13], v[232:235], v[208:211], v[10:13]
	v_mfma_f32_16x16x32_bf16 v[6:9], v[224:227], v[216:219], v[6:9]
	v_mfma_f32_16x16x32_bf16 v[2:5], v[232:235], v[216:219], v[2:5]
	s_setprio 0
	s_add_i32 s9, s9, 2
	s_add_u32 s0, s0, 0x100
	s_addc_u32 s1, s1, 0
	s_cmp_lt_u32 s9, 28
	s_barrier
	s_cbranch_scc1 .LBB0_169
	ds_read_b128 v[150:153], v143
	ds_read_b128 v[158:161], v143 offset:1024
	ds_read_b128 v[162:165], v143 offset:2048
	ds_read_b128 v[142:145], v143 offset:3072
	ds_read_b128 v[170:173], v168
	ds_read_b128 v[174:177], v168 offset:1024
	ds_read_b128 v[178:181], v167
	ds_read_b128 v[182:185], v167 offset:1024
	ds_read_b128 v[186:189], v166
	ds_read_b128 v[190:193], v166 offset:1024
	ds_read_b128 v[196:199], v147
	ds_read_b128 v[200:203], v147 offset:1024
	s_add_u32 s0, s11, 0x80f80
	s_addc_u32 s1, s16, 0
	v_lshl_add_u64 v[132:133], s[0:1], 0, v[132:133]
	v_readfirstlane_b32 s9, v148
	s_mov_b32 m0, s9
	global_load_lds_dwordx4 v[132:133], off
	v_lshl_add_u64 v[130:131], s[0:1], 0, v[130:131]
	v_readfirstlane_b32 s0, v156
	s_mov_b32 m0, s0
	global_load_lds_dwordx4 v[130:131], off
	s_barrier
	s_waitcnt lgkmcnt(0)
	s_setprio 1
	v_mfma_f32_16x16x32_bf16 v[126:129], v[150:153], v[170:173], v[126:129]
	v_mfma_f32_16x16x32_bf16 v[122:125], v[162:165], v[170:173], v[122:125]
	v_mfma_f32_16x16x32_bf16 v[114:117], v[162:165], v[178:181], v[114:117]
	v_mfma_f32_16x16x32_bf16 v[106:109], v[162:165], v[186:189], v[106:109]
	v_mfma_f32_16x16x32_bf16 v[98:101], v[162:165], v[196:199], v[98:101]
	v_mfma_f32_16x16x32_bf16 v[126:129], v[158:161], v[174:177], v[126:129]
	v_mfma_f32_16x16x32_bf16 v[122:125], v[142:145], v[174:177], v[122:125]
	v_mfma_f32_16x16x32_bf16 v[118:121], v[150:153], v[178:181], v[118:121]
	v_mfma_f32_16x16x32_bf16 v[114:117], v[142:145], v[182:185], v[114:117]
	v_mfma_f32_16x16x32_bf16 v[110:113], v[150:153], v[186:189], v[110:113]
	v_mfma_f32_16x16x32_bf16 v[106:109], v[142:145], v[190:193], v[106:109]
	v_mfma_f32_16x16x32_bf16 v[102:105], v[150:153], v[196:199], v[102:105]
	v_mfma_f32_16x16x32_bf16 v[130:133], v[142:145], v[200:203], v[98:101]
	v_mfma_f32_16x16x32_bf16 v[118:121], v[158:161], v[182:185], v[118:121]
	v_mfma_f32_16x16x32_bf16 v[110:113], v[158:161], v[190:193], v[110:113]
	v_mfma_f32_16x16x32_bf16 v[102:105], v[158:161], v[200:203], v[102:105]
	s_setprio 0
	s_barrier
	ds_read_b128 v[98:101], v141
	ds_read_b128 v[154:157], v141 offset:1024
	ds_read_b128 v[204:207], v141 offset:2048
	ds_read_b128 v[138:141], v141 offset:3072
	s_barrier
	s_waitcnt lgkmcnt(0)
	s_setprio 1
	v_mfma_f32_16x16x32_bf16 v[86:89], v[98:101], v[178:181], v[86:89]
	v_mfma_f32_16x16x32_bf16 v[82:85], v[204:207], v[178:181], v[82:85]
	v_mfma_f32_16x16x32_bf16 v[70:73], v[98:101], v[196:199], v[70:73]
	v_mfma_f32_16x16x32_bf16 v[66:69], v[204:207], v[196:199], v[66:69]
	v_mfma_f32_16x16x32_bf16 v[94:97], v[98:101], v[170:173], v[94:97]
	v_mfma_f32_16x16x32_bf16 v[90:93], v[204:207], v[170:173], v[90:93]
	v_mfma_f32_16x16x32_bf16 v[86:89], v[154:157], v[182:185], v[86:89]
	v_mfma_f32_16x16x32_bf16 v[82:85], v[138:141], v[182:185], v[82:85]
	v_mfma_f32_16x16x32_bf16 v[78:81], v[98:101], v[186:189], v[78:81]
	v_mfma_f32_16x16x32_bf16 v[74:77], v[204:207], v[186:189], v[74:77]
	v_mfma_f32_16x16x32_bf16 v[70:73], v[154:157], v[200:203], v[70:73]
	v_mfma_f32_16x16x32_bf16 v[66:69], v[138:141], v[200:203], v[66:69]
	v_mfma_f32_16x16x32_bf16 v[94:97], v[154:157], v[174:177], v[94:97]
	v_mfma_f32_16x16x32_bf16 v[170:173], v[138:141], v[174:177], v[90:93]
	v_mfma_f32_16x16x32_bf16 v[174:177], v[154:157], v[190:193], v[78:81]
	v_mfma_f32_16x16x32_bf16 v[178:181], v[138:141], v[190:193], v[74:77]
	s_setprio 0
	s_barrier
;   #define LDA(dst,b,h) for(int m=0;m<4;++m)for(int k=0;k<2;++k) \
;     dst[m][k]=*reinterpret_cast<const bf16x8*>((char*)SA(b,h)+lds_byte(wr*64+m*16+fr,k*32+fq*8))
;   #define LDB(dst,b,h) for(int n=0;n<2;++n)for(int k=0;k<2;++k) \
;     dst[n][k]=*reinterpret_cast<const bf16x8*>((char*)SB(b,h)+lds_byte(wc*32+n*16+fr,k*32+fq*8))
;   #define MMA(ai,bj,At,Bt_) do{__builtin_amdgcn_s_setprio(1); \
;     for(int m=0;m<4;++m)for(int n=0;n<2;++n)for(int k=0;k<2;++k) \
;       acc[ai][bj][m][n]=__builtin_amdgcn_mfma_f32_16x16x32_bf16(Bt_[n][k],At[m][k],acc[ai][bj][m][n],0,0,0); \
;     __builtin_amdgcn_s_setprio(0);}while(0)
;   #define WAIT_V(n) asm volatile("s_waitcnt vmcnt(" #n ")":::"memory")
;   #define WAIT_L(n) asm volatile("s_waitcnt lgkmcnt(" #n ")":::"memory")
;   #define BAR __builtin_amdgcn_s_barrier()
; template <bool TWO, class MID> ...
;     ...
;     LDB(B1,0,1); BAR; WAIT_L(0); MMA(0,1,At,B1); BAR;
;     LDA(At,0,1); WAIT_V(4); BAR; WAIT_L(0); MMA(1,0,At,B0); MMA(1,1,At,B1); BAR; }
;   { LDB(B0,1,0); LDA(At,1,0); WAIT_V(2); BAR; WAIT_L(0); MMA(0,0,At,B0); BAR;
	s_nop 0
	ds_read_b128 v[74:77], v168 offset:16384
	ds_read_b128 v[78:81], v168 offset:17408
	ds_read_b128 v[90:93], v167 offset:16384
	ds_read_b128 v[182:185], v167 offset:17408
	ds_read_b128 v[186:189], v166 offset:16384
	ds_read_b128 v[190:193], v166 offset:17408
	ds_read_b128 v[196:199], v147 offset:16384
	ds_read_b128 v[200:203], v147 offset:17408
	s_waitcnt vmcnt(4)
	s_barrier
	s_waitcnt lgkmcnt(0)
	s_setprio 1
	v_mfma_f32_16x16x32_bf16 v[62:65], v[150:153], v[74:77], v[62:65]
	v_mfma_f32_16x16x32_bf16 v[58:61], v[162:165], v[74:77], v[58:61]
	v_mfma_f32_16x16x32_bf16 v[54:57], v[150:153], v[90:93], v[54:57]
	v_mfma_f32_16x16x32_bf16 v[50:53], v[162:165], v[90:93], v[50:53]
	v_mfma_f32_16x16x32_bf16 v[38:41], v[150:153], v[196:199], v[38:41]
	v_mfma_f32_16x16x32_bf16 v[34:37], v[162:165], v[196:199], v[34:37]
	v_mfma_f32_16x16x32_bf16 v[62:65], v[158:161], v[78:81], v[62:65]
	v_mfma_f32_16x16x32_bf16 v[58:61], v[142:145], v[78:81], v[58:61]
	v_mfma_f32_16x16x32_bf16 v[54:57], v[158:161], v[182:185], v[54:57]
	v_mfma_f32_16x16x32_bf16 v[50:53], v[142:145], v[182:185], v[50:53]
	v_mfma_f32_16x16x32_bf16 v[46:49], v[150:153], v[186:189], v[46:49]
	v_mfma_f32_16x16x32_bf16 v[42:45], v[162:165], v[186:189], v[42:45]
	v_mfma_f32_16x16x32_bf16 v[38:41], v[158:161], v[200:203], v[38:41]
	v_mfma_f32_16x16x32_bf16 v[34:37], v[142:145], v[200:203], v[34:37]
	v_mfma_f32_16x16x32_bf16 v[208:211], v[158:161], v[190:193], v[46:49]
	v_mfma_f32_16x16x32_bf16 v[212:215], v[142:145], v[190:193], v[42:45]
	s_setprio 0
	s_setprio 1
	v_mfma_f32_16x16x32_bf16 v[22:25], v[98:101], v[90:93], v[22:25]
	v_mfma_f32_16x16x32_bf16 v[18:21], v[204:207], v[90:93], v[18:21]
	v_mfma_f32_16x16x32_bf16 v[6:9], v[98:101], v[196:199], v[6:9]
	v_mfma_f32_16x16x32_bf16 v[2:5], v[204:207], v[196:199], v[2:5]
	v_mfma_f32_16x16x32_bf16 v[30:33], v[98:101], v[74:77], v[30:33]
	v_mfma_f32_16x16x32_bf16 v[26:29], v[204:207], v[74:77], v[26:29]
	v_mfma_f32_16x16x32_bf16 v[22:25], v[154:157], v[182:185], v[22:25]
	v_mfma_f32_16x16x32_bf16 v[18:21], v[138:141], v[182:185], v[18:21]
	v_mfma_f32_16x16x32_bf16 v[14:17], v[98:101], v[186:189], v[14:17]
	v_mfma_f32_16x16x32_bf16 v[10:13], v[204:207], v[186:189], v[10:13]
	v_mfma_f32_16x16x32_bf16 v[6:9], v[154:157], v[200:203], v[6:9]
	v_mfma_f32_16x16x32_bf16 v[2:5], v[138:141], v[200:203], v[2:5]
	v_mfma_f32_16x16x32_bf16 v[148:151], v[154:157], v[78:81], v[30:33]
	v_mfma_f32_16x16x32_bf16 v[158:161], v[138:141], v[78:81], v[26:29]
	v_mfma_f32_16x16x32_bf16 v[162:165], v[154:157], v[190:193], v[14:17]
	v_mfma_f32_16x16x32_bf16 v[182:185], v[138:141], v[190:193], v[10:13]
	s_setprio 0
	s_barrier
	s_nop 0
	ds_read_b128 v[10:13], v137
	ds_read_b128 v[14:17], v137 offset:1024
	ds_read_b128 v[152:155], v137 offset:2048
	ds_read_b128 v[186:189], v137 offset:3072
	ds_read_b128 v[26:29], v168 offset:32768
	ds_read_b128 v[30:33], v168 offset:33792
	ds_read_b128 v[42:45], v167 offset:32768
	ds_read_b128 v[46:49], v167 offset:33792
	ds_read_b128 v[190:193], v166 offset:32768
	ds_read_b128 v[196:199], v166 offset:33792
	ds_read_b128 v[200:203], v147 offset:32768
	ds_read_b128 v[204:207], v147 offset:33792
	s_waitcnt vmcnt(2)
	s_barrier
	s_waitcnt lgkmcnt(0)
	s_setprio 1
	v_mfma_f32_16x16x32_bf16 v[74:77], v[10:13], v[26:29], v[126:129]
	v_mfma_f32_16x16x32_bf16 v[142:145], v[14:17], v[30:33], v[74:77]
	v_mfma_f32_16x16x32_bf16 v[74:77], v[152:155], v[26:29], v[122:125]
	v_mfma_f32_16x16x32_bf16 v[138:141], v[186:189], v[30:33], v[74:77]
	v_mfma_f32_16x16x32_bf16 v[74:77], v[10:13], v[42:45], v[118:121]
	v_mfma_f32_16x16x32_bf16 v[126:129], v[14:17], v[46:49], v[74:77]
	v_mfma_f32_16x16x32_bf16 v[74:77], v[152:155], v[42:45], v[114:117]
	v_mfma_f32_16x16x32_bf16 v[122:125], v[186:189], v[46:49], v[74:77]
	v_mfma_f32_16x16x32_bf16 v[74:77], v[10:13], v[190:193], v[110:113]
	v_mfma_f32_16x16x32_bf16 v[98:101], v[14:17], v[196:199], v[74:77]
	v_mfma_f32_16x16x32_bf16 v[74:77], v[152:155], v[190:193], v[106:109]
	v_mfma_f32_16x16x32_bf16 v[90:93], v[186:189], v[196:199], v[74:77]
	v_mfma_f32_16x16x32_bf16 v[74:77], v[10:13], v[200:203], v[102:105]
	v_mfma_f32_16x16x32_bf16 v[78:81], v[14:17], v[204:207], v[74:77]
	v_mfma_f32_16x16x32_bf16 v[74:77], v[152:155], v[200:203], v[130:133]
	v_mfma_f32_16x16x32_bf16 v[74:77], v[186:189], v[204:207], v[74:77]
	s_setprio 0
	s_barrier
;   #define LDA(dst,b,h) for(int m=0;m<4;++m)for(int k=0;k<2;++k) \
;     dst[m][k]=*reinterpret_cast<const bf16x8*>((char*)SA(b,h)+lds_byte(wr*64+m*16+fr,k*32+fq*8))
;   #define LDB(dst,b,h) for(int n=0;n<2;++n)for(int k=0;k<2;++k) \
;     dst[n][k]=*reinterpret_cast<const bf16x8*>((char*)SB(b,h)+lds_byte(wc*32+n*16+fr,k*32+fq*8))
;   #define MMA(ai,bj,At,Bt_) do{__builtin_amdgcn_s_setprio(1); \
;     for(int m=0;m<4;++m)for(int n=0;n<2;++n)for(int k=0;k<2;++k) \
;       acc[ai][bj][m][n]=__builtin_amdgcn_mfma_f32_16x16x32_bf16(Bt_[n][k],At[m][k],acc[ai][bj][m][n],0,0,0); \
;     __builtin_amdgcn_s_setprio(0);}while(0)
;   #define WAIT_V(n) asm volatile("s_waitcnt vmcnt(" #n ")":::"memory")
;   #define WAIT_L(n) asm volatile("s_waitcnt lgkmcnt(" #n ")":::"memory")
;   #define BAR __builtin_amdgcn_s_barrier()
; template <bool TWO, class MID> ...
;     ...
;   { LDB(B0,1,0); LDA(At,1,0); WAIT_V(2); BAR; WAIT_L(0); MMA(0,0,At,B0); BAR;
;     LDB(B1,1,1); WAIT_V(0); BAR; WAIT_L(0); MMA(0,1,At,B1); BAR;
;     LDA(At,1,1); BAR; WAIT_L(0); MMA(1,0,At,B0); MMA(1,1,At,B1); BAR; }
;   if(wr==0)BAR;
	ds_read_b128 v[102:105], v135
	ds_read_b128 v[110:113], v135 offset:1024
	ds_read_b128 v[118:121], v135 offset:2048
	ds_read_b128 v[216:219], v135 offset:3072
	s_waitcnt vmcnt(0)
	s_barrier
	s_waitcnt lgkmcnt(0)
	s_setprio 1
	v_mfma_f32_16x16x32_bf16 v[94:97], v[102:105], v[26:29], v[94:97]
	v_mfma_f32_16x16x32_bf16 v[26:29], v[118:121], v[26:29], v[170:173]
	v_mfma_f32_16x16x32_bf16 v[130:133], v[216:219], v[30:33], v[26:29]
	v_mfma_f32_16x16x32_bf16 v[26:29], v[102:105], v[42:45], v[86:89]
	v_mfma_f32_16x16x32_bf16 v[114:117], v[110:113], v[46:49], v[26:29]
	v_mfma_f32_16x16x32_bf16 v[26:29], v[118:121], v[42:45], v[82:85]
	v_mfma_f32_16x16x32_bf16 v[106:109], v[216:219], v[46:49], v[26:29]
	v_mfma_f32_16x16x32_bf16 v[26:29], v[102:105], v[190:193], v[174:177]
	v_mfma_f32_16x16x32_bf16 v[86:89], v[110:113], v[196:199], v[26:29]
	v_mfma_f32_16x16x32_bf16 v[26:29], v[118:121], v[190:193], v[178:181]
	v_mfma_f32_16x16x32_bf16 v[82:85], v[216:219], v[196:199], v[26:29]
	v_mfma_f32_16x16x32_bf16 v[26:29], v[102:105], v[200:203], v[70:73]
	v_mfma_f32_16x16x32_bf16 v[70:73], v[110:113], v[204:207], v[26:29]
	v_mfma_f32_16x16x32_bf16 v[26:29], v[118:121], v[200:203], v[66:69]
	v_mfma_f32_16x16x32_bf16 v[134:137], v[110:113], v[30:33], v[94:97]
	v_mfma_f32_16x16x32_bf16 v[66:69], v[216:219], v[204:207], v[26:29]
	s_setprio 0
	s_barrier
	ds_read_b128 v[94:97], v168 offset:49152
	ds_read_b128 v[168:171], v168 offset:50176
	ds_read_b128 v[172:175], v167 offset:49152
	ds_read_b128 v[176:179], v167 offset:50176
	ds_read_b128 v[190:193], v166 offset:49152
	ds_read_b128 v[196:199], v166 offset:50176
	ds_read_b128 v[200:203], v147 offset:49152
	ds_read_b128 v[204:207], v147 offset:50176
	s_barrier
	s_waitcnt lgkmcnt(0)
	s_setprio 1
	v_mfma_f32_16x16x32_bf16 v[26:29], v[10:13], v[94:97], v[62:65]
	v_mfma_f32_16x16x32_bf16 v[62:65], v[14:17], v[168:171], v[26:29]
	v_mfma_f32_16x16x32_bf16 v[26:29], v[152:155], v[94:97], v[58:61]
	v_mfma_f32_16x16x32_bf16 v[58:61], v[186:189], v[168:171], v[26:29]
	v_mfma_f32_16x16x32_bf16 v[26:29], v[10:13], v[172:175], v[54:57]
	v_mfma_f32_16x16x32_bf16 v[46:49], v[14:17], v[176:179], v[26:29]
	v_mfma_f32_16x16x32_bf16 v[26:29], v[152:155], v[172:175], v[50:53]
	v_mfma_f32_16x16x32_bf16 v[42:45], v[186:189], v[176:179], v[26:29]
	v_mfma_f32_16x16x32_bf16 v[26:29], v[10:13], v[190:193], v[208:211]
	v_mfma_f32_16x16x32_bf16 v[10:13], v[10:13], v[200:203], v[38:41]
	v_mfma_f32_16x16x32_bf16 v[30:33], v[14:17], v[196:199], v[26:29]
	v_mfma_f32_16x16x32_bf16 v[26:29], v[152:155], v[190:193], v[212:215]
	v_mfma_f32_16x16x32_bf16 v[14:17], v[14:17], v[204:207], v[10:13]
	v_mfma_f32_16x16x32_bf16 v[10:13], v[152:155], v[200:203], v[34:37]
	v_mfma_f32_16x16x32_bf16 v[26:29], v[186:189], v[196:199], v[26:29]
	v_mfma_f32_16x16x32_bf16 v[10:13], v[186:189], v[204:207], v[10:13]
	s_setprio 0
	s_setprio 1
	v_mfma_f32_16x16x32_bf16 v[34:37], v[102:105], v[94:97], v[148:151]
	v_mfma_f32_16x16x32_bf16 v[54:57], v[110:113], v[168:171], v[34:37]
	v_mfma_f32_16x16x32_bf16 v[34:37], v[118:121], v[94:97], v[158:161]
	v_mfma_f32_16x16x32_bf16 v[18:21], v[118:121], v[172:175], v[18:21]
	v_mfma_f32_16x16x32_bf16 v[50:53], v[216:219], v[168:171], v[34:37]
	v_mfma_f32_16x16x32_bf16 v[22:25], v[102:105], v[172:175], v[22:25]
	v_mfma_f32_16x16x32_bf16 v[34:37], v[216:219], v[176:179], v[18:21]
	v_mfma_f32_16x16x32_bf16 v[18:21], v[102:105], v[190:193], v[162:165]
	v_mfma_f32_16x16x32_bf16 v[38:41], v[110:113], v[176:179], v[22:25]
	v_mfma_f32_16x16x32_bf16 v[22:25], v[110:113], v[196:199], v[18:21]
	v_mfma_f32_16x16x32_bf16 v[18:21], v[118:121], v[190:193], v[182:185]
	v_mfma_f32_16x16x32_bf16 v[6:9], v[102:105], v[200:203], v[6:9]
	v_mfma_f32_16x16x32_bf16 v[2:5], v[118:121], v[200:203], v[2:5]
	v_mfma_f32_16x16x32_bf16 v[18:21], v[216:219], v[196:199], v[18:21]
	v_mfma_f32_16x16x32_bf16 v[6:9], v[110:113], v[204:207], v[6:9]
	v_mfma_f32_16x16x32_bf16 v[2:5], v[216:219], v[204:207], v[2:5]
	s_setprio 0
	v_cmp_gt_u32_e32 vcc, s30, v1
	s_barrier
	s_and_saveexec_b64 s[0:1], vcc
	s_cbranch_execz .LBB0_172
	s_barrier

;   #define LDA(dst,b,h) for(int m=0;m<4;++m)for(int k=0;k<2;++k) \
;     dst[m][k]=*reinterpret_cast<const bf16x8*>((char*)SA(b,h)+lds_byte(wr*64+m*16+fr,k*32+fq*8))
;   #define LDB(dst,b,h) for(int n=0;n<2;++n)for(int k=0;k<2;++k) \
;     dst[n][k]=*reinterpret_cast<const bf16x8*>((char*)SB(b,h)+lds_byte(wc*32+n*16+fr,k*32+fq*8))
;   #define MMA(ai,bj,At,Bt_) do{__builtin_amdgcn_s_setprio(1); \
;     for(int m=0;m<4;++m)for(int n=0;n<2;++n)for(int k=0;k<2;++k) \
;       acc[ai][bj][m][n]=__builtin_amdgcn_mfma_f32_16x16x32_bf16(Bt_[n][k],At[m][k],acc[ai][bj][m][n],0,0,0); \
;     __builtin_amdgcn_s_setprio(0);}while(0)
;   #define WAIT_L(n) asm volatile("s_waitcnt lgkmcnt(" #n ")":::"memory")
;   #define BAR __builtin_amdgcn_s_barrier()
;   #define SCHED __builtin_amdgcn_sched_barrier(0)
; template <bool TWO, class MID> ...
;     ...
;     WAIT_L(8); BAR; WAIT_L(0); MMA(0,0,At,B0); BAR; SCHED;
;     LDB(B1,0,1); STAGE_B(SB(0,0),0,t+2);
;     BAR; WAIT_L(0); MMA(0,1,At,B1); BAR;
;     LDA(At,0,1); STAGE_A(SA(0,0),0,t+2);
.LBB0_409:
	s_waitcnt lgkmcnt(8)
	s_barrier
	s_waitcnt lgkmcnt(0)
	s_setprio 1
	v_mfma_f32_16x16x32_bf16 v[126:129], v[130:133], v[186:189], v[126:129]
	v_mfma_f32_16x16x32_bf16 v[122:125], v[138:141], v[186:189], v[122:125]
	v_mfma_f32_16x16x32_bf16 v[118:121], v[130:133], v[178:181], v[118:121]
	v_mfma_f32_16x16x32_bf16 v[114:117], v[138:141], v[178:181], v[114:117]
	v_mfma_f32_16x16x32_bf16 v[110:113], v[130:133], v[170:173], v[110:113]
	v_mfma_f32_16x16x32_bf16 v[106:109], v[138:141], v[170:173], v[106:109]
	v_mfma_f32_16x16x32_bf16 v[102:105], v[130:133], v[162:165], v[102:105]
	v_mfma_f32_16x16x32_bf16 v[98:101], v[138:141], v[162:165], v[98:101]
	v_mfma_f32_16x16x32_bf16 v[126:129], v[134:137], v[190:193], v[126:129]
	v_mfma_f32_16x16x32_bf16 v[122:125], v[142:145], v[190:193], v[122:125]
	v_mfma_f32_16x16x32_bf16 v[118:121], v[134:137], v[182:185], v[118:121]
	v_mfma_f32_16x16x32_bf16 v[114:117], v[142:145], v[182:185], v[114:117]
	v_mfma_f32_16x16x32_bf16 v[110:113], v[134:137], v[174:177], v[110:113]
	v_mfma_f32_16x16x32_bf16 v[106:109], v[142:145], v[174:177], v[106:109]
	v_mfma_f32_16x16x32_bf16 v[102:105], v[134:137], v[166:169], v[102:105]
	v_mfma_f32_16x16x32_bf16 v[98:101], v[142:145], v[166:169], v[98:101]
	s_setprio 0
	s_barrier
	ds_read_b128 v[146:149], v217
	ds_read_b128 v[150:153], v217 offset:1024
	ds_read_b128 v[154:157], v217 offset:2048
	ds_read_b128 v[158:161], v217 offset:3072
	s_cmp_lt_u32 s26, 6
	s_cselect_b64 s[14:15], -1, 0
	s_mov_b64 s[16:17], -1
	s_and_b64 vcc, exec, s[14:15]
	s_cbranch_vccz .LBB0_411
	s_add_u32 s16, s24, s12
	s_addc_u32 s17, s25, s13
	s_add_u32 s16, s16, 0x2e00100
	s_addc_u32 s17, s17, 0
	v_lshl_add_u64 v[250:251], s[16:17], 0, v[200:201]
	v_readfirstlane_b32 s27, v228
	s_mov_b32 m0, s27
	global_load_lds_dwordx4 v[250:251], off
	v_lshl_add_u64 v[250:251], s[16:17], 0, v[202:203]
	v_readfirstlane_b32 s16, v230
	s_mov_b32 m0, s16
	global_load_lds_dwordx4 v[250:251], off
	s_mov_b64 s[16:17], 0

;   #define LDA(dst,b,h) for(int m=0;m<4;++m)for(int k=0;k<2;++k) \
;     dst[m][k]=*reinterpret_cast<const bf16x8*>((char*)SA(b,h)+lds_byte(wr*64+m*16+fr,k*32+fq*8))
;   #define MMA(ai,bj,At,Bt_) do{__builtin_amdgcn_s_setprio(1); \
;     for(int m=0;m<4;++m)for(int n=0;n<2;++n)for(int k=0;k<2;++k) \
;       acc[ai][bj][m][n]=__builtin_amdgcn_mfma_f32_16x16x32_bf16(Bt_[n][k],At[m][k],acc[ai][bj][m][n],0,0,0); \
;     __builtin_amdgcn_s_setprio(0);}while(0)
;   #define WAIT_L(n) asm volatile("s_waitcnt lgkmcnt(" #n ")":::"memory")
;   #define BAR __builtin_amdgcn_s_barrier()
;   #define SCHED __builtin_amdgcn_sched_barrier(0)
; template <bool TWO, class MID> ...
;     ...
;     BAR; WAIT_L(0); MMA(0,1,At,B1); BAR;
;     LDA(At,0,1); STAGE_A(SA(0,0),0,t+2);
;     BAR; WAIT_L(0); MMA(1,0,At,B0); BAR; SCHED;
;     STAGE_B(SB(0,1),1,t+2);
.LBB0_413:
	s_barrier
	s_waitcnt lgkmcnt(0)
	s_setprio 1
	v_mfma_f32_16x16x32_bf16 v[94:97], v[146:149], v[186:189], v[94:97]
	v_mfma_f32_16x16x32_bf16 v[90:93], v[154:157], v[186:189], v[90:93]
	v_mfma_f32_16x16x32_bf16 v[86:89], v[146:149], v[178:181], v[86:89]
	v_mfma_f32_16x16x32_bf16 v[82:85], v[154:157], v[178:181], v[82:85]
	v_mfma_f32_16x16x32_bf16 v[78:81], v[146:149], v[170:173], v[78:81]
	v_mfma_f32_16x16x32_bf16 v[74:77], v[154:157], v[170:173], v[74:77]
	v_mfma_f32_16x16x32_bf16 v[70:73], v[146:149], v[162:165], v[70:73]
	v_mfma_f32_16x16x32_bf16 v[66:69], v[154:157], v[162:165], v[66:69]
	v_mfma_f32_16x16x32_bf16 v[94:97], v[150:153], v[190:193], v[94:97]
	v_mfma_f32_16x16x32_bf16 v[90:93], v[158:161], v[190:193], v[90:93]
	v_mfma_f32_16x16x32_bf16 v[86:89], v[150:153], v[182:185], v[86:89]
	v_mfma_f32_16x16x32_bf16 v[82:85], v[158:161], v[182:185], v[82:85]
	v_mfma_f32_16x16x32_bf16 v[78:81], v[150:153], v[174:177], v[78:81]
	v_mfma_f32_16x16x32_bf16 v[74:77], v[158:161], v[174:177], v[74:77]
	v_mfma_f32_16x16x32_bf16 v[70:73], v[150:153], v[166:169], v[70:73]
	v_mfma_f32_16x16x32_bf16 v[66:69], v[158:161], v[166:169], v[66:69]
	s_setprio 0
	s_barrier
	ds_read_b128 v[186:189], v211 offset:16384
	ds_read_b128 v[190:193], v211 offset:17408
	ds_read_b128 v[178:181], v209 offset:16384
	ds_read_b128 v[182:185], v209 offset:17408
	ds_read_b128 v[170:173], v207 offset:16384
	ds_read_b128 v[174:177], v207 offset:17408
	ds_read_b128 v[162:165], v205 offset:16384
	ds_read_b128 v[166:169], v205 offset:17408
	s_mov_b64 s[16:17], -1
	s_and_b64 vcc, exec, s[14:15]
	s_cbranch_vccz .LBB0_415
	s_add_u32 s16, s1, s12
	s_addc_u32 s17, s5, s13
	s_add_u32 s16, s16, 0x10000100
	s_addc_u32 s17, s17, 0
	v_lshl_add_u64 v[250:251], s[16:17], 0, v[196:197]
	v_readfirstlane_b32 s27, v204
	s_mov_b32 m0, s27
	global_load_lds_dwordx4 v[250:251], off
	v_lshl_add_u64 v[250:251], s[16:17], 0, v[198:199]
	v_readfirstlane_b32 s16, v206
	s_mov_b32 m0, s16
	global_load_lds_dwordx4 v[250:251], off
	s_mov_b64 s[16:17], 0

;   #define LDA(dst,b,h) for(int m=0;m<4;++m)for(int k=0;k<2;++k) \
;     dst[m][k]=*reinterpret_cast<const bf16x8*>((char*)SA(b,h)+lds_byte(wr*64+m*16+fr,k*32+fq*8))
;   #define LDB(dst,b,h) for(int n=0;n<2;++n)for(int k=0;k<2;++k) \
;     dst[n][k]=*reinterpret_cast<const bf16x8*>((char*)SB(b,h)+lds_byte(wc*32+n*16+fr,k*32+fq*8))
;   #define MMA(ai,bj,At,Bt_) do{__builtin_amdgcn_s_setprio(1); \
;     for(int m=0;m<4;++m)for(int n=0;n<2;++n)for(int k=0;k<2;++k) \
;       acc[ai][bj][m][n]=__builtin_amdgcn_mfma_f32_16x16x32_bf16(Bt_[n][k],At[m][k],acc[ai][bj][m][n],0,0,0); \
;     __builtin_amdgcn_s_setprio(0);}while(0)
;   #define WAIT_V(n) asm volatile("s_waitcnt vmcnt(" #n ")":::"memory")
;   #define WAIT_L(n) asm volatile("s_waitcnt lgkmcnt(" #n ")":::"memory")
;   #define BAR __builtin_amdgcn_s_barrier()
;   #define SCHED __builtin_amdgcn_sched_barrier(0)
; template <bool TWO, class MID> ...
;     ...
;     BAR; WAIT_L(0); MMA(1,0,At,B0); BAR; SCHED;
;     STAGE_B(SB(0,1),1,t+2);
;     WAIT_V(6); BAR; MMA(1,1,At,B1); BAR;
;     LDB(B0,1,0); SCHED; LDA(At,1,0); STAGE_A(SA(0,1),1,t+2);
.LBB0_417:
	s_barrier
	s_waitcnt lgkmcnt(0)
	s_setprio 1
	v_mfma_f32_16x16x32_bf16 v[62:65], v[130:133], v[186:189], v[62:65]
	v_mfma_f32_16x16x32_bf16 v[58:61], v[138:141], v[186:189], v[58:61]
	v_mfma_f32_16x16x32_bf16 v[54:57], v[130:133], v[178:181], v[54:57]
	v_mfma_f32_16x16x32_bf16 v[50:53], v[138:141], v[178:181], v[50:53]
	v_mfma_f32_16x16x32_bf16 v[46:49], v[130:133], v[170:173], v[46:49]
	v_mfma_f32_16x16x32_bf16 v[42:45], v[138:141], v[170:173], v[42:45]
	v_mfma_f32_16x16x32_bf16 v[38:41], v[130:133], v[162:165], v[38:41]
	v_mfma_f32_16x16x32_bf16 v[34:37], v[138:141], v[162:165], v[34:37]
	v_mfma_f32_16x16x32_bf16 v[62:65], v[134:137], v[190:193], v[62:65]
	v_mfma_f32_16x16x32_bf16 v[58:61], v[142:145], v[190:193], v[58:61]
	v_mfma_f32_16x16x32_bf16 v[54:57], v[134:137], v[182:185], v[54:57]
	v_mfma_f32_16x16x32_bf16 v[50:53], v[142:145], v[182:185], v[50:53]
	v_mfma_f32_16x16x32_bf16 v[46:49], v[134:137], v[174:177], v[46:49]
	v_mfma_f32_16x16x32_bf16 v[42:45], v[142:145], v[174:177], v[42:45]
	v_mfma_f32_16x16x32_bf16 v[38:41], v[134:137], v[166:169], v[38:41]
	v_mfma_f32_16x16x32_bf16 v[34:37], v[142:145], v[166:169], v[34:37]
	s_setprio 0
	s_barrier
	s_mov_b64 s[16:17], -1
	s_and_b64 vcc, exec, s[14:15]
	s_cbranch_vccz .LBB0_419
	s_add_u32 s16, s24, s12
	s_addc_u32 s17, s25, s13
	s_add_u32 s16, s16, 0x2e20100
	s_addc_u32 s17, s17, 0
	v_lshl_add_u64 v[130:131], s[16:17], 0, v[200:201]
	v_readfirstlane_b32 s27, v236
	s_mov_b32 m0, s27
	global_load_lds_dwordx4 v[130:131], off
	v_lshl_add_u64 v[130:131], s[16:17], 0, v[202:203]
	v_readfirstlane_b32 s16, v238
	s_mov_b32 m0, s16
	global_load_lds_dwordx4 v[130:131], off
	s_mov_b64 s[16:17], 0

;   #define LDA(dst,b,h) for(int m=0;m<4;++m)for(int k=0;k<2;++k) \
;     dst[m][k]=*reinterpret_cast<const bf16x8*>((char*)SA(b,h)+lds_byte(wr*64+m*16+fr,k*32+fq*8))
;   #define LDB(dst,b,h) for(int n=0;n<2;++n)for(int k=0;k<2;++k) \
;     dst[n][k]=*reinterpret_cast<const bf16x8*>((char*)SB(b,h)+lds_byte(wc*32+n*16+fr,k*32+fq*8))
;   #define MMA(ai,bj,At,Bt_) do{__builtin_amdgcn_s_setprio(1); \
;     for(int m=0;m<4;++m)for(int n=0;n<2;++n)for(int k=0;k<2;++k) \
;       acc[ai][bj][m][n]=__builtin_amdgcn_mfma_f32_16x16x32_bf16(Bt_[n][k],At[m][k],acc[ai][bj][m][n],0,0,0); \
;     __builtin_amdgcn_s_setprio(0);}while(0)
;   #define WAIT_L(n) asm volatile("s_waitcnt lgkmcnt(" #n ")":::"memory")
;   #define BAR __builtin_amdgcn_s_barrier()
;   #define SCHED __builtin_amdgcn_sched_barrier(0)
; template <bool TWO, class MID> ...
;     ...
;     WAIT_L(8); BAR; WAIT_L(0); MMA(0,0,At,B0); BAR; SCHED;
;     LDB(B1,1,1); STAGE_B(SB(1,0),0,t+3);
;     BAR; WAIT_L(0); MMA(0,1,At,B1); BAR;
;     LDA(At,1,1); STAGE_A(SA(1,0),0,t+3);
.LBB0_425:
	s_waitcnt lgkmcnt(8)
	s_barrier
	s_waitcnt lgkmcnt(0)
	s_setprio 1
	v_mfma_f32_16x16x32_bf16 v[126:129], v[130:133], v[186:189], v[126:129]
	v_mfma_f32_16x16x32_bf16 v[122:125], v[138:141], v[186:189], v[122:125]
	v_mfma_f32_16x16x32_bf16 v[118:121], v[130:133], v[178:181], v[118:121]
	v_mfma_f32_16x16x32_bf16 v[114:117], v[138:141], v[178:181], v[114:117]
	v_mfma_f32_16x16x32_bf16 v[110:113], v[130:133], v[170:173], v[110:113]
	v_mfma_f32_16x16x32_bf16 v[106:109], v[138:141], v[170:173], v[106:109]
	v_mfma_f32_16x16x32_bf16 v[102:105], v[130:133], v[162:165], v[102:105]
	v_mfma_f32_16x16x32_bf16 v[98:101], v[138:141], v[162:165], v[98:101]
	v_mfma_f32_16x16x32_bf16 v[126:129], v[134:137], v[190:193], v[126:129]
	v_mfma_f32_16x16x32_bf16 v[122:125], v[142:145], v[190:193], v[122:125]
	v_mfma_f32_16x16x32_bf16 v[118:121], v[134:137], v[182:185], v[118:121]
	v_mfma_f32_16x16x32_bf16 v[114:117], v[142:145], v[182:185], v[114:117]
	v_mfma_f32_16x16x32_bf16 v[110:113], v[134:137], v[174:177], v[110:113]
	v_mfma_f32_16x16x32_bf16 v[106:109], v[142:145], v[174:177], v[106:109]
	v_mfma_f32_16x16x32_bf16 v[102:105], v[134:137], v[166:169], v[102:105]
	v_mfma_f32_16x16x32_bf16 v[98:101], v[142:145], v[166:169], v[98:101]
	s_setprio 0
	s_barrier
	ds_read_b128 v[146:149], v213
	ds_read_b128 v[150:153], v213 offset:1024
	ds_read_b128 v[154:157], v213 offset:2048
	ds_read_b128 v[158:161], v213 offset:3072
	s_cmp_lt_u32 s26, 5
	s_cselect_b64 s[14:15], -1, 0
	s_mov_b64 s[16:17], -1
	s_and_b64 vcc, exec, s[14:15]
	s_cbranch_vccz .LBB0_427
	s_add_u32 s16, s24, s12
	s_addc_u32 s17, s25, s13
	s_add_u32 s16, s16, 0x2e00180
	s_addc_u32 s17, s17, 0
	v_lshl_add_u64 v[250:251], s[16:17], 0, v[200:201]
	v_readfirstlane_b32 s27, v208
	s_mov_b32 m0, s27
	global_load_lds_dwordx4 v[250:251], off
	v_lshl_add_u64 v[250:251], s[16:17], 0, v[202:203]
	v_readfirstlane_b32 s16, v210
	s_mov_b32 m0, s16
	global_load_lds_dwordx4 v[250:251], off
	s_mov_b64 s[16:17], 0

;   #define LDA(dst,b,h) for(int m=0;m<4;++m)for(int k=0;k<2;++k) \
;     dst[m][k]=*reinterpret_cast<const bf16x8*>((char*)SA(b,h)+lds_byte(wr*64+m*16+fr,k*32+fq*8))
;   #define MMA(ai,bj,At,Bt_) do{__builtin_amdgcn_s_setprio(1); \
;     for(int m=0;m<4;++m)for(int n=0;n<2;++n)for(int k=0;k<2;++k) \
;       acc[ai][bj][m][n]=__builtin_amdgcn_mfma_f32_16x16x32_bf16(Bt_[n][k],At[m][k],acc[ai][bj][m][n],0,0,0); \
;     __builtin_amdgcn_s_setprio(0);}while(0)
;   #define WAIT_L(n) asm volatile("s_waitcnt lgkmcnt(" #n ")":::"memory")
;   #define BAR __builtin_amdgcn_s_barrier()
;   #define SCHED __builtin_amdgcn_sched_barrier(0)
; template <bool TWO, class MID> ...
;     ...
;     BAR; WAIT_L(0); MMA(0,1,At,B1); BAR;
;     LDA(At,1,1); STAGE_A(SA(1,0),0,t+3);
;     BAR; WAIT_L(0); MMA(1,0,At,B0); BAR; SCHED;
;     STAGE_B(SB(1,1),1,t+3);
.LBB0_429:
	s_barrier
	s_waitcnt lgkmcnt(0)
	s_setprio 1
	v_mfma_f32_16x16x32_bf16 v[94:97], v[146:149], v[186:189], v[94:97]
	v_mfma_f32_16x16x32_bf16 v[90:93], v[154:157], v[186:189], v[90:93]
	v_mfma_f32_16x16x32_bf16 v[86:89], v[146:149], v[178:181], v[86:89]
	v_mfma_f32_16x16x32_bf16 v[82:85], v[154:157], v[178:181], v[82:85]
	v_mfma_f32_16x16x32_bf16 v[78:81], v[146:149], v[170:173], v[78:81]
	v_mfma_f32_16x16x32_bf16 v[74:77], v[154:157], v[170:173], v[74:77]
	v_mfma_f32_16x16x32_bf16 v[70:73], v[146:149], v[162:165], v[70:73]
	v_mfma_f32_16x16x32_bf16 v[66:69], v[154:157], v[162:165], v[66:69]
	v_mfma_f32_16x16x32_bf16 v[94:97], v[150:153], v[190:193], v[94:97]
	v_mfma_f32_16x16x32_bf16 v[90:93], v[158:161], v[190:193], v[90:93]
	v_mfma_f32_16x16x32_bf16 v[86:89], v[150:153], v[182:185], v[86:89]
	v_mfma_f32_16x16x32_bf16 v[82:85], v[158:161], v[182:185], v[82:85]
	v_mfma_f32_16x16x32_bf16 v[78:81], v[150:153], v[174:177], v[78:81]
	v_mfma_f32_16x16x32_bf16 v[74:77], v[158:161], v[174:177], v[74:77]
	v_mfma_f32_16x16x32_bf16 v[70:73], v[150:153], v[166:169], v[70:73]
	v_mfma_f32_16x16x32_bf16 v[66:69], v[158:161], v[166:169], v[66:69]
	s_setprio 0
	s_barrier
	ds_read_b128 v[186:189], v211 offset:49152
	ds_read_b128 v[190:193], v211 offset:50176
	ds_read_b128 v[178:181], v209 offset:49152
	ds_read_b128 v[182:185], v209 offset:50176
	ds_read_b128 v[170:173], v207 offset:49152
	ds_read_b128 v[174:177], v207 offset:50176
	ds_read_b128 v[162:165], v205 offset:49152
	ds_read_b128 v[166:169], v205 offset:50176
	s_mov_b64 s[16:17], -1
	s_and_b64 vcc, exec, s[14:15]
	s_cbranch_vccz .LBB0_431
	s_add_u32 s16, s1, s12
	s_addc_u32 s17, s5, s13
	s_add_u32 s16, s16, 0x10000180
	s_addc_u32 s17, s17, 0
	v_lshl_add_u64 v[250:251], s[16:17], 0, v[196:197]
	v_readfirstlane_b32 s27, v212
	s_mov_b32 m0, s27
	global_load_lds_dwordx4 v[250:251], off
	v_lshl_add_u64 v[250:251], s[16:17], 0, v[198:199]
	v_readfirstlane_b32 s16, v214
	s_mov_b32 m0, s16
	global_load_lds_dwordx4 v[250:251], off
	s_mov_b64 s[16:17], 0

;   #define MMA(ai,bj,At,Bt_) do{__builtin_amdgcn_s_setprio(1); \
;     for(int m=0;m<4;++m)for(int n=0;n<2;++n)for(int k=0;k<2;++k) \
;       acc[ai][bj][m][n]=__builtin_amdgcn_mfma_f32_16x16x32_bf16(Bt_[n][k],At[m][k],acc[ai][bj][m][n],0,0,0); \
;     __builtin_amdgcn_s_setprio(0);}while(0)
;   #define WAIT_V(n) asm volatile("s_waitcnt vmcnt(" #n ")":::"memory")
;   #define WAIT_L(n) asm volatile("s_waitcnt lgkmcnt(" #n ")":::"memory")
;   #define BAR __builtin_amdgcn_s_barrier()
;   #define SCHED __builtin_amdgcn_sched_barrier(0)
; template <bool TWO, class MID> ...
;     ...
;     BAR; WAIT_L(0); MMA(1,0,At,B0); BAR; SCHED;
;     STAGE_B(SB(1,1),1,t+3);
;     WAIT_V(6); BAR; MMA(1,1,At,B1); BAR;
;   }
.LBB0_433:
	s_barrier
	s_waitcnt lgkmcnt(0)
	s_setprio 1
	v_mfma_f32_16x16x32_bf16 v[62:65], v[130:133], v[186:189], v[62:65]
	v_mfma_f32_16x16x32_bf16 v[58:61], v[138:141], v[186:189], v[58:61]
	v_mfma_f32_16x16x32_bf16 v[54:57], v[130:133], v[178:181], v[54:57]
	v_mfma_f32_16x16x32_bf16 v[50:53], v[138:141], v[178:181], v[50:53]
	v_mfma_f32_16x16x32_bf16 v[46:49], v[130:133], v[170:173], v[46:49]
	v_mfma_f32_16x16x32_bf16 v[42:45], v[138:141], v[170:173], v[42:45]
	v_mfma_f32_16x16x32_bf16 v[38:41], v[130:133], v[162:165], v[38:41]
	v_mfma_f32_16x16x32_bf16 v[34:37], v[138:141], v[162:165], v[34:37]
	v_mfma_f32_16x16x32_bf16 v[62:65], v[134:137], v[190:193], v[62:65]
	v_mfma_f32_16x16x32_bf16 v[58:61], v[142:145], v[190:193], v[58:61]
	v_mfma_f32_16x16x32_bf16 v[54:57], v[134:137], v[182:185], v[54:57]
	v_mfma_f32_16x16x32_bf16 v[50:53], v[142:145], v[182:185], v[50:53]
	v_mfma_f32_16x16x32_bf16 v[46:49], v[134:137], v[174:177], v[46:49]
	v_mfma_f32_16x16x32_bf16 v[42:45], v[142:145], v[174:177], v[42:45]
	v_mfma_f32_16x16x32_bf16 v[38:41], v[134:137], v[166:169], v[38:41]
	v_mfma_f32_16x16x32_bf16 v[34:37], v[142:145], v[166:169], v[34:37]
	s_setprio 0
	s_barrier
	s_mov_b64 s[16:17], -1
	s_and_b64 vcc, exec, s[14:15]
	s_cbranch_vccz .LBB0_435
	s_add_u32 s14, s24, s12
	s_addc_u32 s15, s25, s13
	s_add_u32 s14, s14, 0x2e20180
	s_addc_u32 s15, s15, 0
	v_lshl_add_u64 v[130:131], s[14:15], 0, v[200:201]
	v_readfirstlane_b32 s16, v220
	s_mov_b32 m0, s16
	global_load_lds_dwordx4 v[130:131], off
	v_lshl_add_u64 v[130:131], s[14:15], 0, v[202:203]
	v_readfirstlane_b32 s14, v226
	s_mov_b32 m0, s14
	global_load_lds_dwordx4 v[130:131], off
	s_mov_b64 s[16:17], 0

;   #define LDA(dst,b,h) for(int m=0;m<4;++m)for(int k=0;k<2;++k) \
;     dst[m][k]=*reinterpret_cast<const bf16x8*>((char*)SA(b,h)+lds_byte(wr*64+m*16+fr,k*32+fq*8))
;   #define LDB(dst,b,h) for(int n=0;n<2;++n)for(int k=0;k<2;++k) \
;     dst[n][k]=*reinterpret_cast<const bf16x8*>((char*)SB(b,h)+lds_byte(wc*32+n*16+fr,k*32+fq*8))
;   #define MMA(ai,bj,At,Bt_) do{__builtin_amdgcn_s_setprio(1); \
;     for(int m=0;m<4;++m)for(int n=0;n<2;++n)for(int k=0;k<2;++k) \
;       acc[ai][bj][m][n]=__builtin_amdgcn_mfma_f32_16x16x32_bf16(Bt_[n][k],At[m][k],acc[ai][bj][m][n],0,0,0); \
;     __builtin_amdgcn_s_setprio(0);}while(0)
;   #define WAIT_V(n) asm volatile("s_waitcnt vmcnt(" #n ")":::"memory")
;   #define WAIT_L(n) asm volatile("s_waitcnt lgkmcnt(" #n ")":::"memory")
;   #define BAR __builtin_amdgcn_s_barrier()
; template <bool TWO, class MID> ...
;     ...
;   { LDB(B0,0,0); LDA(At,0,0); STAGE_A(SA(1,1),1,nt-1);
;     BAR; WAIT_L(0); MMA(0,0,At,B0); BAR;
;     LDB(B1,0,1); BAR; WAIT_L(0); MMA(0,1,At,B1); BAR;
;     LDA(At,0,1); WAIT_V(4); BAR; WAIT_L(0); MMA(1,0,At,B0); MMA(1,1,At,B1); BAR; }
.LBB0_439:
	ds_read_b128 v[130:133], v219
	ds_read_b128 v[134:137], v219 offset:1024
	ds_read_b128 v[138:141], v219 offset:2048
	ds_read_b128 v[142:145], v219 offset:3072
	ds_read_b128 v[146:149], v211
	ds_read_b128 v[150:153], v211 offset:1024
	ds_read_b128 v[154:157], v209
	ds_read_b128 v[158:161], v209 offset:1024
	ds_read_b128 v[162:165], v207
	ds_read_b128 v[166:169], v207 offset:1024
	ds_read_b128 v[170:173], v205
	ds_read_b128 v[174:177], v205 offset:1024
	s_add_u32 s12, s20, 0xc0780
	s_addc_u32 s13, s21, 0
	v_lshl_add_u64 v[178:179], s[12:13], 0, v[224:225]
	v_readfirstlane_b32 s1, v218
	s_mov_b32 m0, s1
	global_load_lds_dwordx4 v[178:179], off
	v_lshl_add_u64 v[178:179], s[12:13], 0, v[222:223]
	v_readfirstlane_b32 s1, v216
	s_mov_b32 m0, s1
	global_load_lds_dwordx4 v[178:179], off
	s_barrier
	s_waitcnt lgkmcnt(0)
	s_setprio 1
	v_mfma_f32_16x16x32_bf16 v[126:129], v[130:133], v[146:149], v[126:129]
	v_mfma_f32_16x16x32_bf16 v[122:125], v[138:141], v[146:149], v[122:125]
	v_mfma_f32_16x16x32_bf16 v[118:121], v[130:133], v[154:157], v[118:121]
	v_mfma_f32_16x16x32_bf16 v[114:117], v[138:141], v[154:157], v[114:117]
	v_mfma_f32_16x16x32_bf16 v[102:105], v[130:133], v[170:173], v[102:105]
	v_mfma_f32_16x16x32_bf16 v[98:101], v[138:141], v[170:173], v[98:101]
	v_mfma_f32_16x16x32_bf16 v[126:129], v[134:137], v[150:153], v[126:129]
	v_mfma_f32_16x16x32_bf16 v[122:125], v[142:145], v[150:153], v[122:125]
	v_mfma_f32_16x16x32_bf16 v[118:121], v[134:137], v[158:161], v[118:121]
	v_mfma_f32_16x16x32_bf16 v[114:117], v[142:145], v[158:161], v[114:117]
	v_mfma_f32_16x16x32_bf16 v[110:113], v[130:133], v[162:165], v[110:113]
	v_mfma_f32_16x16x32_bf16 v[106:109], v[138:141], v[162:165], v[106:109]
	v_mfma_f32_16x16x32_bf16 v[102:105], v[134:137], v[174:177], v[102:105]
	v_mfma_f32_16x16x32_bf16 v[98:101], v[142:145], v[174:177], v[98:101]
	v_mfma_f32_16x16x32_bf16 v[178:181], v[134:137], v[166:169], v[110:113]
	v_mfma_f32_16x16x32_bf16 v[182:185], v[142:145], v[166:169], v[106:109]
	s_setprio 0
	s_barrier
	s_nop 0
	ds_read_b128 v[106:109], v217
	ds_read_b128 v[110:113], v217 offset:1024
	ds_read_b128 v[186:189], v217 offset:2048
	ds_read_b128 v[190:193], v217 offset:3072
	s_barrier
	s_waitcnt lgkmcnt(0)
	s_setprio 1
	v_mfma_f32_16x16x32_bf16 v[86:89], v[106:109], v[154:157], v[86:89]
	v_mfma_f32_16x16x32_bf16 v[82:85], v[186:189], v[154:157], v[82:85]
	v_mfma_f32_16x16x32_bf16 v[70:73], v[106:109], v[170:173], v[70:73]
	v_mfma_f32_16x16x32_bf16 v[66:69], v[186:189], v[170:173], v[66:69]
	v_mfma_f32_16x16x32_bf16 v[94:97], v[106:109], v[146:149], v[94:97]
	v_mfma_f32_16x16x32_bf16 v[90:93], v[186:189], v[146:149], v[90:93]
	v_mfma_f32_16x16x32_bf16 v[86:89], v[110:113], v[158:161], v[86:89]
	v_mfma_f32_16x16x32_bf16 v[82:85], v[190:193], v[158:161], v[82:85]
	v_mfma_f32_16x16x32_bf16 v[78:81], v[106:109], v[162:165], v[78:81]
	v_mfma_f32_16x16x32_bf16 v[74:77], v[186:189], v[162:165], v[74:77]
	v_mfma_f32_16x16x32_bf16 v[70:73], v[110:113], v[174:177], v[70:73]
	v_mfma_f32_16x16x32_bf16 v[66:69], v[190:193], v[174:177], v[66:69]
	v_mfma_f32_16x16x32_bf16 v[196:199], v[110:113], v[150:153], v[94:97]
	v_mfma_f32_16x16x32_bf16 v[146:149], v[190:193], v[150:153], v[90:93]
	v_mfma_f32_16x16x32_bf16 v[150:153], v[110:113], v[166:169], v[78:81]
	v_mfma_f32_16x16x32_bf16 v[154:157], v[190:193], v[166:169], v[74:77]
	s_setprio 0
	s_barrier
	s_nop 0
	ds_read_b128 v[74:77], v211 offset:16384
	ds_read_b128 v[78:81], v211 offset:17408
	ds_read_b128 v[90:93], v209 offset:16384
	ds_read_b128 v[94:97], v209 offset:17408
	ds_read_b128 v[158:161], v207 offset:16384
	ds_read_b128 v[162:165], v207 offset:17408
	ds_read_b128 v[166:169], v205 offset:16384
	ds_read_b128 v[170:173], v205 offset:17408
	s_waitcnt vmcnt(4)
	s_barrier
	s_waitcnt lgkmcnt(0)
	s_setprio 1
	v_mfma_f32_16x16x32_bf16 v[62:65], v[130:133], v[74:77], v[62:65]
	v_mfma_f32_16x16x32_bf16 v[58:61], v[138:141], v[74:77], v[58:61]
	v_mfma_f32_16x16x32_bf16 v[54:57], v[130:133], v[90:93], v[54:57]
	v_mfma_f32_16x16x32_bf16 v[50:53], v[138:141], v[90:93], v[50:53]
	v_mfma_f32_16x16x32_bf16 v[38:41], v[130:133], v[166:169], v[38:41]
	v_mfma_f32_16x16x32_bf16 v[34:37], v[138:141], v[166:169], v[34:37]
	v_mfma_f32_16x16x32_bf16 v[62:65], v[134:137], v[78:81], v[62:65]
	v_mfma_f32_16x16x32_bf16 v[58:61], v[142:145], v[78:81], v[58:61]
	v_mfma_f32_16x16x32_bf16 v[54:57], v[134:137], v[94:97], v[54:57]
	v_mfma_f32_16x16x32_bf16 v[50:53], v[142:145], v[94:97], v[50:53]
	v_mfma_f32_16x16x32_bf16 v[46:49], v[130:133], v[158:161], v[46:49]
	v_mfma_f32_16x16x32_bf16 v[42:45], v[138:141], v[158:161], v[42:45]
	v_mfma_f32_16x16x32_bf16 v[38:41], v[134:137], v[170:173], v[38:41]
	v_mfma_f32_16x16x32_bf16 v[34:37], v[142:145], v[170:173], v[34:37]
	v_mfma_f32_16x16x32_bf16 v[174:177], v[134:137], v[162:165], v[46:49]
	v_mfma_f32_16x16x32_bf16 v[200:203], v[142:145], v[162:165], v[42:45]
	s_setprio 0
	s_setprio 1
	v_mfma_f32_16x16x32_bf16 v[22:25], v[106:109], v[90:93], v[22:25]
	v_mfma_f32_16x16x32_bf16 v[18:21], v[186:189], v[90:93], v[18:21]
	v_mfma_f32_16x16x32_bf16 v[6:9], v[106:109], v[166:169], v[6:9]
	v_mfma_f32_16x16x32_bf16 v[2:5], v[186:189], v[166:169], v[2:5]
	v_mfma_f32_16x16x32_bf16 v[30:33], v[106:109], v[74:77], v[30:33]
	v_mfma_f32_16x16x32_bf16 v[26:29], v[186:189], v[74:77], v[26:29]
	v_mfma_f32_16x16x32_bf16 v[22:25], v[110:113], v[94:97], v[22:25]
	v_mfma_f32_16x16x32_bf16 v[18:21], v[190:193], v[94:97], v[18:21]
	v_mfma_f32_16x16x32_bf16 v[14:17], v[106:109], v[158:161], v[14:17]
	v_mfma_f32_16x16x32_bf16 v[10:13], v[186:189], v[158:161], v[10:13]
	v_mfma_f32_16x16x32_bf16 v[6:9], v[110:113], v[170:173], v[6:9]
	v_mfma_f32_16x16x32_bf16 v[2:5], v[190:193], v[170:173], v[2:5]
	v_mfma_f32_16x16x32_bf16 v[130:133], v[110:113], v[78:81], v[30:33]
	v_mfma_f32_16x16x32_bf16 v[134:137], v[190:193], v[78:81], v[26:29]
	v_mfma_f32_16x16x32_bf16 v[138:141], v[110:113], v[162:165], v[14:17]
	v_mfma_f32_16x16x32_bf16 v[142:145], v[190:193], v[162:165], v[10:13]
	s_setprio 0
	s_barrier
;   #define LDA(dst,b,h) for(int m=0;m<4;++m)for(int k=0;k<2;++k) \
;     dst[m][k]=*reinterpret_cast<const bf16x8*>((char*)SA(b,h)+lds_byte(wr*64+m*16+fr,k*32+fq*8))
;   #define LDB(dst,b,h) for(int n=0;n<2;++n)for(int k=0;k<2;++k) \
;     dst[n][k]=*reinterpret_cast<const bf16x8*>((char*)SB(b,h)+lds_byte(wc*32+n*16+fr,k*32+fq*8))
;   #define MMA(ai,bj,At,Bt_) do{__builtin_amdgcn_s_setprio(1); \
;     for(int m=0;m<4;++m)for(int n=0;n<2;++n)for(int k=0;k<2;++k) \
;       acc[ai][bj][m][n]=__builtin_amdgcn_mfma_f32_16x16x32_bf16(Bt_[n][k],At[m][k],acc[ai][bj][m][n],0,0,0); \
;     __builtin_amdgcn_s_setprio(0);}while(0)
;   #define WAIT_V(n) asm volatile("s_waitcnt vmcnt(" #n ")":::"memory")
;   #define WAIT_L(n) asm volatile("s_waitcnt lgkmcnt(" #n ")":::"memory")
;   #define BAR __builtin_amdgcn_s_barrier()
; template <bool TWO, class MID> ...
;     ...
;     LDA(At,0,1); WAIT_V(4); BAR; WAIT_L(0); MMA(1,0,At,B0); MMA(1,1,At,B1); BAR; }
;   { LDB(B0,1,0); LDA(At,1,0); WAIT_V(2); BAR; WAIT_L(0); MMA(0,0,At,B0); BAR;
;     LDB(B1,1,1); WAIT_V(0); BAR; WAIT_L(0); MMA(0,1,At,B1); BAR;
;     LDA(At,1,1); BAR; WAIT_L(0); MMA(1,0,At,B0); MMA(1,1,At,B1); BAR; }
;   if(wr==0)BAR;
	s_nop 0
	ds_read_b128 v[10:13], v215
	ds_read_b128 v[14:17], v215 offset:1024
	ds_read_b128 v[158:161], v215 offset:2048
	ds_read_b128 v[162:165], v215 offset:3072
	ds_read_b128 v[26:29], v211 offset:32768
	ds_read_b128 v[30:33], v211 offset:33792
	ds_read_b128 v[42:45], v209 offset:32768
	ds_read_b128 v[46:49], v209 offset:33792
	ds_read_b128 v[166:169], v207 offset:32768
	ds_read_b128 v[170:173], v207 offset:33792
	ds_read_b128 v[186:189], v205 offset:32768
	ds_read_b128 v[190:193], v205 offset:33792
	s_waitcnt vmcnt(2)
	s_barrier
	s_waitcnt lgkmcnt(0)
	s_setprio 1
	v_mfma_f32_16x16x32_bf16 v[74:77], v[10:13], v[26:29], v[126:129]
	v_mfma_f32_16x16x32_bf16 v[126:129], v[14:17], v[30:33], v[74:77]
	v_mfma_f32_16x16x32_bf16 v[74:77], v[158:161], v[26:29], v[122:125]
	v_mfma_f32_16x16x32_bf16 v[122:125], v[162:165], v[30:33], v[74:77]
	v_mfma_f32_16x16x32_bf16 v[74:77], v[10:13], v[42:45], v[118:121]
	v_mfma_f32_16x16x32_bf16 v[110:113], v[14:17], v[46:49], v[74:77]
	v_mfma_f32_16x16x32_bf16 v[74:77], v[158:161], v[42:45], v[114:117]
	v_mfma_f32_16x16x32_bf16 v[106:109], v[162:165], v[46:49], v[74:77]
	v_mfma_f32_16x16x32_bf16 v[74:77], v[10:13], v[166:169], v[178:181]
	v_mfma_f32_16x16x32_bf16 v[94:97], v[14:17], v[170:173], v[74:77]
	v_mfma_f32_16x16x32_bf16 v[74:77], v[158:161], v[166:169], v[182:185]
	v_mfma_f32_16x16x32_bf16 v[90:93], v[162:165], v[170:173], v[74:77]
	v_mfma_f32_16x16x32_bf16 v[74:77], v[10:13], v[186:189], v[102:105]
	v_mfma_f32_16x16x32_bf16 v[78:81], v[14:17], v[190:193], v[74:77]
	v_mfma_f32_16x16x32_bf16 v[74:77], v[158:161], v[186:189], v[98:101]
	v_mfma_f32_16x16x32_bf16 v[74:77], v[162:165], v[190:193], v[74:77]
	s_setprio 0
	s_barrier
	ds_read_b128 v[178:181], v213
	ds_read_b128 v[182:185], v213 offset:1024
	ds_read_b128 v[214:217], v213 offset:2048
	ds_read_b128 v[218:221], v213 offset:3072
	s_waitcnt vmcnt(0)
	s_barrier
	s_waitcnt lgkmcnt(0)
	s_setprio 1
	v_mfma_f32_16x16x32_bf16 v[98:101], v[178:181], v[26:29], v[196:199]
	v_mfma_f32_16x16x32_bf16 v[26:29], v[214:217], v[26:29], v[146:149]
	v_mfma_f32_16x16x32_bf16 v[114:117], v[218:221], v[30:33], v[26:29]
	v_mfma_f32_16x16x32_bf16 v[26:29], v[178:181], v[42:45], v[86:89]
	v_mfma_f32_16x16x32_bf16 v[102:105], v[182:185], v[46:49], v[26:29]
	v_mfma_f32_16x16x32_bf16 v[26:29], v[214:217], v[42:45], v[82:85]
	v_mfma_f32_16x16x32_bf16 v[118:121], v[182:185], v[30:33], v[98:101]
	v_mfma_f32_16x16x32_bf16 v[98:101], v[218:221], v[46:49], v[26:29]
	v_mfma_f32_16x16x32_bf16 v[26:29], v[178:181], v[166:169], v[150:153]
	v_mfma_f32_16x16x32_bf16 v[86:89], v[182:185], v[170:173], v[26:29]
	v_mfma_f32_16x16x32_bf16 v[26:29], v[214:217], v[166:169], v[154:157]
	v_mfma_f32_16x16x32_bf16 v[82:85], v[218:221], v[170:173], v[26:29]
	v_mfma_f32_16x16x32_bf16 v[26:29], v[178:181], v[186:189], v[70:73]
	v_mfma_f32_16x16x32_bf16 v[70:73], v[182:185], v[190:193], v[26:29]
	v_mfma_f32_16x16x32_bf16 v[26:29], v[214:217], v[186:189], v[66:69]
	v_mfma_f32_16x16x32_bf16 v[66:69], v[218:221], v[190:193], v[26:29]
	s_setprio 0
	s_barrier
	ds_read_b128 v[146:149], v211 offset:49152
	ds_read_b128 v[150:153], v211 offset:50176
	ds_read_b128 v[154:157], v209 offset:49152
	ds_read_b128 v[166:169], v209 offset:50176
	ds_read_b128 v[170:173], v207 offset:49152
	ds_read_b128 v[186:189], v207 offset:50176
	ds_read_b128 v[190:193], v205 offset:49152
	ds_read_b128 v[196:199], v205 offset:50176
	s_barrier
	s_waitcnt lgkmcnt(0)
	s_setprio 1
	v_mfma_f32_16x16x32_bf16 v[26:29], v[10:13], v[146:149], v[62:65]
	v_mfma_f32_16x16x32_bf16 v[62:65], v[14:17], v[150:153], v[26:29]
	v_mfma_f32_16x16x32_bf16 v[26:29], v[158:161], v[146:149], v[58:61]
	v_mfma_f32_16x16x32_bf16 v[58:61], v[162:165], v[150:153], v[26:29]
	v_mfma_f32_16x16x32_bf16 v[26:29], v[10:13], v[154:157], v[54:57]
	v_mfma_f32_16x16x32_bf16 v[46:49], v[14:17], v[166:169], v[26:29]
	v_mfma_f32_16x16x32_bf16 v[26:29], v[158:161], v[154:157], v[50:53]
	v_mfma_f32_16x16x32_bf16 v[42:45], v[162:165], v[166:169], v[26:29]
	v_mfma_f32_16x16x32_bf16 v[26:29], v[10:13], v[170:173], v[174:177]
	v_mfma_f32_16x16x32_bf16 v[10:13], v[10:13], v[190:193], v[38:41]
	v_mfma_f32_16x16x32_bf16 v[30:33], v[14:17], v[186:189], v[26:29]
	v_mfma_f32_16x16x32_bf16 v[26:29], v[158:161], v[170:173], v[200:203]
	v_mfma_f32_16x16x32_bf16 v[14:17], v[14:17], v[196:199], v[10:13]
	v_mfma_f32_16x16x32_bf16 v[10:13], v[158:161], v[190:193], v[34:37]
	v_mfma_f32_16x16x32_bf16 v[26:29], v[162:165], v[186:189], v[26:29]
	v_mfma_f32_16x16x32_bf16 v[10:13], v[162:165], v[196:199], v[10:13]
	s_setprio 0
	s_setprio 1
	v_mfma_f32_16x16x32_bf16 v[34:37], v[178:181], v[146:149], v[130:133]
	v_mfma_f32_16x16x32_bf16 v[54:57], v[182:185], v[150:153], v[34:37]
	v_mfma_f32_16x16x32_bf16 v[34:37], v[214:217], v[146:149], v[134:137]
	v_mfma_f32_16x16x32_bf16 v[18:21], v[214:217], v[154:157], v[18:21]
	v_mfma_f32_16x16x32_bf16 v[50:53], v[218:221], v[150:153], v[34:37]
	v_mfma_f32_16x16x32_bf16 v[22:25], v[178:181], v[154:157], v[22:25]
	v_mfma_f32_16x16x32_bf16 v[34:37], v[218:221], v[166:169], v[18:21]
	v_mfma_f32_16x16x32_bf16 v[18:21], v[178:181], v[170:173], v[138:141]
	v_mfma_f32_16x16x32_bf16 v[38:41], v[182:185], v[166:169], v[22:25]
	v_mfma_f32_16x16x32_bf16 v[22:25], v[182:185], v[186:189], v[18:21]
	v_mfma_f32_16x16x32_bf16 v[18:21], v[214:217], v[170:173], v[142:145]
	v_mfma_f32_16x16x32_bf16 v[6:9], v[178:181], v[190:193], v[6:9]
	v_mfma_f32_16x16x32_bf16 v[2:5], v[214:217], v[190:193], v[2:5]
	v_mfma_f32_16x16x32_bf16 v[18:21], v[218:221], v[186:189], v[18:21]
	v_mfma_f32_16x16x32_bf16 v[6:9], v[182:185], v[196:199], v[6:9]
	v_mfma_f32_16x16x32_bf16 v[2:5], v[218:221], v[196:199], v[2:5]
	s_setprio 0
	v_cmp_gt_u32_e32 vcc, s30, v249
	s_barrier
	s_and_saveexec_b64 s[12:13], vcc
	s_cbranch_execz .LBB0_396
	s_barrier
	s_branch .LBB0_396

;   #define LDA(dst,b,h) for(int m=0;m<4;++m)for(int k=0;k<2;++k) \
;     dst[m][k]=*reinterpret_cast<const bf16x8*>((char*)SA(b,h)+lds_byte(wr*64+m*16+fr,k*32+fq*8))
;   #define LDB(dst,b,h) for(int n=0;n<2;++n)for(int k=0;k<2;++k) \
;     dst[n][k]=*reinterpret_cast<const bf16x8*>((char*)SB(b,h)+lds_byte(wc*32+n*16+fr,k*32+fq*8))
;   #define MMA(ai,bj,At,Bt_) do{__builtin_amdgcn_s_setprio(1); \
;     for(int m=0;m<4;++m)for(int n=0;n<2;++n)for(int k=0;k<2;++k) \
;       acc[ai][bj][m][n]=__builtin_amdgcn_mfma_f32_16x16x32_bf16(Bt_[n][k],At[m][k],acc[ai][bj][m][n],0,0,0); \
;     __builtin_amdgcn_s_setprio(0);}while(0)
;   #define WAIT_V(n) asm volatile("s_waitcnt vmcnt(" #n ")":::"memory")
;   #define WAIT_L(n) asm volatile("s_waitcnt lgkmcnt(" #n ")":::"memory")
;   #define BAR __builtin_amdgcn_s_barrier()
;   #define SCHED __builtin_amdgcn_sched_barrier(0)
; template <bool TWO, class MID> ...
;     ...
;     LDB(B0,0,0); SCHED; LDA(At,0,0); STAGE_A(SA(1,1),1,t+1);
;     WAIT_L(8); BAR; WAIT_L(0); MMA(0,0,At,B0); BAR; SCHED;
;     LDB(B1,0,1); STAGE_B(SB(0,0),0,t+2);
;     BAR; WAIT_L(0); MMA(0,1,At,B1); BAR;
;     LDA(At,0,1); STAGE_A(SA(0,0),0,t+2);
;     BAR; WAIT_L(0); MMA(1,0,At,B0); BAR; SCHED;
;     STAGE_B(SB(0,1),1,t+2);
;     WAIT_V(6); BAR; MMA(1,1,At,B1); BAR;
;     LDB(B0,1,0); SCHED; LDA(At,1,0); STAGE_A(SA(0,1),1,t+2);
;     WAIT_L(8); BAR; WAIT_L(0); MMA(0,0,At,B0); BAR; SCHED;
.LBB0_489:
	ds_read_b128 v[166:169], v149
	ds_read_b128 v[170:173], v149 offset:1024
	ds_read_b128 v[174:177], v149 offset:2048
	ds_read_b128 v[178:181], v149 offset:3072
	ds_read_b128 v[182:185], v141
	ds_read_b128 v[186:189], v141 offset:1024
	ds_read_b128 v[190:193], v139
	ds_read_b128 v[196:199], v139 offset:1024
	ds_read_b128 v[200:203], v137
	ds_read_b128 v[204:207], v137 offset:1024
	ds_read_b128 v[208:211], v135
	ds_read_b128 v[212:215], v135 offset:1024
	s_add_u32 s19, s4, s10
	s_addc_u32 s24, s5, s11
	s_add_u32 s26, s19, 0x36080080
	s_addc_u32 s27, s24, 0
	v_lshl_add_u64 v[216:217], s[26:27], 0, v[132:133]
	v_readfirstlane_b32 s25, v148
	s_mov_b32 m0, s25
	global_load_lds_dwordx4 v[216:217], off
	v_lshl_add_u64 v[216:217], s[26:27], 0, v[130:131]
	v_readfirstlane_b32 s25, v150
	s_mov_b32 m0, s25
	global_load_lds_dwordx4 v[216:217], off
	s_waitcnt lgkmcnt(8)
	s_barrier
	s_waitcnt lgkmcnt(0)
	s_setprio 1
	v_mfma_f32_16x16x32_bf16 v[126:129], v[166:169], v[182:185], v[126:129]
	v_mfma_f32_16x16x32_bf16 v[122:125], v[174:177], v[182:185], v[122:125]
	v_mfma_f32_16x16x32_bf16 v[118:121], v[166:169], v[190:193], v[118:121]
	v_mfma_f32_16x16x32_bf16 v[114:117], v[174:177], v[190:193], v[114:117]
	v_mfma_f32_16x16x32_bf16 v[110:113], v[166:169], v[200:203], v[110:113]
	v_mfma_f32_16x16x32_bf16 v[106:109], v[174:177], v[200:203], v[106:109]
	v_mfma_f32_16x16x32_bf16 v[102:105], v[166:169], v[208:211], v[102:105]
	v_mfma_f32_16x16x32_bf16 v[98:101], v[174:177], v[208:211], v[98:101]
	v_mfma_f32_16x16x32_bf16 v[126:129], v[170:173], v[186:189], v[126:129]
	v_mfma_f32_16x16x32_bf16 v[122:125], v[178:181], v[186:189], v[122:125]
	v_mfma_f32_16x16x32_bf16 v[118:121], v[170:173], v[196:199], v[118:121]
	v_mfma_f32_16x16x32_bf16 v[114:117], v[178:181], v[196:199], v[114:117]
	v_mfma_f32_16x16x32_bf16 v[110:113], v[170:173], v[204:207], v[110:113]
	v_mfma_f32_16x16x32_bf16 v[106:109], v[178:181], v[204:207], v[106:109]
	v_mfma_f32_16x16x32_bf16 v[102:105], v[170:173], v[212:215], v[102:105]
	v_mfma_f32_16x16x32_bf16 v[98:101], v[178:181], v[212:215], v[98:101]
	s_setprio 0
	s_barrier
	s_add_u32 s25, s4, s16
	ds_read_b128 v[216:219], v147
	ds_read_b128 v[220:223], v147 offset:1024
	ds_read_b128 v[224:227], v147 offset:2048
	ds_read_b128 v[228:231], v147 offset:3072
	s_addc_u32 s26, s5, s17
	s_add_u32 s28, s25, 0x3400100
	s_addc_u32 s29, s26, 0
	v_lshl_add_u64 v[232:233], s[28:29], 0, v[132:133]
	v_readfirstlane_b32 s27, v152
	s_mov_b32 m0, s27
	global_load_lds_dwordx4 v[232:233], off
	v_lshl_add_u64 v[232:233], s[28:29], 0, v[130:131]
	v_readfirstlane_b32 s27, v154
	s_mov_b32 m0, s27
	global_load_lds_dwordx4 v[232:233], off
	s_barrier
	s_waitcnt lgkmcnt(0)
	s_setprio 1
	v_mfma_f32_16x16x32_bf16 v[94:97], v[216:219], v[182:185], v[94:97]
	v_mfma_f32_16x16x32_bf16 v[90:93], v[224:227], v[182:185], v[90:93]
	v_mfma_f32_16x16x32_bf16 v[86:89], v[216:219], v[190:193], v[86:89]
	v_mfma_f32_16x16x32_bf16 v[82:85], v[224:227], v[190:193], v[82:85]
	v_mfma_f32_16x16x32_bf16 v[78:81], v[216:219], v[200:203], v[78:81]
	v_mfma_f32_16x16x32_bf16 v[74:77], v[224:227], v[200:203], v[74:77]
	v_mfma_f32_16x16x32_bf16 v[70:73], v[216:219], v[208:211], v[70:73]
	v_mfma_f32_16x16x32_bf16 v[66:69], v[224:227], v[208:211], v[66:69]
	v_mfma_f32_16x16x32_bf16 v[94:97], v[220:223], v[186:189], v[94:97]
	v_mfma_f32_16x16x32_bf16 v[90:93], v[228:231], v[186:189], v[90:93]
	v_mfma_f32_16x16x32_bf16 v[86:89], v[220:223], v[196:199], v[86:89]
	v_mfma_f32_16x16x32_bf16 v[82:85], v[228:231], v[196:199], v[82:85]
	v_mfma_f32_16x16x32_bf16 v[78:81], v[220:223], v[204:207], v[78:81]
	v_mfma_f32_16x16x32_bf16 v[74:77], v[228:231], v[204:207], v[74:77]
	v_mfma_f32_16x16x32_bf16 v[70:73], v[220:223], v[212:215], v[70:73]
	v_mfma_f32_16x16x32_bf16 v[66:69], v[228:231], v[212:215], v[66:69]
	s_setprio 0
	s_barrier
	ds_read_b128 v[182:185], v141 offset:16384
	ds_read_b128 v[186:189], v141 offset:17408
	ds_read_b128 v[190:193], v139 offset:16384
	ds_read_b128 v[196:199], v139 offset:17408
	ds_read_b128 v[200:203], v137 offset:16384
	ds_read_b128 v[204:207], v137 offset:17408
	ds_read_b128 v[208:211], v135 offset:16384
	ds_read_b128 v[212:215], v135 offset:17408
	s_add_u32 s28, s19, 0x36000100
	s_addc_u32 s29, s24, 0
	v_lshl_add_u64 v[232:233], s[28:29], 0, v[132:133]
	v_readfirstlane_b32 s27, v138
	s_mov_b32 m0, s27
	global_load_lds_dwordx4 v[232:233], off
	v_lshl_add_u64 v[232:233], s[28:29], 0, v[130:131]
	v_readfirstlane_b32 s27, v156
	s_mov_b32 m0, s27
	global_load_lds_dwordx4 v[232:233], off
	s_barrier
	s_waitcnt lgkmcnt(0)
	s_setprio 1
	v_mfma_f32_16x16x32_bf16 v[62:65], v[166:169], v[182:185], v[62:65]
	v_mfma_f32_16x16x32_bf16 v[58:61], v[174:177], v[182:185], v[58:61]
	v_mfma_f32_16x16x32_bf16 v[54:57], v[166:169], v[190:193], v[54:57]
	v_mfma_f32_16x16x32_bf16 v[50:53], v[174:177], v[190:193], v[50:53]
	v_mfma_f32_16x16x32_bf16 v[46:49], v[166:169], v[200:203], v[46:49]
	v_mfma_f32_16x16x32_bf16 v[42:45], v[174:177], v[200:203], v[42:45]
	v_mfma_f32_16x16x32_bf16 v[38:41], v[166:169], v[208:211], v[38:41]
	v_mfma_f32_16x16x32_bf16 v[34:37], v[174:177], v[208:211], v[34:37]
	v_mfma_f32_16x16x32_bf16 v[62:65], v[170:173], v[186:189], v[62:65]
	v_mfma_f32_16x16x32_bf16 v[58:61], v[178:181], v[186:189], v[58:61]
	v_mfma_f32_16x16x32_bf16 v[54:57], v[170:173], v[196:199], v[54:57]
	v_mfma_f32_16x16x32_bf16 v[50:53], v[178:181], v[196:199], v[50:53]
	v_mfma_f32_16x16x32_bf16 v[46:49], v[170:173], v[204:207], v[46:49]
	v_mfma_f32_16x16x32_bf16 v[42:45], v[178:181], v[204:207], v[42:45]
	v_mfma_f32_16x16x32_bf16 v[38:41], v[170:173], v[212:215], v[38:41]
	v_mfma_f32_16x16x32_bf16 v[34:37], v[178:181], v[212:215], v[34:37]
	s_setprio 0
	s_barrier
;   #define LDA(dst,b,h) for(int m=0;m<4;++m)for(int k=0;k<2;++k) \
;     dst[m][k]=*reinterpret_cast<const bf16x8*>((char*)SA(b,h)+lds_byte(wr*64+m*16+fr,k*32+fq*8))
;   #define LDB(dst,b,h) for(int n=0;n<2;++n)for(int k=0;k<2;++k) \
;     dst[n][k]=*reinterpret_cast<const bf16x8*>((char*)SB(b,h)+lds_byte(wc*32+n*16+fr,k*32+fq*8))
;   #define MMA(ai,bj,At,Bt_) do{__builtin_amdgcn_s_setprio(1); \
;     for(int m=0;m<4;++m)for(int n=0;n<2;++n)for(int k=0;k<2;++k) \
;       acc[ai][bj][m][n]=__builtin_amdgcn_mfma_f32_16x16x32_bf16(Bt_[n][k],At[m][k],acc[ai][bj][m][n],0,0,0); \
;     __builtin_amdgcn_s_setprio(0);}while(0)
;   #define WAIT_V(n) asm volatile("s_waitcnt vmcnt(" #n ")":::"memory")
;   #define WAIT_L(n) asm volatile("s_waitcnt lgkmcnt(" #n ")":::"memory")
;   #define BAR __builtin_amdgcn_s_barrier()
;   #define SCHED __builtin_amdgcn_sched_barrier(0)
; template <bool TWO, class MID> ...
;     ...
;     STAGE_B(SB(0,1),1,t+2);
;     WAIT_V(6); BAR; MMA(1,1,At,B1); BAR;
;     LDB(B0,1,0); SCHED; LDA(At,1,0); STAGE_A(SA(0,1),1,t+2);
;     WAIT_L(8); BAR; WAIT_L(0); MMA(0,0,At,B0); BAR; SCHED;
;     LDB(B1,1,1); STAGE_B(SB(1,0),0,t+3);
;     BAR; WAIT_L(0); MMA(0,1,At,B1); BAR;
;     LDA(At,1,1); STAGE_A(SA(1,0),0,t+3);
;     BAR; WAIT_L(0); MMA(1,0,At,B0); BAR; SCHED;
	s_add_u32 s28, s25, 0x3480100
	s_addc_u32 s29, s26, 0
	v_lshl_add_u64 v[166:167], s[28:29], 0, v[132:133]
	v_readfirstlane_b32 s27, v158
	s_mov_b32 m0, s27
	global_load_lds_dwordx4 v[166:167], off
	v_lshl_add_u64 v[166:167], s[28:29], 0, v[130:131]
	v_readfirstlane_b32 s27, v160
	s_mov_b32 m0, s27
	global_load_lds_dwordx4 v[166:167], off
	s_waitcnt vmcnt(6)
	s_barrier
	s_setprio 1
	v_mfma_f32_16x16x32_bf16 v[30:33], v[216:219], v[182:185], v[30:33]
	v_mfma_f32_16x16x32_bf16 v[26:29], v[224:227], v[182:185], v[26:29]
	v_mfma_f32_16x16x32_bf16 v[22:25], v[216:219], v[190:193], v[22:25]
	v_mfma_f32_16x16x32_bf16 v[18:21], v[224:227], v[190:193], v[18:21]
	v_mfma_f32_16x16x32_bf16 v[14:17], v[216:219], v[200:203], v[14:17]
	v_mfma_f32_16x16x32_bf16 v[10:13], v[224:227], v[200:203], v[10:13]
	v_mfma_f32_16x16x32_bf16 v[6:9], v[216:219], v[208:211], v[6:9]
	v_mfma_f32_16x16x32_bf16 v[2:5], v[224:227], v[208:211], v[2:5]
	v_mfma_f32_16x16x32_bf16 v[30:33], v[220:223], v[186:189], v[30:33]
	v_mfma_f32_16x16x32_bf16 v[26:29], v[228:231], v[186:189], v[26:29]
	v_mfma_f32_16x16x32_bf16 v[22:25], v[220:223], v[196:199], v[22:25]
	v_mfma_f32_16x16x32_bf16 v[18:21], v[228:231], v[196:199], v[18:21]
	v_mfma_f32_16x16x32_bf16 v[14:17], v[220:223], v[204:207], v[14:17]
	v_mfma_f32_16x16x32_bf16 v[10:13], v[228:231], v[204:207], v[10:13]
	v_mfma_f32_16x16x32_bf16 v[6:9], v[220:223], v[212:215], v[6:9]
	v_mfma_f32_16x16x32_bf16 v[2:5], v[228:231], v[212:215], v[2:5]
	s_setprio 0
	s_barrier
	ds_read_b128 v[166:169], v145
	ds_read_b128 v[170:173], v145 offset:1024
	ds_read_b128 v[174:177], v145 offset:2048
	ds_read_b128 v[178:181], v145 offset:3072
	ds_read_b128 v[182:185], v141 offset:32768
	ds_read_b128 v[186:189], v141 offset:33792
	ds_read_b128 v[190:193], v139 offset:32768
	ds_read_b128 v[196:199], v139 offset:33792
	ds_read_b128 v[200:203], v137 offset:32768
	ds_read_b128 v[204:207], v137 offset:33792
	ds_read_b128 v[208:211], v135 offset:32768
	ds_read_b128 v[212:215], v135 offset:33792
	s_add_u32 s28, s19, 0x36080100
	s_addc_u32 s29, s24, 0
	v_lshl_add_u64 v[216:217], s[28:29], 0, v[132:133]
	v_readfirstlane_b32 s27, v162
	s_mov_b32 m0, s27
	global_load_lds_dwordx4 v[216:217], off
	v_lshl_add_u64 v[216:217], s[28:29], 0, v[130:131]
	v_readfirstlane_b32 s27, v164
	s_mov_b32 m0, s27
	global_load_lds_dwordx4 v[216:217], off
	s_waitcnt lgkmcnt(8)
	s_barrier
	s_waitcnt lgkmcnt(0)
	s_setprio 1
	v_mfma_f32_16x16x32_bf16 v[126:129], v[166:169], v[182:185], v[126:129]
	v_mfma_f32_16x16x32_bf16 v[122:125], v[174:177], v[182:185], v[122:125]
	v_mfma_f32_16x16x32_bf16 v[118:121], v[166:169], v[190:193], v[118:121]
	v_mfma_f32_16x16x32_bf16 v[114:117], v[174:177], v[190:193], v[114:117]
	v_mfma_f32_16x16x32_bf16 v[110:113], v[166:169], v[200:203], v[110:113]
	v_mfma_f32_16x16x32_bf16 v[106:109], v[174:177], v[200:203], v[106:109]
	v_mfma_f32_16x16x32_bf16 v[102:105], v[166:169], v[208:211], v[102:105]
	v_mfma_f32_16x16x32_bf16 v[98:101], v[174:177], v[208:211], v[98:101]
	v_mfma_f32_16x16x32_bf16 v[126:129], v[170:173], v[186:189], v[126:129]
	v_mfma_f32_16x16x32_bf16 v[122:125], v[178:181], v[186:189], v[122:125]
	v_mfma_f32_16x16x32_bf16 v[118:121], v[170:173], v[196:199], v[118:121]
	v_mfma_f32_16x16x32_bf16 v[114:117], v[178:181], v[196:199], v[114:117]
	v_mfma_f32_16x16x32_bf16 v[110:113], v[170:173], v[204:207], v[110:113]
	v_mfma_f32_16x16x32_bf16 v[106:109], v[178:181], v[204:207], v[106:109]
	v_mfma_f32_16x16x32_bf16 v[102:105], v[170:173], v[212:215], v[102:105]
	v_mfma_f32_16x16x32_bf16 v[98:101], v[178:181], v[212:215], v[98:101]
	s_setprio 0
	s_barrier
	ds_read_b128 v[216:219], v143
	ds_read_b128 v[220:223], v143 offset:1024
	ds_read_b128 v[224:227], v143 offset:2048
	ds_read_b128 v[228:231], v143 offset:3072
	s_add_u32 s28, s25, 0x3400180
	s_addc_u32 s29, s26, 0
	v_lshl_add_u64 v[232:233], s[28:29], 0, v[132:133]
	v_readfirstlane_b32 s27, v134
	s_mov_b32 m0, s27
	global_load_lds_dwordx4 v[232:233], off
	v_lshl_add_u64 v[232:233], s[28:29], 0, v[130:131]
	v_readfirstlane_b32 s27, v136
	s_mov_b32 m0, s27
	global_load_lds_dwordx4 v[232:233], off
	s_barrier
	s_waitcnt lgkmcnt(0)
	s_setprio 1
	v_mfma_f32_16x16x32_bf16 v[94:97], v[216:219], v[182:185], v[94:97]
	v_mfma_f32_16x16x32_bf16 v[90:93], v[224:227], v[182:185], v[90:93]
	v_mfma_f32_16x16x32_bf16 v[86:89], v[216:219], v[190:193], v[86:89]
	v_mfma_f32_16x16x32_bf16 v[82:85], v[224:227], v[190:193], v[82:85]
	v_mfma_f32_16x16x32_bf16 v[78:81], v[216:219], v[200:203], v[78:81]
	v_mfma_f32_16x16x32_bf16 v[74:77], v[224:227], v[200:203], v[74:77]
	v_mfma_f32_16x16x32_bf16 v[70:73], v[216:219], v[208:211], v[70:73]
	v_mfma_f32_16x16x32_bf16 v[66:69], v[224:227], v[208:211], v[66:69]
	v_mfma_f32_16x16x32_bf16 v[94:97], v[220:223], v[186:189], v[94:97]
	v_mfma_f32_16x16x32_bf16 v[90:93], v[228:231], v[186:189], v[90:93]
	v_mfma_f32_16x16x32_bf16 v[86:89], v[220:223], v[196:199], v[86:89]
	v_mfma_f32_16x16x32_bf16 v[82:85], v[228:231], v[196:199], v[82:85]
	v_mfma_f32_16x16x32_bf16 v[78:81], v[220:223], v[204:207], v[78:81]
	v_mfma_f32_16x16x32_bf16 v[74:77], v[228:231], v[204:207], v[74:77]
	v_mfma_f32_16x16x32_bf16 v[70:73], v[220:223], v[212:215], v[70:73]
	v_mfma_f32_16x16x32_bf16 v[66:69], v[228:231], v[212:215], v[66:69]
	s_setprio 0
	s_barrier
	ds_read_b128 v[182:185], v141 offset:49152
	ds_read_b128 v[186:189], v141 offset:50176
	ds_read_b128 v[190:193], v139 offset:49152
	ds_read_b128 v[196:199], v139 offset:50176
	ds_read_b128 v[200:203], v137 offset:49152
	ds_read_b128 v[204:207], v137 offset:50176
	ds_read_b128 v[208:211], v135 offset:49152
	ds_read_b128 v[212:215], v135 offset:50176
	s_add_u32 s28, s19, 0x36000180
	s_addc_u32 s29, s24, 0
	v_lshl_add_u64 v[232:233], s[28:29], 0, v[132:133]
	v_readfirstlane_b32 s19, v140
	s_mov_b32 m0, s19
	global_load_lds_dwordx4 v[232:233], off
	v_lshl_add_u64 v[232:233], s[28:29], 0, v[130:131]
	v_readfirstlane_b32 s19, v142
	s_mov_b32 m0, s19
	global_load_lds_dwordx4 v[232:233], off
	s_barrier
;   #define LDA(dst,b,h) for(int m=0;m<4;++m)for(int k=0;k<2;++k) \
;     dst[m][k]=*reinterpret_cast<const bf16x8*>((char*)SA(b,h)+lds_byte(wr*64+m*16+fr,k*32+fq*8))
;   #define LDB(dst,b,h) for(int n=0;n<2;++n)for(int k=0;k<2;++k) \
;     dst[n][k]=*reinterpret_cast<const bf16x8*>((char*)SB(b,h)+lds_byte(wc*32+n*16+fr,k*32+fq*8))
;   #define MMA(ai,bj,At,Bt_) do{__builtin_amdgcn_s_setprio(1); \
;     for(int m=0;m<4;++m)for(int n=0;n<2;++n)for(int k=0;k<2;++k) \
;       acc[ai][bj][m][n]=__builtin_amdgcn_mfma_f32_16x16x32_bf16(Bt_[n][k],At[m][k],acc[ai][bj][m][n],0,0,0); \
;     __builtin_amdgcn_s_setprio(0);}while(0)
;   #define WAIT_V(n) asm volatile("s_waitcnt vmcnt(" #n ")":::"memory")
;   #define WAIT_L(n) asm volatile("s_waitcnt lgkmcnt(" #n ")":::"memory")
;   #define BAR __builtin_amdgcn_s_barrier()
;   #define SCHED __builtin_amdgcn_sched_barrier(0)
; template <bool TWO, class MID> ...
;     ...
;     BAR; WAIT_L(0); MMA(0,1,At,B1); BAR;
;     LDA(At,1,1); STAGE_A(SA(1,0),0,t+3);
;     BAR; WAIT_L(0); MMA(1,0,At,B0); BAR; SCHED;
;     STAGE_B(SB(1,1),1,t+3);
;     WAIT_V(6); BAR; MMA(1,1,At,B1); BAR;
;   }
;   { LDB(B0,0,0); LDA(At,0,0); STAGE_A(SA(1,1),1,nt-1);
;     BAR; WAIT_L(0); MMA(0,0,At,B0); BAR;
;     LDB(B1,0,1); BAR; WAIT_L(0); MMA(0,1,At,B1); BAR;
	s_waitcnt lgkmcnt(0)
	s_setprio 1
	v_mfma_f32_16x16x32_bf16 v[62:65], v[166:169], v[182:185], v[62:65]
	v_mfma_f32_16x16x32_bf16 v[58:61], v[174:177], v[182:185], v[58:61]
	v_mfma_f32_16x16x32_bf16 v[54:57], v[166:169], v[190:193], v[54:57]
	v_mfma_f32_16x16x32_bf16 v[50:53], v[174:177], v[190:193], v[50:53]
	v_mfma_f32_16x16x32_bf16 v[46:49], v[166:169], v[200:203], v[46:49]
	v_mfma_f32_16x16x32_bf16 v[42:45], v[174:177], v[200:203], v[42:45]
	v_mfma_f32_16x16x32_bf16 v[38:41], v[166:169], v[208:211], v[38:41]
	v_mfma_f32_16x16x32_bf16 v[34:37], v[174:177], v[208:211], v[34:37]
	v_mfma_f32_16x16x32_bf16 v[62:65], v[170:173], v[186:189], v[62:65]
	v_mfma_f32_16x16x32_bf16 v[58:61], v[178:181], v[186:189], v[58:61]
	v_mfma_f32_16x16x32_bf16 v[54:57], v[170:173], v[196:199], v[54:57]
	v_mfma_f32_16x16x32_bf16 v[50:53], v[178:181], v[196:199], v[50:53]
	v_mfma_f32_16x16x32_bf16 v[46:49], v[170:173], v[204:207], v[46:49]
	v_mfma_f32_16x16x32_bf16 v[42:45], v[178:181], v[204:207], v[42:45]
	v_mfma_f32_16x16x32_bf16 v[38:41], v[170:173], v[212:215], v[38:41]
	v_mfma_f32_16x16x32_bf16 v[34:37], v[178:181], v[212:215], v[34:37]
	s_setprio 0
	s_barrier
	s_add_u32 s24, s25, 0x3480180
	s_addc_u32 s25, s26, 0
	v_lshl_add_u64 v[166:167], s[24:25], 0, v[132:133]
	v_readfirstlane_b32 s19, v144
	s_mov_b32 m0, s19
	global_load_lds_dwordx4 v[166:167], off
	v_lshl_add_u64 v[166:167], s[24:25], 0, v[130:131]
	v_readfirstlane_b32 s19, v146
	s_mov_b32 m0, s19
	global_load_lds_dwordx4 v[166:167], off
	s_waitcnt vmcnt(6)
	s_barrier
	s_setprio 1
	v_mfma_f32_16x16x32_bf16 v[30:33], v[216:219], v[182:185], v[30:33]
	v_mfma_f32_16x16x32_bf16 v[26:29], v[224:227], v[182:185], v[26:29]
	v_mfma_f32_16x16x32_bf16 v[22:25], v[216:219], v[190:193], v[22:25]
	v_mfma_f32_16x16x32_bf16 v[18:21], v[224:227], v[190:193], v[18:21]
	v_mfma_f32_16x16x32_bf16 v[14:17], v[216:219], v[200:203], v[14:17]
	v_mfma_f32_16x16x32_bf16 v[10:13], v[224:227], v[200:203], v[10:13]
	v_mfma_f32_16x16x32_bf16 v[6:9], v[216:219], v[208:211], v[6:9]
	v_mfma_f32_16x16x32_bf16 v[2:5], v[224:227], v[208:211], v[2:5]
	v_mfma_f32_16x16x32_bf16 v[30:33], v[220:223], v[186:189], v[30:33]
	v_mfma_f32_16x16x32_bf16 v[26:29], v[228:231], v[186:189], v[26:29]
	v_mfma_f32_16x16x32_bf16 v[22:25], v[220:223], v[196:199], v[22:25]
	v_mfma_f32_16x16x32_bf16 v[18:21], v[228:231], v[196:199], v[18:21]
	v_mfma_f32_16x16x32_bf16 v[14:17], v[220:223], v[204:207], v[14:17]
	v_mfma_f32_16x16x32_bf16 v[10:13], v[228:231], v[204:207], v[10:13]
	v_mfma_f32_16x16x32_bf16 v[6:9], v[220:223], v[212:215], v[6:9]
	v_mfma_f32_16x16x32_bf16 v[2:5], v[228:231], v[212:215], v[2:5]
	s_setprio 0
	s_add_i32 s18, s18, 2
	s_add_u32 s4, s4, 0x100
	s_addc_u32 s5, s5, 0
	s_cmp_lt_u32 s18, 28
	s_barrier
	s_cbranch_scc1 .LBB0_489
	ds_read_b128 v[152:155], v149
	ds_read_b128 v[156:159], v149 offset:1024
	ds_read_b128 v[160:163], v149 offset:2048
	ds_read_b128 v[164:167], v149 offset:3072
	ds_read_b128 v[168:171], v141
	ds_read_b128 v[172:175], v141 offset:1024
	ds_read_b128 v[176:179], v139
	ds_read_b128 v[180:183], v139 offset:1024
	ds_read_b128 v[184:187], v137
	ds_read_b128 v[188:191], v137 offset:1024
	ds_read_b128 v[196:199], v135
	ds_read_b128 v[200:203], v135 offset:1024
	s_add_u32 s4, s12, 0x80f80
	s_addc_u32 s5, s13, 0
	v_lshl_add_u64 v[132:133], s[4:5], 0, v[132:133]
	v_readfirstlane_b32 s12, v148
	s_mov_b32 m0, s12
	global_load_lds_dwordx4 v[132:133], off
	v_lshl_add_u64 v[130:131], s[4:5], 0, v[130:131]
	v_readfirstlane_b32 s4, v150
	s_mov_b32 m0, s4
	global_load_lds_dwordx4 v[130:131], off
	s_barrier
	s_waitcnt lgkmcnt(0)
	s_setprio 1
	v_mfma_f32_16x16x32_bf16 v[126:129], v[152:155], v[168:171], v[126:129]
	v_mfma_f32_16x16x32_bf16 v[122:125], v[160:163], v[168:171], v[122:125]
	v_mfma_f32_16x16x32_bf16 v[118:121], v[152:155], v[176:179], v[118:121]
	v_mfma_f32_16x16x32_bf16 v[114:117], v[160:163], v[176:179], v[114:117]
	v_mfma_f32_16x16x32_bf16 v[102:105], v[152:155], v[196:199], v[102:105]
	v_mfma_f32_16x16x32_bf16 v[98:101], v[160:163], v[196:199], v[98:101]
	v_mfma_f32_16x16x32_bf16 v[126:129], v[156:159], v[172:175], v[126:129]
	v_mfma_f32_16x16x32_bf16 v[122:125], v[164:167], v[172:175], v[122:125]
	v_mfma_f32_16x16x32_bf16 v[118:121], v[156:159], v[180:183], v[118:121]
	v_mfma_f32_16x16x32_bf16 v[114:117], v[164:167], v[180:183], v[114:117]
	v_mfma_f32_16x16x32_bf16 v[110:113], v[152:155], v[184:187], v[110:113]
	v_mfma_f32_16x16x32_bf16 v[106:109], v[160:163], v[184:187], v[106:109]
	v_mfma_f32_16x16x32_bf16 v[102:105], v[156:159], v[200:203], v[102:105]
	v_mfma_f32_16x16x32_bf16 v[98:101], v[164:167], v[200:203], v[98:101]
	v_mfma_f32_16x16x32_bf16 v[130:133], v[156:159], v[188:191], v[110:113]
	v_mfma_f32_16x16x32_bf16 v[148:151], v[164:167], v[188:191], v[106:109]
	s_setprio 0
	s_barrier
	s_nop 0
	ds_read_b128 v[106:109], v147
	ds_read_b128 v[110:113], v147 offset:1024
	ds_read_b128 v[204:207], v147 offset:2048
	ds_read_b128 v[208:211], v147 offset:3072
	s_barrier
	s_waitcnt lgkmcnt(0)
	s_setprio 1
	v_mfma_f32_16x16x32_bf16 v[86:89], v[106:109], v[176:179], v[86:89]
	v_mfma_f32_16x16x32_bf16 v[82:85], v[204:207], v[176:179], v[82:85]
	v_mfma_f32_16x16x32_bf16 v[70:73], v[106:109], v[196:199], v[70:73]
	v_mfma_f32_16x16x32_bf16 v[66:69], v[204:207], v[196:199], v[66:69]
	v_mfma_f32_16x16x32_bf16 v[94:97], v[106:109], v[168:171], v[94:97]
	v_mfma_f32_16x16x32_bf16 v[90:93], v[204:207], v[168:171], v[90:93]
	v_mfma_f32_16x16x32_bf16 v[86:89], v[110:113], v[180:183], v[86:89]
	v_mfma_f32_16x16x32_bf16 v[82:85], v[208:211], v[180:183], v[82:85]
	v_mfma_f32_16x16x32_bf16 v[78:81], v[106:109], v[184:187], v[78:81]
	v_mfma_f32_16x16x32_bf16 v[74:77], v[204:207], v[184:187], v[74:77]
	v_mfma_f32_16x16x32_bf16 v[70:73], v[110:113], v[200:203], v[70:73]
	v_mfma_f32_16x16x32_bf16 v[66:69], v[208:211], v[200:203], v[66:69]
	v_mfma_f32_16x16x32_bf16 v[212:215], v[110:113], v[172:175], v[94:97]
	v_mfma_f32_16x16x32_bf16 v[168:171], v[208:211], v[172:175], v[90:93]
	v_mfma_f32_16x16x32_bf16 v[172:175], v[110:113], v[188:191], v[78:81]
	v_mfma_f32_16x16x32_bf16 v[176:179], v[208:211], v[188:191], v[74:77]
	s_setprio 0
	s_barrier
;   #define LDA(dst,b,h) for(int m=0;m<4;++m)for(int k=0;k<2;++k) \
;     dst[m][k]=*reinterpret_cast<const bf16x8*>((char*)SA(b,h)+lds_byte(wr*64+m*16+fr,k*32+fq*8))
;   #define LDB(dst,b,h) for(int n=0;n<2;++n)for(int k=0;k<2;++k) \
;     dst[n][k]=*reinterpret_cast<const bf16x8*>((char*)SB(b,h)+lds_byte(wc*32+n*16+fr,k*32+fq*8))
;   #define MMA(ai,bj,At,Bt_) do{__builtin_amdgcn_s_setprio(1); \
;     for(int m=0;m<4;++m)for(int n=0;n<2;++n)for(int k=0;k<2;++k) \
;       acc[ai][bj][m][n]=__builtin_amdgcn_mfma_f32_16x16x32_bf16(Bt_[n][k],At[m][k],acc[ai][bj][m][n],0,0,0); \
;     __builtin_amdgcn_s_setprio(0);}while(0)
;   #define WAIT_V(n) asm volatile("s_waitcnt vmcnt(" #n ")":::"memory")
;   #define WAIT_L(n) asm volatile("s_waitcnt lgkmcnt(" #n ")":::"memory")
;   #define BAR __builtin_amdgcn_s_barrier()
; template <bool TWO, class MID> ...
;     ...
;     LDB(B1,0,1); BAR; WAIT_L(0); MMA(0,1,At,B1); BAR;
;     LDA(At,0,1); WAIT_V(4); BAR; WAIT_L(0); MMA(1,0,At,B0); MMA(1,1,At,B1); BAR; }
;   { LDB(B0,1,0); LDA(At,1,0); WAIT_V(2); BAR; WAIT_L(0); MMA(0,0,At,B0); BAR;
	s_nop 0
	ds_read_b128 v[74:77], v141 offset:16384
	ds_read_b128 v[78:81], v141 offset:17408
	ds_read_b128 v[90:93], v139 offset:16384
	ds_read_b128 v[94:97], v139 offset:17408
	ds_read_b128 v[180:183], v137 offset:16384
	ds_read_b128 v[184:187], v137 offset:17408
	ds_read_b128 v[188:191], v135 offset:16384
	ds_read_b128 v[196:199], v135 offset:17408
	s_waitcnt vmcnt(4)
	s_barrier
	s_waitcnt lgkmcnt(0)
	s_setprio 1
	v_mfma_f32_16x16x32_bf16 v[62:65], v[152:155], v[74:77], v[62:65]
	v_mfma_f32_16x16x32_bf16 v[58:61], v[160:163], v[74:77], v[58:61]
	v_mfma_f32_16x16x32_bf16 v[54:57], v[152:155], v[90:93], v[54:57]
	v_mfma_f32_16x16x32_bf16 v[50:53], v[160:163], v[90:93], v[50:53]
	v_mfma_f32_16x16x32_bf16 v[38:41], v[152:155], v[188:191], v[38:41]
	v_mfma_f32_16x16x32_bf16 v[34:37], v[160:163], v[188:191], v[34:37]
	v_mfma_f32_16x16x32_bf16 v[62:65], v[156:159], v[78:81], v[62:65]
	v_mfma_f32_16x16x32_bf16 v[58:61], v[164:167], v[78:81], v[58:61]
	v_mfma_f32_16x16x32_bf16 v[54:57], v[156:159], v[94:97], v[54:57]
	v_mfma_f32_16x16x32_bf16 v[50:53], v[164:167], v[94:97], v[50:53]
	v_mfma_f32_16x16x32_bf16 v[46:49], v[152:155], v[180:183], v[46:49]
	v_mfma_f32_16x16x32_bf16 v[42:45], v[160:163], v[180:183], v[42:45]
	v_mfma_f32_16x16x32_bf16 v[38:41], v[156:159], v[196:199], v[38:41]
	v_mfma_f32_16x16x32_bf16 v[34:37], v[164:167], v[196:199], v[34:37]
	v_mfma_f32_16x16x32_bf16 v[200:203], v[156:159], v[184:187], v[46:49]
	v_mfma_f32_16x16x32_bf16 v[216:219], v[164:167], v[184:187], v[42:45]
	s_setprio 0
	s_setprio 1
	v_mfma_f32_16x16x32_bf16 v[22:25], v[106:109], v[90:93], v[22:25]
	v_mfma_f32_16x16x32_bf16 v[18:21], v[204:207], v[90:93], v[18:21]
	v_mfma_f32_16x16x32_bf16 v[6:9], v[106:109], v[188:191], v[6:9]
	v_mfma_f32_16x16x32_bf16 v[2:5], v[204:207], v[188:191], v[2:5]
	v_mfma_f32_16x16x32_bf16 v[30:33], v[106:109], v[74:77], v[30:33]
	v_mfma_f32_16x16x32_bf16 v[26:29], v[204:207], v[74:77], v[26:29]
	v_mfma_f32_16x16x32_bf16 v[22:25], v[110:113], v[94:97], v[22:25]
	v_mfma_f32_16x16x32_bf16 v[18:21], v[208:211], v[94:97], v[18:21]
	v_mfma_f32_16x16x32_bf16 v[14:17], v[106:109], v[180:183], v[14:17]
	v_mfma_f32_16x16x32_bf16 v[10:13], v[204:207], v[180:183], v[10:13]
	v_mfma_f32_16x16x32_bf16 v[6:9], v[110:113], v[196:199], v[6:9]
	v_mfma_f32_16x16x32_bf16 v[2:5], v[208:211], v[196:199], v[2:5]
	v_mfma_f32_16x16x32_bf16 v[152:155], v[110:113], v[78:81], v[30:33]
	v_mfma_f32_16x16x32_bf16 v[156:159], v[208:211], v[78:81], v[26:29]
	v_mfma_f32_16x16x32_bf16 v[160:163], v[110:113], v[184:187], v[14:17]
	v_mfma_f32_16x16x32_bf16 v[164:167], v[208:211], v[184:187], v[10:13]
	s_setprio 0
	s_barrier
	s_nop 0
	ds_read_b128 v[10:13], v145
	ds_read_b128 v[14:17], v145 offset:1024
	ds_read_b128 v[180:183], v145 offset:2048
	ds_read_b128 v[144:147], v145 offset:3072
	ds_read_b128 v[26:29], v141 offset:32768
	ds_read_b128 v[30:33], v141 offset:33792
	ds_read_b128 v[42:45], v139 offset:32768
	ds_read_b128 v[46:49], v139 offset:33792
	ds_read_b128 v[184:187], v137 offset:32768
	ds_read_b128 v[188:191], v137 offset:33792
	ds_read_b128 v[196:199], v135 offset:32768
	ds_read_b128 v[204:207], v135 offset:33792
	s_waitcnt vmcnt(2)
	s_barrier
	s_waitcnt lgkmcnt(0)
	s_setprio 1
	v_mfma_f32_16x16x32_bf16 v[74:77], v[10:13], v[26:29], v[126:129]
	v_mfma_f32_16x16x32_bf16 v[126:129], v[14:17], v[30:33], v[74:77]
	v_mfma_f32_16x16x32_bf16 v[74:77], v[180:183], v[26:29], v[122:125]
	v_mfma_f32_16x16x32_bf16 v[122:125], v[144:147], v[30:33], v[74:77]
	v_mfma_f32_16x16x32_bf16 v[74:77], v[10:13], v[42:45], v[118:121]
	v_mfma_f32_16x16x32_bf16 v[110:113], v[14:17], v[46:49], v[74:77]
	v_mfma_f32_16x16x32_bf16 v[74:77], v[180:183], v[42:45], v[114:117]
	v_mfma_f32_16x16x32_bf16 v[106:109], v[144:147], v[46:49], v[74:77]
	v_mfma_f32_16x16x32_bf16 v[74:77], v[10:13], v[184:187], v[130:133]
	v_mfma_f32_16x16x32_bf16 v[94:97], v[14:17], v[188:191], v[74:77]
	v_mfma_f32_16x16x32_bf16 v[74:77], v[180:183], v[184:187], v[148:151]
	v_mfma_f32_16x16x32_bf16 v[90:93], v[144:147], v[188:191], v[74:77]
	v_mfma_f32_16x16x32_bf16 v[74:77], v[10:13], v[196:199], v[102:105]
	v_mfma_f32_16x16x32_bf16 v[78:81], v[14:17], v[204:207], v[74:77]
	v_mfma_f32_16x16x32_bf16 v[74:77], v[180:183], v[196:199], v[98:101]
	v_mfma_f32_16x16x32_bf16 v[74:77], v[144:147], v[204:207], v[74:77]
	s_setprio 0
	s_barrier
;   #define LDA(dst,b,h) for(int m=0;m<4;++m)for(int k=0;k<2;++k) \
;     dst[m][k]=*reinterpret_cast<const bf16x8*>((char*)SA(b,h)+lds_byte(wr*64+m*16+fr,k*32+fq*8))
;   #define LDB(dst,b,h) for(int n=0;n<2;++n)for(int k=0;k<2;++k) \
;     dst[n][k]=*reinterpret_cast<const bf16x8*>((char*)SB(b,h)+lds_byte(wc*32+n*16+fr,k*32+fq*8))
;   #define MMA(ai,bj,At,Bt_) do{__builtin_amdgcn_s_setprio(1); \
;     for(int m=0;m<4;++m)for(int n=0;n<2;++n)for(int k=0;k<2;++k) \
;       acc[ai][bj][m][n]=__builtin_amdgcn_mfma_f32_16x16x32_bf16(Bt_[n][k],At[m][k],acc[ai][bj][m][n],0,0,0); \
;     __builtin_amdgcn_s_setprio(0);}while(0)
;   #define WAIT_V(n) asm volatile("s_waitcnt vmcnt(" #n ")":::"memory")
;   #define WAIT_L(n) asm volatile("s_waitcnt lgkmcnt(" #n ")":::"memory")
;   #define BAR __builtin_amdgcn_s_barrier()
; template <bool TWO, class MID> ...
;     ...
;   { LDB(B0,1,0); LDA(At,1,0); WAIT_V(2); BAR; WAIT_L(0); MMA(0,0,At,B0); BAR;
;     LDB(B1,1,1); WAIT_V(0); BAR; WAIT_L(0); MMA(0,1,At,B1); BAR;
;     LDA(At,1,1); BAR; WAIT_L(0); MMA(1,0,At,B0); MMA(1,1,At,B1); BAR; }
;   if(wr==0)BAR;
	ds_read_b128 v[130:133], v143
	ds_read_b128 v[148:151], v143 offset:1024
	ds_read_b128 v[208:211], v143 offset:2048
	ds_read_b128 v[220:223], v143 offset:3072
	s_waitcnt vmcnt(0)
	s_barrier
	s_waitcnt lgkmcnt(0)
	s_setprio 1
	v_mfma_f32_16x16x32_bf16 v[98:101], v[130:133], v[26:29], v[212:215]
	v_mfma_f32_16x16x32_bf16 v[26:29], v[208:211], v[26:29], v[168:171]
	v_mfma_f32_16x16x32_bf16 v[114:117], v[220:223], v[30:33], v[26:29]
	v_mfma_f32_16x16x32_bf16 v[26:29], v[130:133], v[42:45], v[86:89]
	v_mfma_f32_16x16x32_bf16 v[102:105], v[148:151], v[46:49], v[26:29]
	v_mfma_f32_16x16x32_bf16 v[26:29], v[208:211], v[42:45], v[82:85]
	v_mfma_f32_16x16x32_bf16 v[118:121], v[148:151], v[30:33], v[98:101]
	v_mfma_f32_16x16x32_bf16 v[98:101], v[220:223], v[46:49], v[26:29]
	v_mfma_f32_16x16x32_bf16 v[26:29], v[130:133], v[184:187], v[172:175]
	v_mfma_f32_16x16x32_bf16 v[86:89], v[148:151], v[188:191], v[26:29]
	v_mfma_f32_16x16x32_bf16 v[26:29], v[208:211], v[184:187], v[176:179]
	v_mfma_f32_16x16x32_bf16 v[82:85], v[220:223], v[188:191], v[26:29]
	v_mfma_f32_16x16x32_bf16 v[26:29], v[130:133], v[196:199], v[70:73]
	v_mfma_f32_16x16x32_bf16 v[70:73], v[148:151], v[204:207], v[26:29]
	v_mfma_f32_16x16x32_bf16 v[26:29], v[208:211], v[196:199], v[66:69]
	v_mfma_f32_16x16x32_bf16 v[66:69], v[220:223], v[204:207], v[26:29]
	s_setprio 0
	s_barrier
	ds_read_b128 v[168:171], v141 offset:49152
	ds_read_b128 v[140:143], v141 offset:50176
	ds_read_b128 v[172:175], v139 offset:49152
	ds_read_b128 v[176:179], v139 offset:50176
	ds_read_b128 v[184:187], v137 offset:49152
	ds_read_b128 v[136:139], v137 offset:50176
	ds_read_b128 v[188:191], v135 offset:49152
	ds_read_b128 v[196:199], v135 offset:50176
	s_barrier
	s_waitcnt lgkmcnt(0)
	s_setprio 1
	v_mfma_f32_16x16x32_bf16 v[26:29], v[10:13], v[168:171], v[62:65]
	v_mfma_f32_16x16x32_bf16 v[62:65], v[14:17], v[140:143], v[26:29]
	v_mfma_f32_16x16x32_bf16 v[26:29], v[180:183], v[168:171], v[58:61]
	v_mfma_f32_16x16x32_bf16 v[58:61], v[144:147], v[140:143], v[26:29]
	v_mfma_f32_16x16x32_bf16 v[26:29], v[10:13], v[172:175], v[54:57]
	v_mfma_f32_16x16x32_bf16 v[46:49], v[14:17], v[176:179], v[26:29]
	v_mfma_f32_16x16x32_bf16 v[26:29], v[180:183], v[172:175], v[50:53]
	v_mfma_f32_16x16x32_bf16 v[42:45], v[144:147], v[176:179], v[26:29]
	v_mfma_f32_16x16x32_bf16 v[26:29], v[10:13], v[184:187], v[200:203]
	v_mfma_f32_16x16x32_bf16 v[10:13], v[10:13], v[188:191], v[38:41]
	v_mfma_f32_16x16x32_bf16 v[30:33], v[14:17], v[136:139], v[26:29]
	v_mfma_f32_16x16x32_bf16 v[26:29], v[180:183], v[184:187], v[216:219]
	v_mfma_f32_16x16x32_bf16 v[14:17], v[14:17], v[196:199], v[10:13]
	v_mfma_f32_16x16x32_bf16 v[10:13], v[180:183], v[188:191], v[34:37]
	v_mfma_f32_16x16x32_bf16 v[26:29], v[144:147], v[136:139], v[26:29]
	v_mfma_f32_16x16x32_bf16 v[10:13], v[144:147], v[196:199], v[10:13]
	s_setprio 0
	s_setprio 1
	v_mfma_f32_16x16x32_bf16 v[34:37], v[130:133], v[168:171], v[152:155]
	v_mfma_f32_16x16x32_bf16 v[54:57], v[148:151], v[140:143], v[34:37]
	v_mfma_f32_16x16x32_bf16 v[34:37], v[208:211], v[168:171], v[156:159]
	v_mfma_f32_16x16x32_bf16 v[18:21], v[208:211], v[172:175], v[18:21]
	v_mfma_f32_16x16x32_bf16 v[50:53], v[220:223], v[140:143], v[34:37]
	v_mfma_f32_16x16x32_bf16 v[22:25], v[130:133], v[172:175], v[22:25]
	v_mfma_f32_16x16x32_bf16 v[34:37], v[220:223], v[176:179], v[18:21]
	v_mfma_f32_16x16x32_bf16 v[18:21], v[130:133], v[184:187], v[160:163]
	v_mfma_f32_16x16x32_bf16 v[38:41], v[148:151], v[176:179], v[22:25]
	v_mfma_f32_16x16x32_bf16 v[22:25], v[148:151], v[136:139], v[18:21]
	v_mfma_f32_16x16x32_bf16 v[18:21], v[208:211], v[184:187], v[164:167]
	v_mfma_f32_16x16x32_bf16 v[6:9], v[130:133], v[188:191], v[6:9]
	v_mfma_f32_16x16x32_bf16 v[2:5], v[208:211], v[188:191], v[2:5]
	v_mfma_f32_16x16x32_bf16 v[18:21], v[220:223], v[136:139], v[18:21]
	v_mfma_f32_16x16x32_bf16 v[6:9], v[148:151], v[196:199], v[6:9]
	v_mfma_f32_16x16x32_bf16 v[2:5], v[220:223], v[196:199], v[2:5]
	s_setprio 0
	v_cmp_gt_u32_e32 vcc, s30, v1
	s_barrier
	s_and_saveexec_b64 s[4:5], vcc
	s_cbranch_execz .LBB0_492
	s_barrier

;   #define LDA(dst,b,h) for(int m=0;m<4;++m)for(int k=0;k<2;++k) \
;     dst[m][k]=*reinterpret_cast<const bf16x8*>((char*)SA(b,h)+lds_byte(wr*64+m*16+fr,k*32+fq*8))
;   #define LDB(dst,b,h) for(int n=0;n<2;++n)for(int k=0;k<2;++k) \
;     dst[n][k]=*reinterpret_cast<const bf16x8*>((char*)SB(b,h)+lds_byte(wc*32+n*16+fr,k*32+fq*8))
;   #define MMA(ai,bj,At,Bt_) do{__builtin_amdgcn_s_setprio(1); \
;     for(int m=0;m<4;++m)for(int n=0;n<2;++n)for(int k=0;k<2;++k) \
;       acc[ai][bj][m][n]=__builtin_amdgcn_mfma_f32_16x16x32_bf16(Bt_[n][k],At[m][k],acc[ai][bj][m][n],0,0,0); \
;     __builtin_amdgcn_s_setprio(0);}while(0)
;   #define WAIT_V(n) asm volatile("s_waitcnt vmcnt(" #n ")":::"memory")
;   #define WAIT_L(n) asm volatile("s_waitcnt lgkmcnt(" #n ")":::"memory")
;   #define BAR __builtin_amdgcn_s_barrier()
;   #define SCHED __builtin_amdgcn_sched_barrier(0)
; template <bool TWO, class MID> ...
;     ...
;     LDB(B0,0,0); SCHED; LDA(At,0,0); STAGE_A(SA(1,1),1,t+1);
;     WAIT_L(8); BAR; WAIT_L(0); MMA(0,0,At,B0); BAR; SCHED;
;     LDB(B1,0,1); STAGE_B(SB(0,0),0,t+2);
;     BAR; WAIT_L(0); MMA(0,1,At,B1); BAR;
;     LDA(At,0,1); STAGE_A(SA(0,0),0,t+2);
;     BAR; WAIT_L(0); MMA(1,0,At,B0); BAR; SCHED;
;     STAGE_B(SB(0,1),1,t+2);
;     WAIT_V(6); BAR; MMA(1,1,At,B1); BAR;
;     LDB(B0,1,0); SCHED; LDA(At,1,0); STAGE_A(SA(0,1),1,t+2);
;     WAIT_L(8); BAR; WAIT_L(0); MMA(0,0,At,B0); BAR; SCHED;
.LBB0_562:
	ds_read_b128 v[166:169], v149
	ds_read_b128 v[170:173], v149 offset:1024
	ds_read_b128 v[174:177], v149 offset:2048
	ds_read_b128 v[178:181], v149 offset:3072
	ds_read_b128 v[182:185], v141
	ds_read_b128 v[186:189], v141 offset:1024
	ds_read_b128 v[190:193], v139
	ds_read_b128 v[196:199], v139 offset:1024
	ds_read_b128 v[200:203], v137
	ds_read_b128 v[204:207], v137 offset:1024
	ds_read_b128 v[208:211], v135
	ds_read_b128 v[212:215], v135 offset:1024
	s_add_u32 s23, s4, s12
	s_addc_u32 s24, s5, s13
	s_add_u32 s26, s23, 0x8080080
	s_addc_u32 s27, s24, 0
	v_lshl_add_u64 v[216:217], s[26:27], 0, v[132:133]
	v_readfirstlane_b32 s25, v148
	s_mov_b32 m0, s25
	global_load_lds_dwordx4 v[216:217], off
	v_lshl_add_u64 v[216:217], s[26:27], 0, v[130:131]
	v_readfirstlane_b32 s25, v150
	s_mov_b32 m0, s25
	global_load_lds_dwordx4 v[216:217], off
	s_waitcnt lgkmcnt(8)
	s_barrier
	s_waitcnt lgkmcnt(0)
	s_setprio 1
	v_mfma_f32_16x16x32_bf16 v[126:129], v[166:169], v[182:185], v[126:129]
	v_mfma_f32_16x16x32_bf16 v[122:125], v[174:177], v[182:185], v[122:125]
	v_mfma_f32_16x16x32_bf16 v[118:121], v[166:169], v[190:193], v[118:121]
	v_mfma_f32_16x16x32_bf16 v[114:117], v[174:177], v[190:193], v[114:117]
	v_mfma_f32_16x16x32_bf16 v[110:113], v[166:169], v[200:203], v[110:113]
	v_mfma_f32_16x16x32_bf16 v[106:109], v[174:177], v[200:203], v[106:109]
	v_mfma_f32_16x16x32_bf16 v[102:105], v[166:169], v[208:211], v[102:105]
	v_mfma_f32_16x16x32_bf16 v[98:101], v[174:177], v[208:211], v[98:101]
	v_mfma_f32_16x16x32_bf16 v[126:129], v[170:173], v[186:189], v[126:129]
	v_mfma_f32_16x16x32_bf16 v[122:125], v[178:181], v[186:189], v[122:125]
	v_mfma_f32_16x16x32_bf16 v[118:121], v[170:173], v[196:199], v[118:121]
	v_mfma_f32_16x16x32_bf16 v[114:117], v[178:181], v[196:199], v[114:117]
	v_mfma_f32_16x16x32_bf16 v[110:113], v[170:173], v[204:207], v[110:113]
	v_mfma_f32_16x16x32_bf16 v[106:109], v[178:181], v[204:207], v[106:109]
	v_mfma_f32_16x16x32_bf16 v[102:105], v[170:173], v[212:215], v[102:105]
	v_mfma_f32_16x16x32_bf16 v[98:101], v[178:181], v[212:215], v[98:101]
	s_setprio 0
	s_barrier
	s_add_u32 s25, s4, s14
	ds_read_b128 v[216:219], v147
	ds_read_b128 v[220:223], v147 offset:1024
	ds_read_b128 v[224:227], v147 offset:2048
	ds_read_b128 v[228:231], v147 offset:3072
	s_addc_u32 s26, s5, s15
	s_add_u32 s28, s25, 0x3c00100
	s_addc_u32 s29, s26, 0
	v_lshl_add_u64 v[232:233], s[28:29], 0, v[132:133]
	v_readfirstlane_b32 s27, v152
	s_mov_b32 m0, s27
	global_load_lds_dwordx4 v[232:233], off
	v_lshl_add_u64 v[232:233], s[28:29], 0, v[130:131]
	v_readfirstlane_b32 s27, v154
	s_mov_b32 m0, s27
	global_load_lds_dwordx4 v[232:233], off
	s_barrier
	s_waitcnt lgkmcnt(0)
	s_setprio 1
	v_mfma_f32_16x16x32_bf16 v[94:97], v[216:219], v[182:185], v[94:97]
	v_mfma_f32_16x16x32_bf16 v[90:93], v[224:227], v[182:185], v[90:93]
	v_mfma_f32_16x16x32_bf16 v[86:89], v[216:219], v[190:193], v[86:89]
	v_mfma_f32_16x16x32_bf16 v[82:85], v[224:227], v[190:193], v[82:85]
	v_mfma_f32_16x16x32_bf16 v[78:81], v[216:219], v[200:203], v[78:81]
	v_mfma_f32_16x16x32_bf16 v[74:77], v[224:227], v[200:203], v[74:77]
	v_mfma_f32_16x16x32_bf16 v[70:73], v[216:219], v[208:211], v[70:73]
	v_mfma_f32_16x16x32_bf16 v[66:69], v[224:227], v[208:211], v[66:69]
	v_mfma_f32_16x16x32_bf16 v[94:97], v[220:223], v[186:189], v[94:97]
	v_mfma_f32_16x16x32_bf16 v[90:93], v[228:231], v[186:189], v[90:93]
	v_mfma_f32_16x16x32_bf16 v[86:89], v[220:223], v[196:199], v[86:89]
	v_mfma_f32_16x16x32_bf16 v[82:85], v[228:231], v[196:199], v[82:85]
	v_mfma_f32_16x16x32_bf16 v[78:81], v[220:223], v[204:207], v[78:81]
	v_mfma_f32_16x16x32_bf16 v[74:77], v[228:231], v[204:207], v[74:77]
	v_mfma_f32_16x16x32_bf16 v[70:73], v[220:223], v[212:215], v[70:73]
	v_mfma_f32_16x16x32_bf16 v[66:69], v[228:231], v[212:215], v[66:69]
	s_setprio 0
	s_barrier
	ds_read_b128 v[182:185], v141 offset:16384
	ds_read_b128 v[186:189], v141 offset:17408
	ds_read_b128 v[190:193], v139 offset:16384
	ds_read_b128 v[196:199], v139 offset:17408
	ds_read_b128 v[200:203], v137 offset:16384
	ds_read_b128 v[204:207], v137 offset:17408
	ds_read_b128 v[208:211], v135 offset:16384
	ds_read_b128 v[212:215], v135 offset:17408
	s_add_u32 s28, s23, 0x8000100
	s_addc_u32 s29, s24, 0
	v_lshl_add_u64 v[232:233], s[28:29], 0, v[132:133]
	v_readfirstlane_b32 s27, v138
	s_mov_b32 m0, s27
	global_load_lds_dwordx4 v[232:233], off
	v_lshl_add_u64 v[232:233], s[28:29], 0, v[130:131]
	v_readfirstlane_b32 s27, v156
	s_mov_b32 m0, s27
	global_load_lds_dwordx4 v[232:233], off
	s_barrier
	s_waitcnt lgkmcnt(0)
	s_setprio 1
	v_mfma_f32_16x16x32_bf16 v[62:65], v[166:169], v[182:185], v[62:65]
	v_mfma_f32_16x16x32_bf16 v[58:61], v[174:177], v[182:185], v[58:61]
	v_mfma_f32_16x16x32_bf16 v[54:57], v[166:169], v[190:193], v[54:57]
	v_mfma_f32_16x16x32_bf16 v[50:53], v[174:177], v[190:193], v[50:53]
	v_mfma_f32_16x16x32_bf16 v[46:49], v[166:169], v[200:203], v[46:49]
	v_mfma_f32_16x16x32_bf16 v[42:45], v[174:177], v[200:203], v[42:45]
	v_mfma_f32_16x16x32_bf16 v[38:41], v[166:169], v[208:211], v[38:41]
	v_mfma_f32_16x16x32_bf16 v[34:37], v[174:177], v[208:211], v[34:37]
	v_mfma_f32_16x16x32_bf16 v[62:65], v[170:173], v[186:189], v[62:65]
	v_mfma_f32_16x16x32_bf16 v[58:61], v[178:181], v[186:189], v[58:61]
	v_mfma_f32_16x16x32_bf16 v[54:57], v[170:173], v[196:199], v[54:57]
	v_mfma_f32_16x16x32_bf16 v[50:53], v[178:181], v[196:199], v[50:53]
	v_mfma_f32_16x16x32_bf16 v[46:49], v[170:173], v[204:207], v[46:49]
	v_mfma_f32_16x16x32_bf16 v[42:45], v[178:181], v[204:207], v[42:45]
	v_mfma_f32_16x16x32_bf16 v[38:41], v[170:173], v[212:215], v[38:41]
	v_mfma_f32_16x16x32_bf16 v[34:37], v[178:181], v[212:215], v[34:37]
	s_setprio 0
	s_barrier
;   #define LDA(dst,b,h) for(int m=0;m<4;++m)for(int k=0;k<2;++k) \
;     dst[m][k]=*reinterpret_cast<const bf16x8*>((char*)SA(b,h)+lds_byte(wr*64+m*16+fr,k*32+fq*8))
;   #define LDB(dst,b,h) for(int n=0;n<2;++n)for(int k=0;k<2;++k) \
;     dst[n][k]=*reinterpret_cast<const bf16x8*>((char*)SB(b,h)+lds_byte(wc*32+n*16+fr,k*32+fq*8))
;   #define MMA(ai,bj,At,Bt_) do{__builtin_amdgcn_s_setprio(1); \
;     for(int m=0;m<4;++m)for(int n=0;n<2;++n)for(int k=0;k<2;++k) \
;       acc[ai][bj][m][n]=__builtin_amdgcn_mfma_f32_16x16x32_bf16(Bt_[n][k],At[m][k],acc[ai][bj][m][n],0,0,0); \
;     __builtin_amdgcn_s_setprio(0);}while(0)
;   #define WAIT_V(n) asm volatile("s_waitcnt vmcnt(" #n ")":::"memory")
;   #define WAIT_L(n) asm volatile("s_waitcnt lgkmcnt(" #n ")":::"memory")
;   #define BAR __builtin_amdgcn_s_barrier()
;   #define SCHED __builtin_amdgcn_sched_barrier(0)
; template <bool TWO, class MID> ...
;     ...
;     STAGE_B(SB(0,1),1,t+2);
;     WAIT_V(6); BAR; MMA(1,1,At,B1); BAR;
;     LDB(B0,1,0); SCHED; LDA(At,1,0); STAGE_A(SA(0,1),1,t+2);
;     WAIT_L(8); BAR; WAIT_L(0); MMA(0,0,At,B0); BAR; SCHED;
;     LDB(B1,1,1); STAGE_B(SB(1,0),0,t+3);
;     BAR; WAIT_L(0); MMA(0,1,At,B1); BAR;
;     LDA(At,1,1); STAGE_A(SA(1,0),0,t+3);
;     BAR; WAIT_L(0); MMA(1,0,At,B0); BAR; SCHED;
	s_add_u32 s28, s25, 0x3c80100
	s_addc_u32 s29, s26, 0
	v_lshl_add_u64 v[166:167], s[28:29], 0, v[132:133]
	v_readfirstlane_b32 s27, v158
	s_mov_b32 m0, s27
	global_load_lds_dwordx4 v[166:167], off
	v_lshl_add_u64 v[166:167], s[28:29], 0, v[130:131]
	v_readfirstlane_b32 s27, v160
	s_mov_b32 m0, s27
	global_load_lds_dwordx4 v[166:167], off
	s_waitcnt vmcnt(6)
	s_barrier
	s_setprio 1
	v_mfma_f32_16x16x32_bf16 v[30:33], v[216:219], v[182:185], v[30:33]
	v_mfma_f32_16x16x32_bf16 v[26:29], v[224:227], v[182:185], v[26:29]
	v_mfma_f32_16x16x32_bf16 v[22:25], v[216:219], v[190:193], v[22:25]
	v_mfma_f32_16x16x32_bf16 v[18:21], v[224:227], v[190:193], v[18:21]
	v_mfma_f32_16x16x32_bf16 v[14:17], v[216:219], v[200:203], v[14:17]
	v_mfma_f32_16x16x32_bf16 v[10:13], v[224:227], v[200:203], v[10:13]
	v_mfma_f32_16x16x32_bf16 v[6:9], v[216:219], v[208:211], v[6:9]
	v_mfma_f32_16x16x32_bf16 v[2:5], v[224:227], v[208:211], v[2:5]
	v_mfma_f32_16x16x32_bf16 v[30:33], v[220:223], v[186:189], v[30:33]
	v_mfma_f32_16x16x32_bf16 v[26:29], v[228:231], v[186:189], v[26:29]
	v_mfma_f32_16x16x32_bf16 v[22:25], v[220:223], v[196:199], v[22:25]
	v_mfma_f32_16x16x32_bf16 v[18:21], v[228:231], v[196:199], v[18:21]
	v_mfma_f32_16x16x32_bf16 v[14:17], v[220:223], v[204:207], v[14:17]
	v_mfma_f32_16x16x32_bf16 v[10:13], v[228:231], v[204:207], v[10:13]
	v_mfma_f32_16x16x32_bf16 v[6:9], v[220:223], v[212:215], v[6:9]
	v_mfma_f32_16x16x32_bf16 v[2:5], v[228:231], v[212:215], v[2:5]
	s_setprio 0
	s_barrier
	ds_read_b128 v[166:169], v145
	ds_read_b128 v[170:173], v145 offset:1024
	ds_read_b128 v[174:177], v145 offset:2048
	ds_read_b128 v[178:181], v145 offset:3072
	ds_read_b128 v[182:185], v141 offset:32768
	ds_read_b128 v[186:189], v141 offset:33792
	ds_read_b128 v[190:193], v139 offset:32768
	ds_read_b128 v[196:199], v139 offset:33792
	ds_read_b128 v[200:203], v137 offset:32768
	ds_read_b128 v[204:207], v137 offset:33792
	ds_read_b128 v[208:211], v135 offset:32768
	ds_read_b128 v[212:215], v135 offset:33792
	s_add_u32 s28, s23, 0x8080100
	s_addc_u32 s29, s24, 0
	v_lshl_add_u64 v[216:217], s[28:29], 0, v[132:133]
	v_readfirstlane_b32 s27, v162
	s_mov_b32 m0, s27
	global_load_lds_dwordx4 v[216:217], off
	v_lshl_add_u64 v[216:217], s[28:29], 0, v[130:131]
	v_readfirstlane_b32 s27, v164
	s_mov_b32 m0, s27
	global_load_lds_dwordx4 v[216:217], off
	s_waitcnt lgkmcnt(8)
	s_barrier
	s_waitcnt lgkmcnt(0)
	s_setprio 1
	v_mfma_f32_16x16x32_bf16 v[126:129], v[166:169], v[182:185], v[126:129]
	v_mfma_f32_16x16x32_bf16 v[122:125], v[174:177], v[182:185], v[122:125]
	v_mfma_f32_16x16x32_bf16 v[118:121], v[166:169], v[190:193], v[118:121]
	v_mfma_f32_16x16x32_bf16 v[114:117], v[174:177], v[190:193], v[114:117]
	v_mfma_f32_16x16x32_bf16 v[110:113], v[166:169], v[200:203], v[110:113]
	v_mfma_f32_16x16x32_bf16 v[106:109], v[174:177], v[200:203], v[106:109]
	v_mfma_f32_16x16x32_bf16 v[102:105], v[166:169], v[208:211], v[102:105]
	v_mfma_f32_16x16x32_bf16 v[98:101], v[174:177], v[208:211], v[98:101]
	v_mfma_f32_16x16x32_bf16 v[126:129], v[170:173], v[186:189], v[126:129]
	v_mfma_f32_16x16x32_bf16 v[122:125], v[178:181], v[186:189], v[122:125]
	v_mfma_f32_16x16x32_bf16 v[118:121], v[170:173], v[196:199], v[118:121]
	v_mfma_f32_16x16x32_bf16 v[114:117], v[178:181], v[196:199], v[114:117]
	v_mfma_f32_16x16x32_bf16 v[110:113], v[170:173], v[204:207], v[110:113]
	v_mfma_f32_16x16x32_bf16 v[106:109], v[178:181], v[204:207], v[106:109]
	v_mfma_f32_16x16x32_bf16 v[102:105], v[170:173], v[212:215], v[102:105]
	v_mfma_f32_16x16x32_bf16 v[98:101], v[178:181], v[212:215], v[98:101]
	s_setprio 0
	s_barrier
	ds_read_b128 v[216:219], v143
	ds_read_b128 v[220:223], v143 offset:1024
	ds_read_b128 v[224:227], v143 offset:2048
	ds_read_b128 v[228:231], v143 offset:3072
	s_add_u32 s28, s25, 0x3c00180
	s_addc_u32 s29, s26, 0
	v_lshl_add_u64 v[232:233], s[28:29], 0, v[132:133]
	v_readfirstlane_b32 s27, v134
	s_mov_b32 m0, s27
	global_load_lds_dwordx4 v[232:233], off
	v_lshl_add_u64 v[232:233], s[28:29], 0, v[130:131]
	v_readfirstlane_b32 s27, v136
	s_mov_b32 m0, s27
	global_load_lds_dwordx4 v[232:233], off
	s_barrier
	s_waitcnt lgkmcnt(0)
	s_setprio 1
	v_mfma_f32_16x16x32_bf16 v[94:97], v[216:219], v[182:185], v[94:97]
	v_mfma_f32_16x16x32_bf16 v[90:93], v[224:227], v[182:185], v[90:93]
	v_mfma_f32_16x16x32_bf16 v[86:89], v[216:219], v[190:193], v[86:89]
	v_mfma_f32_16x16x32_bf16 v[82:85], v[224:227], v[190:193], v[82:85]
	v_mfma_f32_16x16x32_bf16 v[78:81], v[216:219], v[200:203], v[78:81]
	v_mfma_f32_16x16x32_bf16 v[74:77], v[224:227], v[200:203], v[74:77]
	v_mfma_f32_16x16x32_bf16 v[70:73], v[216:219], v[208:211], v[70:73]
	v_mfma_f32_16x16x32_bf16 v[66:69], v[224:227], v[208:211], v[66:69]
	v_mfma_f32_16x16x32_bf16 v[94:97], v[220:223], v[186:189], v[94:97]
	v_mfma_f32_16x16x32_bf16 v[90:93], v[228:231], v[186:189], v[90:93]
	v_mfma_f32_16x16x32_bf16 v[86:89], v[220:223], v[196:199], v[86:89]
	v_mfma_f32_16x16x32_bf16 v[82:85], v[228:231], v[196:199], v[82:85]
	v_mfma_f32_16x16x32_bf16 v[78:81], v[220:223], v[204:207], v[78:81]
	v_mfma_f32_16x16x32_bf16 v[74:77], v[228:231], v[204:207], v[74:77]
	v_mfma_f32_16x16x32_bf16 v[70:73], v[220:223], v[212:215], v[70:73]
	v_mfma_f32_16x16x32_bf16 v[66:69], v[228:231], v[212:215], v[66:69]
	s_setprio 0
	s_barrier
	ds_read_b128 v[182:185], v141 offset:49152
	ds_read_b128 v[186:189], v141 offset:50176
	ds_read_b128 v[190:193], v139 offset:49152
	ds_read_b128 v[196:199], v139 offset:50176
	ds_read_b128 v[200:203], v137 offset:49152
	ds_read_b128 v[204:207], v137 offset:50176
	ds_read_b128 v[208:211], v135 offset:49152
	ds_read_b128 v[212:215], v135 offset:50176
	s_add_u32 s28, s23, 0x8000180
	s_addc_u32 s29, s24, 0
	v_lshl_add_u64 v[232:233], s[28:29], 0, v[132:133]
	v_readfirstlane_b32 s23, v140
	s_mov_b32 m0, s23
	global_load_lds_dwordx4 v[232:233], off
	v_lshl_add_u64 v[232:233], s[28:29], 0, v[130:131]
	v_readfirstlane_b32 s23, v142
	s_mov_b32 m0, s23
	global_load_lds_dwordx4 v[232:233], off
	s_barrier
;   #define LDA(dst,b,h) for(int m=0;m<4;++m)for(int k=0;k<2;++k) \
;     dst[m][k]=*reinterpret_cast<const bf16x8*>((char*)SA(b,h)+lds_byte(wr*64+m*16+fr,k*32+fq*8))
;   #define LDB(dst,b,h) for(int n=0;n<2;++n)for(int k=0;k<2;++k) \
;     dst[n][k]=*reinterpret_cast<const bf16x8*>((char*)SB(b,h)+lds_byte(wc*32+n*16+fr,k*32+fq*8))
;   #define MMA(ai,bj,At,Bt_) do{__builtin_amdgcn_s_setprio(1); \
;     for(int m=0;m<4;++m)for(int n=0;n<2;++n)for(int k=0;k<2;++k) \
;       acc[ai][bj][m][n]=__builtin_amdgcn_mfma_f32_16x16x32_bf16(Bt_[n][k],At[m][k],acc[ai][bj][m][n],0,0,0); \
;     __builtin_amdgcn_s_setprio(0);}while(0)
;   #define WAIT_V(n) asm volatile("s_waitcnt vmcnt(" #n ")":::"memory")
;   #define WAIT_L(n) asm volatile("s_waitcnt lgkmcnt(" #n ")":::"memory")
;   #define BAR __builtin_amdgcn_s_barrier()
;   #define SCHED __builtin_amdgcn_sched_barrier(0)
; template <bool TWO, class MID> ...
;     ...
;     BAR; WAIT_L(0); MMA(0,1,At,B1); BAR;
;     LDA(At,1,1); STAGE_A(SA(1,0),0,t+3);
;     BAR; WAIT_L(0); MMA(1,0,At,B0); BAR; SCHED;
;     STAGE_B(SB(1,1),1,t+3);
;     WAIT_V(6); BAR; MMA(1,1,At,B1); BAR;
;   }
;   { LDB(B0,0,0); LDA(At,0,0); STAGE_A(SA(1,1),1,nt-1);
;     BAR; WAIT_L(0); MMA(0,0,At,B0); BAR;
;     LDB(B1,0,1); BAR; WAIT_L(0); MMA(0,1,At,B1); BAR;
	s_waitcnt lgkmcnt(0)
	s_setprio 1
	v_mfma_f32_16x16x32_bf16 v[62:65], v[166:169], v[182:185], v[62:65]
	v_mfma_f32_16x16x32_bf16 v[58:61], v[174:177], v[182:185], v[58:61]
	v_mfma_f32_16x16x32_bf16 v[54:57], v[166:169], v[190:193], v[54:57]
	v_mfma_f32_16x16x32_bf16 v[50:53], v[174:177], v[190:193], v[50:53]
	v_mfma_f32_16x16x32_bf16 v[46:49], v[166:169], v[200:203], v[46:49]
	v_mfma_f32_16x16x32_bf16 v[42:45], v[174:177], v[200:203], v[42:45]
	v_mfma_f32_16x16x32_bf16 v[38:41], v[166:169], v[208:211], v[38:41]
	v_mfma_f32_16x16x32_bf16 v[34:37], v[174:177], v[208:211], v[34:37]
	v_mfma_f32_16x16x32_bf16 v[62:65], v[170:173], v[186:189], v[62:65]
	v_mfma_f32_16x16x32_bf16 v[58:61], v[178:181], v[186:189], v[58:61]
	v_mfma_f32_16x16x32_bf16 v[54:57], v[170:173], v[196:199], v[54:57]
	v_mfma_f32_16x16x32_bf16 v[50:53], v[178:181], v[196:199], v[50:53]
	v_mfma_f32_16x16x32_bf16 v[46:49], v[170:173], v[204:207], v[46:49]
	v_mfma_f32_16x16x32_bf16 v[42:45], v[178:181], v[204:207], v[42:45]
	v_mfma_f32_16x16x32_bf16 v[38:41], v[170:173], v[212:215], v[38:41]
	v_mfma_f32_16x16x32_bf16 v[34:37], v[178:181], v[212:215], v[34:37]
	s_setprio 0
	s_barrier
	s_add_u32 s24, s25, 0x3c80180
	s_addc_u32 s25, s26, 0
	v_lshl_add_u64 v[166:167], s[24:25], 0, v[132:133]
	v_readfirstlane_b32 s23, v144
	s_mov_b32 m0, s23
	global_load_lds_dwordx4 v[166:167], off
	v_lshl_add_u64 v[166:167], s[24:25], 0, v[130:131]
	v_readfirstlane_b32 s23, v146
	s_mov_b32 m0, s23
	global_load_lds_dwordx4 v[166:167], off
	s_waitcnt vmcnt(6)
	s_barrier
	s_setprio 1
	v_mfma_f32_16x16x32_bf16 v[30:33], v[216:219], v[182:185], v[30:33]
	v_mfma_f32_16x16x32_bf16 v[26:29], v[224:227], v[182:185], v[26:29]
	v_mfma_f32_16x16x32_bf16 v[22:25], v[216:219], v[190:193], v[22:25]
	v_mfma_f32_16x16x32_bf16 v[18:21], v[224:227], v[190:193], v[18:21]
	v_mfma_f32_16x16x32_bf16 v[14:17], v[216:219], v[200:203], v[14:17]
	v_mfma_f32_16x16x32_bf16 v[10:13], v[224:227], v[200:203], v[10:13]
	v_mfma_f32_16x16x32_bf16 v[6:9], v[216:219], v[208:211], v[6:9]
	v_mfma_f32_16x16x32_bf16 v[2:5], v[224:227], v[208:211], v[2:5]
	v_mfma_f32_16x16x32_bf16 v[30:33], v[220:223], v[186:189], v[30:33]
	v_mfma_f32_16x16x32_bf16 v[26:29], v[228:231], v[186:189], v[26:29]
	v_mfma_f32_16x16x32_bf16 v[22:25], v[220:223], v[196:199], v[22:25]
	v_mfma_f32_16x16x32_bf16 v[18:21], v[228:231], v[196:199], v[18:21]
	v_mfma_f32_16x16x32_bf16 v[14:17], v[220:223], v[204:207], v[14:17]
	v_mfma_f32_16x16x32_bf16 v[10:13], v[228:231], v[204:207], v[10:13]
	v_mfma_f32_16x16x32_bf16 v[6:9], v[220:223], v[212:215], v[6:9]
	v_mfma_f32_16x16x32_bf16 v[2:5], v[228:231], v[212:215], v[2:5]
	s_setprio 0
	s_add_i32 s22, s22, 2
	s_add_u32 s4, s4, 0x100
	s_addc_u32 s5, s5, 0
	s_cmp_lt_u32 s22, 28
	s_barrier
	s_cbranch_scc1 .LBB0_562
	ds_read_b128 v[152:155], v149
	ds_read_b128 v[156:159], v149 offset:1024
	ds_read_b128 v[160:163], v149 offset:2048
	ds_read_b128 v[164:167], v149 offset:3072
	ds_read_b128 v[168:171], v141
	ds_read_b128 v[172:175], v141 offset:1024
	ds_read_b128 v[176:179], v139
	ds_read_b128 v[180:183], v139 offset:1024
	ds_read_b128 v[184:187], v137
	ds_read_b128 v[188:191], v137 offset:1024
	ds_read_b128 v[196:199], v135
	ds_read_b128 v[200:203], v135 offset:1024
	s_add_u32 s4, s19, 0x80f80
	s_addc_u32 s5, s21, 0
	v_lshl_add_u64 v[132:133], s[4:5], 0, v[132:133]
	v_readfirstlane_b32 s12, v148
	s_mov_b32 m0, s12
	global_load_lds_dwordx4 v[132:133], off
	v_lshl_add_u64 v[130:131], s[4:5], 0, v[130:131]
	v_readfirstlane_b32 s4, v150
	s_mov_b32 m0, s4
	global_load_lds_dwordx4 v[130:131], off
	s_barrier
	s_waitcnt lgkmcnt(0)
	s_setprio 1
	v_mfma_f32_16x16x32_bf16 v[126:129], v[152:155], v[168:171], v[126:129]
	v_mfma_f32_16x16x32_bf16 v[122:125], v[160:163], v[168:171], v[122:125]
	v_mfma_f32_16x16x32_bf16 v[114:117], v[160:163], v[176:179], v[114:117]
	v_mfma_f32_16x16x32_bf16 v[106:109], v[160:163], v[184:187], v[106:109]
	v_mfma_f32_16x16x32_bf16 v[98:101], v[160:163], v[196:199], v[98:101]
	v_mfma_f32_16x16x32_bf16 v[126:129], v[156:159], v[172:175], v[126:129]
	v_mfma_f32_16x16x32_bf16 v[122:125], v[164:167], v[172:175], v[122:125]
	v_mfma_f32_16x16x32_bf16 v[118:121], v[152:155], v[176:179], v[118:121]
	v_mfma_f32_16x16x32_bf16 v[114:117], v[164:167], v[180:183], v[114:117]
	v_mfma_f32_16x16x32_bf16 v[110:113], v[152:155], v[184:187], v[110:113]
	v_mfma_f32_16x16x32_bf16 v[106:109], v[164:167], v[188:191], v[106:109]
	v_mfma_f32_16x16x32_bf16 v[102:105], v[152:155], v[196:199], v[102:105]
	v_mfma_f32_16x16x32_bf16 v[98:101], v[164:167], v[200:203], v[98:101]
	v_mfma_f32_16x16x32_bf16 v[130:133], v[156:159], v[180:183], v[118:121]
	v_mfma_f32_16x16x32_bf16 v[148:151], v[156:159], v[188:191], v[110:113]
	v_mfma_f32_16x16x32_bf16 v[204:207], v[156:159], v[200:203], v[102:105]
	s_setprio 0
	s_barrier
	s_nop 0
	ds_read_b128 v[102:105], v147
	ds_read_b128 v[110:113], v147 offset:1024
	ds_read_b128 v[118:121], v147 offset:2048
	ds_read_b128 v[208:211], v147 offset:3072
	s_barrier
	s_waitcnt lgkmcnt(0)
	s_setprio 1
	v_mfma_f32_16x16x32_bf16 v[90:93], v[118:121], v[168:171], v[90:93]
	v_mfma_f32_16x16x32_bf16 v[82:85], v[118:121], v[176:179], v[82:85]
	v_mfma_f32_16x16x32_bf16 v[74:77], v[118:121], v[184:187], v[74:77]
	v_mfma_f32_16x16x32_bf16 v[66:69], v[118:121], v[196:199], v[66:69]
	v_mfma_f32_16x16x32_bf16 v[94:97], v[102:105], v[168:171], v[94:97]
	v_mfma_f32_16x16x32_bf16 v[90:93], v[208:211], v[172:175], v[90:93]
	v_mfma_f32_16x16x32_bf16 v[86:89], v[102:105], v[176:179], v[86:89]
	v_mfma_f32_16x16x32_bf16 v[82:85], v[208:211], v[180:183], v[82:85]
	v_mfma_f32_16x16x32_bf16 v[78:81], v[102:105], v[184:187], v[78:81]
	v_mfma_f32_16x16x32_bf16 v[74:77], v[208:211], v[188:191], v[74:77]
	v_mfma_f32_16x16x32_bf16 v[70:73], v[102:105], v[196:199], v[70:73]
	v_mfma_f32_16x16x32_bf16 v[66:69], v[208:211], v[200:203], v[66:69]
	v_mfma_f32_16x16x32_bf16 v[212:215], v[110:113], v[172:175], v[94:97]
	v_mfma_f32_16x16x32_bf16 v[168:171], v[110:113], v[180:183], v[86:89]
	v_mfma_f32_16x16x32_bf16 v[172:175], v[110:113], v[188:191], v[78:81]
	v_mfma_f32_16x16x32_bf16 v[176:179], v[110:113], v[200:203], v[70:73]
	s_setprio 0
	s_barrier
;   #define LDA(dst,b,h) for(int m=0;m<4;++m)for(int k=0;k<2;++k) \
;     dst[m][k]=*reinterpret_cast<const bf16x8*>((char*)SA(b,h)+lds_byte(wr*64+m*16+fr,k*32+fq*8))
;   #define LDB(dst,b,h) for(int n=0;n<2;++n)for(int k=0;k<2;++k) \
;     dst[n][k]=*reinterpret_cast<const bf16x8*>((char*)SB(b,h)+lds_byte(wc*32+n*16+fr,k*32+fq*8))
;   #define MMA(ai,bj,At,Bt_) do{__builtin_amdgcn_s_setprio(1); \
;     for(int m=0;m<4;++m)for(int n=0;n<2;++n)for(int k=0;k<2;++k) \
;       acc[ai][bj][m][n]=__builtin_amdgcn_mfma_f32_16x16x32_bf16(Bt_[n][k],At[m][k],acc[ai][bj][m][n],0,0,0); \
;     __builtin_amdgcn_s_setprio(0);}while(0)
;   #define WAIT_V(n) asm volatile("s_waitcnt vmcnt(" #n ")":::"memory")
;   #define WAIT_L(n) asm volatile("s_waitcnt lgkmcnt(" #n ")":::"memory")
;   #define BAR __builtin_amdgcn_s_barrier()
; template <bool TWO, class MID> ...
;     ...
;     LDB(B1,0,1); BAR; WAIT_L(0); MMA(0,1,At,B1); BAR;
;     LDA(At,0,1); WAIT_V(4); BAR; WAIT_L(0); MMA(1,0,At,B0); MMA(1,1,At,B1); BAR; }
;   { LDB(B0,1,0); LDA(At,1,0); WAIT_V(2); BAR; WAIT_L(0); MMA(0,0,At,B0); BAR;
	s_nop 0
	ds_read_b128 v[70:73], v141 offset:16384
	ds_read_b128 v[78:81], v141 offset:17408
	ds_read_b128 v[86:89], v139 offset:16384
	ds_read_b128 v[94:97], v139 offset:17408
	ds_read_b128 v[180:183], v137 offset:16384
	ds_read_b128 v[184:187], v137 offset:17408
	ds_read_b128 v[188:191], v135 offset:16384
	ds_read_b128 v[196:199], v135 offset:17408
	s_waitcnt vmcnt(4)
	s_barrier
	s_waitcnt lgkmcnt(0)
	s_setprio 1
	v_mfma_f32_16x16x32_bf16 v[62:65], v[152:155], v[70:73], v[62:65]
	v_mfma_f32_16x16x32_bf16 v[58:61], v[160:163], v[70:73], v[58:61]
	v_mfma_f32_16x16x32_bf16 v[54:57], v[152:155], v[86:89], v[54:57]
	v_mfma_f32_16x16x32_bf16 v[50:53], v[160:163], v[86:89], v[50:53]
	v_mfma_f32_16x16x32_bf16 v[38:41], v[152:155], v[188:191], v[38:41]
	v_mfma_f32_16x16x32_bf16 v[34:37], v[160:163], v[188:191], v[34:37]
	v_mfma_f32_16x16x32_bf16 v[62:65], v[156:159], v[78:81], v[62:65]
	v_mfma_f32_16x16x32_bf16 v[58:61], v[164:167], v[78:81], v[58:61]
	v_mfma_f32_16x16x32_bf16 v[54:57], v[156:159], v[94:97], v[54:57]
	v_mfma_f32_16x16x32_bf16 v[50:53], v[164:167], v[94:97], v[50:53]
	v_mfma_f32_16x16x32_bf16 v[46:49], v[152:155], v[180:183], v[46:49]
	v_mfma_f32_16x16x32_bf16 v[42:45], v[160:163], v[180:183], v[42:45]
	v_mfma_f32_16x16x32_bf16 v[38:41], v[156:159], v[196:199], v[38:41]
	v_mfma_f32_16x16x32_bf16 v[34:37], v[164:167], v[196:199], v[34:37]
	v_mfma_f32_16x16x32_bf16 v[200:203], v[156:159], v[184:187], v[46:49]
	v_mfma_f32_16x16x32_bf16 v[216:219], v[164:167], v[184:187], v[42:45]
	s_setprio 0
	s_setprio 1
	v_mfma_f32_16x16x32_bf16 v[22:25], v[102:105], v[86:89], v[22:25]
	v_mfma_f32_16x16x32_bf16 v[18:21], v[118:121], v[86:89], v[18:21]
	v_mfma_f32_16x16x32_bf16 v[6:9], v[102:105], v[188:191], v[6:9]
	v_mfma_f32_16x16x32_bf16 v[2:5], v[118:121], v[188:191], v[2:5]
	v_mfma_f32_16x16x32_bf16 v[30:33], v[102:105], v[70:73], v[30:33]
	v_mfma_f32_16x16x32_bf16 v[26:29], v[118:121], v[70:73], v[26:29]
	v_mfma_f32_16x16x32_bf16 v[22:25], v[110:113], v[94:97], v[22:25]
	v_mfma_f32_16x16x32_bf16 v[18:21], v[208:211], v[94:97], v[18:21]
	v_mfma_f32_16x16x32_bf16 v[14:17], v[102:105], v[180:183], v[14:17]
	v_mfma_f32_16x16x32_bf16 v[10:13], v[118:121], v[180:183], v[10:13]
	v_mfma_f32_16x16x32_bf16 v[6:9], v[110:113], v[196:199], v[6:9]
	v_mfma_f32_16x16x32_bf16 v[2:5], v[208:211], v[196:199], v[2:5]
	v_mfma_f32_16x16x32_bf16 v[152:155], v[110:113], v[78:81], v[30:33]
	v_mfma_f32_16x16x32_bf16 v[156:159], v[208:211], v[78:81], v[26:29]
	v_mfma_f32_16x16x32_bf16 v[160:163], v[110:113], v[184:187], v[14:17]
	v_mfma_f32_16x16x32_bf16 v[164:167], v[208:211], v[184:187], v[10:13]
	s_setprio 0
	s_barrier
	s_nop 0
	ds_read_b128 v[10:13], v145
	ds_read_b128 v[14:17], v145 offset:1024
	ds_read_b128 v[180:183], v145 offset:2048
	ds_read_b128 v[144:147], v145 offset:3072
	ds_read_b128 v[26:29], v141 offset:32768
	ds_read_b128 v[30:33], v141 offset:33792
	ds_read_b128 v[42:45], v139 offset:32768
	ds_read_b128 v[46:49], v139 offset:33792
	ds_read_b128 v[184:187], v137 offset:32768
	ds_read_b128 v[188:191], v137 offset:33792
	ds_read_b128 v[196:199], v135 offset:32768
	ds_read_b128 v[208:211], v135 offset:33792
	s_waitcnt vmcnt(2)
	s_barrier
	s_waitcnt lgkmcnt(0)
	s_setprio 1
	v_mfma_f32_16x16x32_bf16 v[70:73], v[10:13], v[26:29], v[126:129]
	v_mfma_f32_16x16x32_bf16 v[126:129], v[14:17], v[30:33], v[70:73]
	v_mfma_f32_16x16x32_bf16 v[70:73], v[180:183], v[26:29], v[122:125]
	v_mfma_f32_16x16x32_bf16 v[118:121], v[144:147], v[30:33], v[70:73]
	v_mfma_f32_16x16x32_bf16 v[70:73], v[10:13], v[42:45], v[130:133]
	v_mfma_f32_16x16x32_bf16 v[110:113], v[14:17], v[46:49], v[70:73]
	v_mfma_f32_16x16x32_bf16 v[70:73], v[180:183], v[42:45], v[114:117]
	v_mfma_f32_16x16x32_bf16 v[102:105], v[144:147], v[46:49], v[70:73]
	v_mfma_f32_16x16x32_bf16 v[70:73], v[10:13], v[184:187], v[148:151]
	v_mfma_f32_16x16x32_bf16 v[94:97], v[14:17], v[188:191], v[70:73]
	v_mfma_f32_16x16x32_bf16 v[70:73], v[180:183], v[184:187], v[106:109]
	v_mfma_f32_16x16x32_bf16 v[86:89], v[144:147], v[188:191], v[70:73]
	v_mfma_f32_16x16x32_bf16 v[70:73], v[10:13], v[196:199], v[204:207]
	v_mfma_f32_16x16x32_bf16 v[78:81], v[14:17], v[208:211], v[70:73]
	v_mfma_f32_16x16x32_bf16 v[70:73], v[180:183], v[196:199], v[98:101]
	v_mfma_f32_16x16x32_bf16 v[70:73], v[144:147], v[208:211], v[70:73]
	s_setprio 0
	s_barrier
;   #define LDA(dst,b,h) for(int m=0;m<4;++m)for(int k=0;k<2;++k) \
;     dst[m][k]=*reinterpret_cast<const bf16x8*>((char*)SA(b,h)+lds_byte(wr*64+m*16+fr,k*32+fq*8))
;   #define LDB(dst,b,h) for(int n=0;n<2;++n)for(int k=0;k<2;++k) \
;     dst[n][k]=*reinterpret_cast<const bf16x8*>((char*)SB(b,h)+lds_byte(wc*32+n*16+fr,k*32+fq*8))
;   #define MMA(ai,bj,At,Bt_) do{__builtin_amdgcn_s_setprio(1); \
;     for(int m=0;m<4;++m)for(int n=0;n<2;++n)for(int k=0;k<2;++k) \
;       acc[ai][bj][m][n]=__builtin_amdgcn_mfma_f32_16x16x32_bf16(Bt_[n][k],At[m][k],acc[ai][bj][m][n],0,0,0); \
;     __builtin_amdgcn_s_setprio(0);}while(0)
;   #define WAIT_V(n) asm volatile("s_waitcnt vmcnt(" #n ")":::"memory")
;   #define WAIT_L(n) asm volatile("s_waitcnt lgkmcnt(" #n ")":::"memory")
;   #define BAR __builtin_amdgcn_s_barrier()
; template <bool TWO, class MID> ...
;     ...
;   { LDB(B0,1,0); LDA(At,1,0); WAIT_V(2); BAR; WAIT_L(0); MMA(0,0,At,B0); BAR;
;     LDB(B1,1,1); WAIT_V(0); BAR; WAIT_L(0); MMA(0,1,At,B1); BAR;
;     LDA(At,1,1); BAR; WAIT_L(0); MMA(1,0,At,B0); MMA(1,1,At,B1); BAR; }
;   if(wr==0)BAR;
	ds_read_b128 v[130:133], v143
	ds_read_b128 v[148:151], v143 offset:1024
	ds_read_b128 v[204:207], v143 offset:2048
	ds_read_b128 v[220:223], v143 offset:3072
	s_waitcnt vmcnt(0)
	s_barrier
	s_waitcnt lgkmcnt(0)
	s_setprio 1
	v_mfma_f32_16x16x32_bf16 v[98:101], v[130:133], v[26:29], v[212:215]
	v_mfma_f32_16x16x32_bf16 v[26:29], v[204:207], v[26:29], v[90:93]
	v_mfma_f32_16x16x32_bf16 v[114:117], v[220:223], v[30:33], v[26:29]
	v_mfma_f32_16x16x32_bf16 v[26:29], v[130:133], v[42:45], v[168:171]
	v_mfma_f32_16x16x32_bf16 v[106:109], v[148:151], v[46:49], v[26:29]
	v_mfma_f32_16x16x32_bf16 v[26:29], v[204:207], v[42:45], v[82:85]
	v_mfma_f32_16x16x32_bf16 v[122:125], v[148:151], v[30:33], v[98:101]
	v_mfma_f32_16x16x32_bf16 v[98:101], v[220:223], v[46:49], v[26:29]
	v_mfma_f32_16x16x32_bf16 v[26:29], v[130:133], v[184:187], v[172:175]
	v_mfma_f32_16x16x32_bf16 v[90:93], v[148:151], v[188:191], v[26:29]
	v_mfma_f32_16x16x32_bf16 v[26:29], v[204:207], v[184:187], v[74:77]
	v_mfma_f32_16x16x32_bf16 v[82:85], v[220:223], v[188:191], v[26:29]
	v_mfma_f32_16x16x32_bf16 v[26:29], v[130:133], v[196:199], v[176:179]
	v_mfma_f32_16x16x32_bf16 v[74:77], v[148:151], v[208:211], v[26:29]
	v_mfma_f32_16x16x32_bf16 v[26:29], v[204:207], v[196:199], v[66:69]
	v_mfma_f32_16x16x32_bf16 v[66:69], v[220:223], v[208:211], v[26:29]
	s_setprio 0
	s_barrier
	ds_read_b128 v[168:171], v141 offset:49152
	ds_read_b128 v[140:143], v141 offset:50176
	ds_read_b128 v[172:175], v139 offset:49152
	ds_read_b128 v[176:179], v139 offset:50176
	ds_read_b128 v[184:187], v137 offset:49152
	ds_read_b128 v[136:139], v137 offset:50176
	ds_read_b128 v[188:191], v135 offset:49152
	ds_read_b128 v[196:199], v135 offset:50176
	s_barrier
	s_waitcnt lgkmcnt(0)
	s_setprio 1
	v_mfma_f32_16x16x32_bf16 v[26:29], v[10:13], v[168:171], v[62:65]
	v_mfma_f32_16x16x32_bf16 v[62:65], v[14:17], v[140:143], v[26:29]
	v_mfma_f32_16x16x32_bf16 v[26:29], v[180:183], v[168:171], v[58:61]
	v_mfma_f32_16x16x32_bf16 v[58:61], v[144:147], v[140:143], v[26:29]
	v_mfma_f32_16x16x32_bf16 v[26:29], v[10:13], v[172:175], v[54:57]
	v_mfma_f32_16x16x32_bf16 v[46:49], v[14:17], v[176:179], v[26:29]
	v_mfma_f32_16x16x32_bf16 v[26:29], v[180:183], v[172:175], v[50:53]
	v_mfma_f32_16x16x32_bf16 v[42:45], v[144:147], v[176:179], v[26:29]
	v_mfma_f32_16x16x32_bf16 v[26:29], v[10:13], v[184:187], v[200:203]
	v_mfma_f32_16x16x32_bf16 v[10:13], v[10:13], v[188:191], v[38:41]
	v_mfma_f32_16x16x32_bf16 v[30:33], v[14:17], v[136:139], v[26:29]
	v_mfma_f32_16x16x32_bf16 v[26:29], v[180:183], v[184:187], v[216:219]
	v_mfma_f32_16x16x32_bf16 v[14:17], v[14:17], v[196:199], v[10:13]
	v_mfma_f32_16x16x32_bf16 v[10:13], v[180:183], v[188:191], v[34:37]
	v_mfma_f32_16x16x32_bf16 v[26:29], v[144:147], v[136:139], v[26:29]
	v_mfma_f32_16x16x32_bf16 v[10:13], v[144:147], v[196:199], v[10:13]
	s_setprio 0
	s_setprio 1
	v_mfma_f32_16x16x32_bf16 v[34:37], v[130:133], v[168:171], v[152:155]
	v_mfma_f32_16x16x32_bf16 v[54:57], v[148:151], v[140:143], v[34:37]
	v_mfma_f32_16x16x32_bf16 v[34:37], v[204:207], v[168:171], v[156:159]
	v_mfma_f32_16x16x32_bf16 v[18:21], v[204:207], v[172:175], v[18:21]
	v_mfma_f32_16x16x32_bf16 v[50:53], v[220:223], v[140:143], v[34:37]
	v_mfma_f32_16x16x32_bf16 v[22:25], v[130:133], v[172:175], v[22:25]
	v_mfma_f32_16x16x32_bf16 v[34:37], v[220:223], v[176:179], v[18:21]
	v_mfma_f32_16x16x32_bf16 v[18:21], v[130:133], v[184:187], v[160:163]
	v_mfma_f32_16x16x32_bf16 v[38:41], v[148:151], v[176:179], v[22:25]
	v_mfma_f32_16x16x32_bf16 v[22:25], v[148:151], v[136:139], v[18:21]
	v_mfma_f32_16x16x32_bf16 v[18:21], v[204:207], v[184:187], v[164:167]
	v_mfma_f32_16x16x32_bf16 v[6:9], v[130:133], v[188:191], v[6:9]
	v_mfma_f32_16x16x32_bf16 v[2:5], v[204:207], v[188:191], v[2:5]
	v_mfma_f32_16x16x32_bf16 v[18:21], v[220:223], v[136:139], v[18:21]
	v_mfma_f32_16x16x32_bf16 v[6:9], v[148:151], v[196:199], v[6:9]
	v_mfma_f32_16x16x32_bf16 v[2:5], v[220:223], v[196:199], v[2:5]
	s_setprio 0
	v_cmp_gt_u32_e32 vcc, s30, v1
	s_barrier
	s_and_saveexec_b64 s[4:5], vcc
	s_cbranch_execz .LBB0_565
	s_barrier

;   #define LDA(dst,b,h) for(int m=0;m<4;++m)for(int k=0;k<2;++k) \
;     dst[m][k]=*reinterpret_cast<const bf16x8*>((char*)SA(b,h)+lds_byte(wr*64+m*16+fr,k*32+fq*8))
;   #define LDB(dst,b,h) for(int n=0;n<2;++n)for(int k=0;k<2;++k) \
;     dst[n][k]=*reinterpret_cast<const bf16x8*>((char*)SB(b,h)+lds_byte(wc*32+n*16+fr,k*32+fq*8))
;   #define MMA(ai,bj,At,Bt_) do{__builtin_amdgcn_s_setprio(1); \
;     for(int m=0;m<4;++m)for(int n=0;n<2;++n)for(int k=0;k<2;++k) \
;       acc[ai][bj][m][n]=__builtin_amdgcn_mfma_f32_16x16x32_bf16(Bt_[n][k],At[m][k],acc[ai][bj][m][n],0,0,0); \
;     __builtin_amdgcn_s_setprio(0);}while(0)
;   #define WAIT_V(n) asm volatile("s_waitcnt vmcnt(" #n ")":::"memory")
;   #define WAIT_L(n) asm volatile("s_waitcnt lgkmcnt(" #n ")":::"memory")
;   #define BAR __builtin_amdgcn_s_barrier()
;   #define SCHED __builtin_amdgcn_sched_barrier(0)
; template <bool TWO, class MID> ...
;     ...
;   for(int t=0;t<nt-2;t+=2){
;     if (TWO && t == nt1) mid();
;     LDB(B0,0,0); SCHED; LDA(At,0,0); STAGE_A(SA(1,1),1,t+1);
;     WAIT_L(8); BAR; WAIT_L(0); MMA(0,0,At,B0); BAR; SCHED;
;     LDB(B1,0,1); STAGE_B(SB(0,0),0,t+2);
;     BAR; WAIT_L(0); MMA(0,1,At,B1); BAR;
;     LDA(At,0,1); STAGE_A(SA(0,0),0,t+2);
;     BAR; WAIT_L(0); MMA(1,0,At,B0); BAR; SCHED;
;     STAGE_B(SB(0,1),1,t+2);
;     WAIT_V(6); BAR; MMA(1,1,At,B1); BAR;
;     LDB(B0,1,0); SCHED; LDA(At,1,0); STAGE_A(SA(0,1),1,t+2);
;     WAIT_L(8); BAR; WAIT_L(0); MMA(0,0,At,B0); BAR; SCHED;
.LBB0_620:
	ds_read_b128 v[166:169], v149
	ds_read_b128 v[170:173], v149 offset:1024
	ds_read_b128 v[174:177], v149 offset:2048
	ds_read_b128 v[178:181], v149 offset:3072
	ds_read_b128 v[182:185], v141
	ds_read_b128 v[186:189], v141 offset:1024
	ds_read_b128 v[190:193], v139
	ds_read_b128 v[196:199], v139 offset:1024
	ds_read_b128 v[200:203], v137
	ds_read_b128 v[204:207], v137 offset:1024
	ds_read_b128 v[208:211], v135
	ds_read_b128 v[212:215], v135 offset:1024
	s_add_u32 s15, s0, s16
	s_addc_u32 s18, s1, s17
	s_add_u32 s24, s15, 0x10200080
	s_addc_u32 s25, s18, 0
	v_lshl_add_u64 v[216:217], s[24:25], 0, v[132:133]
	v_readfirstlane_b32 s19, v148
	s_mov_b32 m0, s19
	global_load_lds_dwordx4 v[216:217], off
	v_lshl_add_u64 v[216:217], s[24:25], 0, v[130:131]
	v_readfirstlane_b32 s19, v150
	s_mov_b32 m0, s19
	global_load_lds_dwordx4 v[216:217], off
	s_waitcnt lgkmcnt(8)
	s_barrier
	s_waitcnt lgkmcnt(0)
	s_setprio 1
	v_mfma_f32_16x16x32_bf16 v[126:129], v[166:169], v[182:185], v[126:129]
	v_mfma_f32_16x16x32_bf16 v[122:125], v[174:177], v[182:185], v[122:125]
	v_mfma_f32_16x16x32_bf16 v[118:121], v[166:169], v[190:193], v[118:121]
	v_mfma_f32_16x16x32_bf16 v[114:117], v[174:177], v[190:193], v[114:117]
	v_mfma_f32_16x16x32_bf16 v[110:113], v[166:169], v[200:203], v[110:113]
	v_mfma_f32_16x16x32_bf16 v[106:109], v[174:177], v[200:203], v[106:109]
	v_mfma_f32_16x16x32_bf16 v[102:105], v[166:169], v[208:211], v[102:105]
	v_mfma_f32_16x16x32_bf16 v[98:101], v[174:177], v[208:211], v[98:101]
	v_mfma_f32_16x16x32_bf16 v[126:129], v[170:173], v[186:189], v[126:129]
	v_mfma_f32_16x16x32_bf16 v[122:125], v[178:181], v[186:189], v[122:125]
	v_mfma_f32_16x16x32_bf16 v[118:121], v[170:173], v[196:199], v[118:121]
	v_mfma_f32_16x16x32_bf16 v[114:117], v[178:181], v[196:199], v[114:117]
	v_mfma_f32_16x16x32_bf16 v[110:113], v[170:173], v[204:207], v[110:113]
	v_mfma_f32_16x16x32_bf16 v[106:109], v[178:181], v[204:207], v[106:109]
	v_mfma_f32_16x16x32_bf16 v[102:105], v[170:173], v[212:215], v[102:105]
	v_mfma_f32_16x16x32_bf16 v[98:101], v[178:181], v[212:215], v[98:101]
	s_setprio 0
	s_barrier
	s_add_u32 s19, s0, s4
	ds_read_b128 v[216:219], v147
	ds_read_b128 v[220:223], v147 offset:1024
	ds_read_b128 v[224:227], v147 offset:2048
	ds_read_b128 v[228:231], v147 offset:3072
	s_addc_u32 s24, s1, s5
	s_add_u32 s26, s19, 0x5c00100
	s_addc_u32 s27, s24, 0
	v_lshl_add_u64 v[232:233], s[26:27], 0, v[132:133]
	v_readfirstlane_b32 s25, v152
	s_mov_b32 m0, s25
	global_load_lds_dwordx4 v[232:233], off
	v_lshl_add_u64 v[232:233], s[26:27], 0, v[130:131]
	v_readfirstlane_b32 s25, v154
	s_mov_b32 m0, s25
	global_load_lds_dwordx4 v[232:233], off
	s_barrier
	s_waitcnt lgkmcnt(0)
	s_setprio 1
	v_mfma_f32_16x16x32_bf16 v[94:97], v[216:219], v[182:185], v[94:97]
	v_mfma_f32_16x16x32_bf16 v[90:93], v[224:227], v[182:185], v[90:93]
	v_mfma_f32_16x16x32_bf16 v[86:89], v[216:219], v[190:193], v[86:89]
	v_mfma_f32_16x16x32_bf16 v[82:85], v[224:227], v[190:193], v[82:85]
	v_mfma_f32_16x16x32_bf16 v[78:81], v[216:219], v[200:203], v[78:81]
	v_mfma_f32_16x16x32_bf16 v[74:77], v[224:227], v[200:203], v[74:77]
	v_mfma_f32_16x16x32_bf16 v[70:73], v[216:219], v[208:211], v[70:73]
	v_mfma_f32_16x16x32_bf16 v[66:69], v[224:227], v[208:211], v[66:69]
	v_mfma_f32_16x16x32_bf16 v[94:97], v[220:223], v[186:189], v[94:97]
	v_mfma_f32_16x16x32_bf16 v[90:93], v[228:231], v[186:189], v[90:93]
	v_mfma_f32_16x16x32_bf16 v[86:89], v[220:223], v[196:199], v[86:89]
	v_mfma_f32_16x16x32_bf16 v[82:85], v[228:231], v[196:199], v[82:85]
	v_mfma_f32_16x16x32_bf16 v[78:81], v[220:223], v[204:207], v[78:81]
	v_mfma_f32_16x16x32_bf16 v[74:77], v[228:231], v[204:207], v[74:77]
	v_mfma_f32_16x16x32_bf16 v[70:73], v[220:223], v[212:215], v[70:73]
	v_mfma_f32_16x16x32_bf16 v[66:69], v[228:231], v[212:215], v[66:69]
	s_setprio 0
	s_barrier
	ds_read_b128 v[182:185], v141 offset:16384
	ds_read_b128 v[186:189], v141 offset:17408
	ds_read_b128 v[190:193], v139 offset:16384
	ds_read_b128 v[196:199], v139 offset:17408
	ds_read_b128 v[200:203], v137 offset:16384
	ds_read_b128 v[204:207], v137 offset:17408
	ds_read_b128 v[208:211], v135 offset:16384
	ds_read_b128 v[212:215], v135 offset:17408
	s_add_u32 s26, s15, 0x10000100
	s_addc_u32 s27, s18, 0
	v_lshl_add_u64 v[232:233], s[26:27], 0, v[132:133]
	v_readfirstlane_b32 s25, v138
	s_mov_b32 m0, s25
	global_load_lds_dwordx4 v[232:233], off
	v_lshl_add_u64 v[232:233], s[26:27], 0, v[130:131]
	v_readfirstlane_b32 s25, v156
	s_mov_b32 m0, s25
	global_load_lds_dwordx4 v[232:233], off
	s_barrier
	s_waitcnt lgkmcnt(0)
	s_setprio 1
	v_mfma_f32_16x16x32_bf16 v[62:65], v[166:169], v[182:185], v[62:65]
	v_mfma_f32_16x16x32_bf16 v[58:61], v[174:177], v[182:185], v[58:61]
	v_mfma_f32_16x16x32_bf16 v[54:57], v[166:169], v[190:193], v[54:57]
	v_mfma_f32_16x16x32_bf16 v[50:53], v[174:177], v[190:193], v[50:53]
	v_mfma_f32_16x16x32_bf16 v[46:49], v[166:169], v[200:203], v[46:49]
	v_mfma_f32_16x16x32_bf16 v[42:45], v[174:177], v[200:203], v[42:45]
	v_mfma_f32_16x16x32_bf16 v[38:41], v[166:169], v[208:211], v[38:41]
	v_mfma_f32_16x16x32_bf16 v[34:37], v[174:177], v[208:211], v[34:37]
	v_mfma_f32_16x16x32_bf16 v[62:65], v[170:173], v[186:189], v[62:65]
	v_mfma_f32_16x16x32_bf16 v[58:61], v[178:181], v[186:189], v[58:61]
	v_mfma_f32_16x16x32_bf16 v[54:57], v[170:173], v[196:199], v[54:57]
	v_mfma_f32_16x16x32_bf16 v[50:53], v[178:181], v[196:199], v[50:53]
	v_mfma_f32_16x16x32_bf16 v[46:49], v[170:173], v[204:207], v[46:49]
	v_mfma_f32_16x16x32_bf16 v[42:45], v[178:181], v[204:207], v[42:45]
	v_mfma_f32_16x16x32_bf16 v[38:41], v[170:173], v[212:215], v[38:41]
	v_mfma_f32_16x16x32_bf16 v[34:37], v[178:181], v[212:215], v[34:37]
	s_setprio 0
	s_barrier
;   #define LDA(dst,b,h) for(int m=0;m<4;++m)for(int k=0;k<2;++k) \
;     dst[m][k]=*reinterpret_cast<const bf16x8*>((char*)SA(b,h)+lds_byte(wr*64+m*16+fr,k*32+fq*8))
;   #define LDB(dst,b,h) for(int n=0;n<2;++n)for(int k=0;k<2;++k) \
;     dst[n][k]=*reinterpret_cast<const bf16x8*>((char*)SB(b,h)+lds_byte(wc*32+n*16+fr,k*32+fq*8))
;   #define MMA(ai,bj,At,Bt_) do{__builtin_amdgcn_s_setprio(1); \
;     for(int m=0;m<4;++m)for(int n=0;n<2;++n)for(int k=0;k<2;++k) \
;       acc[ai][bj][m][n]=__builtin_amdgcn_mfma_f32_16x16x32_bf16(Bt_[n][k],At[m][k],acc[ai][bj][m][n],0,0,0); \
;     __builtin_amdgcn_s_setprio(0);}while(0)
;   #define WAIT_V(n) asm volatile("s_waitcnt vmcnt(" #n ")":::"memory")
;   #define WAIT_L(n) asm volatile("s_waitcnt lgkmcnt(" #n ")":::"memory")
;   #define BAR __builtin_amdgcn_s_barrier()
;   #define SCHED __builtin_amdgcn_sched_barrier(0)
; template <bool TWO, class MID> ...
;     ...
;     STAGE_B(SB(0,1),1,t+2);
;     WAIT_V(6); BAR; MMA(1,1,At,B1); BAR;
;     LDB(B0,1,0); SCHED; LDA(At,1,0); STAGE_A(SA(0,1),1,t+2);
;     WAIT_L(8); BAR; WAIT_L(0); MMA(0,0,At,B0); BAR; SCHED;
;     LDB(B1,1,1); STAGE_B(SB(1,0),0,t+3);
;     BAR; WAIT_L(0); MMA(0,1,At,B1); BAR;
;     LDA(At,1,1); STAGE_A(SA(1,0),0,t+3);
;     BAR; WAIT_L(0); MMA(1,0,At,B0); BAR; SCHED;
	s_add_u32 s26, s19, 0x5e00100
	s_addc_u32 s27, s24, 0
	v_lshl_add_u64 v[166:167], s[26:27], 0, v[132:133]
	v_readfirstlane_b32 s25, v158
	s_mov_b32 m0, s25
	global_load_lds_dwordx4 v[166:167], off
	v_lshl_add_u64 v[166:167], s[26:27], 0, v[130:131]
	v_readfirstlane_b32 s25, v160
	s_mov_b32 m0, s25
	global_load_lds_dwordx4 v[166:167], off
	s_waitcnt vmcnt(6)
	s_barrier
	s_setprio 1
	v_mfma_f32_16x16x32_bf16 v[30:33], v[216:219], v[182:185], v[30:33]
	v_mfma_f32_16x16x32_bf16 v[26:29], v[224:227], v[182:185], v[26:29]
	v_mfma_f32_16x16x32_bf16 v[22:25], v[216:219], v[190:193], v[22:25]
	v_mfma_f32_16x16x32_bf16 v[18:21], v[224:227], v[190:193], v[18:21]
	v_mfma_f32_16x16x32_bf16 v[14:17], v[216:219], v[200:203], v[14:17]
	v_mfma_f32_16x16x32_bf16 v[10:13], v[224:227], v[200:203], v[10:13]
	v_mfma_f32_16x16x32_bf16 v[6:9], v[216:219], v[208:211], v[6:9]
	v_mfma_f32_16x16x32_bf16 v[2:5], v[224:227], v[208:211], v[2:5]
	v_mfma_f32_16x16x32_bf16 v[30:33], v[220:223], v[186:189], v[30:33]
	v_mfma_f32_16x16x32_bf16 v[26:29], v[228:231], v[186:189], v[26:29]
	v_mfma_f32_16x16x32_bf16 v[22:25], v[220:223], v[196:199], v[22:25]
	v_mfma_f32_16x16x32_bf16 v[18:21], v[228:231], v[196:199], v[18:21]
	v_mfma_f32_16x16x32_bf16 v[14:17], v[220:223], v[204:207], v[14:17]
	v_mfma_f32_16x16x32_bf16 v[10:13], v[228:231], v[204:207], v[10:13]
	v_mfma_f32_16x16x32_bf16 v[6:9], v[220:223], v[212:215], v[6:9]
	v_mfma_f32_16x16x32_bf16 v[2:5], v[228:231], v[212:215], v[2:5]
	s_setprio 0
	s_barrier
	ds_read_b128 v[166:169], v145
	ds_read_b128 v[170:173], v145 offset:1024
	ds_read_b128 v[174:177], v145 offset:2048
	ds_read_b128 v[178:181], v145 offset:3072
	ds_read_b128 v[182:185], v141 offset:32768
	ds_read_b128 v[186:189], v141 offset:33792
	ds_read_b128 v[190:193], v139 offset:32768
	ds_read_b128 v[196:199], v139 offset:33792
	ds_read_b128 v[200:203], v137 offset:32768
	ds_read_b128 v[204:207], v137 offset:33792
	ds_read_b128 v[208:211], v135 offset:32768
	ds_read_b128 v[212:215], v135 offset:33792
	s_add_u32 s26, s15, 0x10200100
	s_addc_u32 s27, s18, 0
	v_lshl_add_u64 v[216:217], s[26:27], 0, v[132:133]
	v_readfirstlane_b32 s25, v162
	s_mov_b32 m0, s25
	global_load_lds_dwordx4 v[216:217], off
	v_lshl_add_u64 v[216:217], s[26:27], 0, v[130:131]
	v_readfirstlane_b32 s25, v164
	s_mov_b32 m0, s25
	global_load_lds_dwordx4 v[216:217], off
	s_waitcnt lgkmcnt(8)
	s_barrier
	s_waitcnt lgkmcnt(0)
	s_setprio 1
	v_mfma_f32_16x16x32_bf16 v[126:129], v[166:169], v[182:185], v[126:129]
	v_mfma_f32_16x16x32_bf16 v[122:125], v[174:177], v[182:185], v[122:125]
	v_mfma_f32_16x16x32_bf16 v[118:121], v[166:169], v[190:193], v[118:121]
	v_mfma_f32_16x16x32_bf16 v[114:117], v[174:177], v[190:193], v[114:117]
	v_mfma_f32_16x16x32_bf16 v[110:113], v[166:169], v[200:203], v[110:113]
	v_mfma_f32_16x16x32_bf16 v[106:109], v[174:177], v[200:203], v[106:109]
	v_mfma_f32_16x16x32_bf16 v[102:105], v[166:169], v[208:211], v[102:105]
	v_mfma_f32_16x16x32_bf16 v[98:101], v[174:177], v[208:211], v[98:101]
	v_mfma_f32_16x16x32_bf16 v[126:129], v[170:173], v[186:189], v[126:129]
	v_mfma_f32_16x16x32_bf16 v[122:125], v[178:181], v[186:189], v[122:125]
	v_mfma_f32_16x16x32_bf16 v[118:121], v[170:173], v[196:199], v[118:121]
	v_mfma_f32_16x16x32_bf16 v[114:117], v[178:181], v[196:199], v[114:117]
	v_mfma_f32_16x16x32_bf16 v[110:113], v[170:173], v[204:207], v[110:113]
	v_mfma_f32_16x16x32_bf16 v[106:109], v[178:181], v[204:207], v[106:109]
	v_mfma_f32_16x16x32_bf16 v[102:105], v[170:173], v[212:215], v[102:105]
	v_mfma_f32_16x16x32_bf16 v[98:101], v[178:181], v[212:215], v[98:101]
	s_setprio 0
	s_barrier
	ds_read_b128 v[216:219], v143
	ds_read_b128 v[220:223], v143 offset:1024
	ds_read_b128 v[224:227], v143 offset:2048
	ds_read_b128 v[228:231], v143 offset:3072
	s_add_u32 s26, s19, 0x5c00180
	s_addc_u32 s27, s24, 0
	v_lshl_add_u64 v[232:233], s[26:27], 0, v[132:133]
	v_readfirstlane_b32 s25, v134
	s_mov_b32 m0, s25
	global_load_lds_dwordx4 v[232:233], off
	v_lshl_add_u64 v[232:233], s[26:27], 0, v[130:131]
	v_readfirstlane_b32 s25, v136
	s_mov_b32 m0, s25
	global_load_lds_dwordx4 v[232:233], off
	s_barrier
	s_waitcnt lgkmcnt(0)
	s_setprio 1
	v_mfma_f32_16x16x32_bf16 v[94:97], v[216:219], v[182:185], v[94:97]
	v_mfma_f32_16x16x32_bf16 v[90:93], v[224:227], v[182:185], v[90:93]
	v_mfma_f32_16x16x32_bf16 v[86:89], v[216:219], v[190:193], v[86:89]
	v_mfma_f32_16x16x32_bf16 v[82:85], v[224:227], v[190:193], v[82:85]
	v_mfma_f32_16x16x32_bf16 v[78:81], v[216:219], v[200:203], v[78:81]
	v_mfma_f32_16x16x32_bf16 v[74:77], v[224:227], v[200:203], v[74:77]
	v_mfma_f32_16x16x32_bf16 v[70:73], v[216:219], v[208:211], v[70:73]
	v_mfma_f32_16x16x32_bf16 v[66:69], v[224:227], v[208:211], v[66:69]
	v_mfma_f32_16x16x32_bf16 v[94:97], v[220:223], v[186:189], v[94:97]
	v_mfma_f32_16x16x32_bf16 v[90:93], v[228:231], v[186:189], v[90:93]
	v_mfma_f32_16x16x32_bf16 v[86:89], v[220:223], v[196:199], v[86:89]
	v_mfma_f32_16x16x32_bf16 v[82:85], v[228:231], v[196:199], v[82:85]
	v_mfma_f32_16x16x32_bf16 v[78:81], v[220:223], v[204:207], v[78:81]
	v_mfma_f32_16x16x32_bf16 v[74:77], v[228:231], v[204:207], v[74:77]
	v_mfma_f32_16x16x32_bf16 v[70:73], v[220:223], v[212:215], v[70:73]
	v_mfma_f32_16x16x32_bf16 v[66:69], v[228:231], v[212:215], v[66:69]
	s_setprio 0
	s_barrier
	ds_read_b128 v[182:185], v141 offset:49152
	ds_read_b128 v[186:189], v141 offset:50176
	ds_read_b128 v[190:193], v139 offset:49152
	ds_read_b128 v[196:199], v139 offset:50176
	ds_read_b128 v[200:203], v137 offset:49152
	ds_read_b128 v[204:207], v137 offset:50176
	ds_read_b128 v[208:211], v135 offset:49152
	ds_read_b128 v[212:215], v135 offset:50176
	s_add_u32 s26, s15, 0x10000180
	s_addc_u32 s27, s18, 0
	v_lshl_add_u64 v[232:233], s[26:27], 0, v[132:133]
	v_readfirstlane_b32 s15, v140
	s_mov_b32 m0, s15
	global_load_lds_dwordx4 v[232:233], off
	v_lshl_add_u64 v[232:233], s[26:27], 0, v[130:131]
	v_readfirstlane_b32 s15, v142
	s_mov_b32 m0, s15
	global_load_lds_dwordx4 v[232:233], off
	s_barrier
;   #define LDA(dst,b,h) for(int m=0;m<4;++m)for(int k=0;k<2;++k) \
;     dst[m][k]=*reinterpret_cast<const bf16x8*>((char*)SA(b,h)+lds_byte(wr*64+m*16+fr,k*32+fq*8))
;   #define LDB(dst,b,h) for(int n=0;n<2;++n)for(int k=0;k<2;++k) \
;     dst[n][k]=*reinterpret_cast<const bf16x8*>((char*)SB(b,h)+lds_byte(wc*32+n*16+fr,k*32+fq*8))
;   #define MMA(ai,bj,At,Bt_) do{__builtin_amdgcn_s_setprio(1); \
;     for(int m=0;m<4;++m)for(int n=0;n<2;++n)for(int k=0;k<2;++k) \
;       acc[ai][bj][m][n]=__builtin_amdgcn_mfma_f32_16x16x32_bf16(Bt_[n][k],At[m][k],acc[ai][bj][m][n],0,0,0); \
;     __builtin_amdgcn_s_setprio(0);}while(0)
;   #define WAIT_V(n) asm volatile("s_waitcnt vmcnt(" #n ")":::"memory")
;   #define WAIT_L(n) asm volatile("s_waitcnt lgkmcnt(" #n ")":::"memory")
;   #define BAR __builtin_amdgcn_s_barrier()
; template <bool TWO, class MID> ...
;     ...
;     STAGE_B(SB(1,1),1,t+3);
;     WAIT_V(6); BAR; MMA(1,1,At,B1); BAR;
;   }
;   { LDB(B0,0,0); LDA(At,0,0); STAGE_A(SA(1,1),1,nt-1);
;     BAR; WAIT_L(0); MMA(0,0,At,B0); BAR;
;     LDB(B1,0,1); BAR; WAIT_L(0); MMA(0,1,At,B1); BAR;
;     LDA(At,0,1); WAIT_V(4); BAR; WAIT_L(0); MMA(1,0,At,B0); MMA(1,1,At,B1); BAR; }
	s_waitcnt lgkmcnt(0)
	s_setprio 1
	v_mfma_f32_16x16x32_bf16 v[62:65], v[166:169], v[182:185], v[62:65]
	v_mfma_f32_16x16x32_bf16 v[58:61], v[174:177], v[182:185], v[58:61]
	v_mfma_f32_16x16x32_bf16 v[54:57], v[166:169], v[190:193], v[54:57]
	v_mfma_f32_16x16x32_bf16 v[50:53], v[174:177], v[190:193], v[50:53]
	v_mfma_f32_16x16x32_bf16 v[46:49], v[166:169], v[200:203], v[46:49]
	v_mfma_f32_16x16x32_bf16 v[42:45], v[174:177], v[200:203], v[42:45]
	v_mfma_f32_16x16x32_bf16 v[38:41], v[166:169], v[208:211], v[38:41]
	v_mfma_f32_16x16x32_bf16 v[34:37], v[174:177], v[208:211], v[34:37]
	v_mfma_f32_16x16x32_bf16 v[62:65], v[170:173], v[186:189], v[62:65]
	v_mfma_f32_16x16x32_bf16 v[58:61], v[178:181], v[186:189], v[58:61]
	v_mfma_f32_16x16x32_bf16 v[54:57], v[170:173], v[196:199], v[54:57]
	v_mfma_f32_16x16x32_bf16 v[50:53], v[178:181], v[196:199], v[50:53]
	v_mfma_f32_16x16x32_bf16 v[46:49], v[170:173], v[204:207], v[46:49]
	v_mfma_f32_16x16x32_bf16 v[42:45], v[178:181], v[204:207], v[42:45]
	v_mfma_f32_16x16x32_bf16 v[38:41], v[170:173], v[212:215], v[38:41]
	v_mfma_f32_16x16x32_bf16 v[34:37], v[178:181], v[212:215], v[34:37]
	s_setprio 0
	s_barrier
	s_add_u32 s18, s19, 0x5e00180
	s_addc_u32 s19, s24, 0
	v_lshl_add_u64 v[166:167], s[18:19], 0, v[132:133]
	v_readfirstlane_b32 s15, v144
	s_mov_b32 m0, s15
	global_load_lds_dwordx4 v[166:167], off
	v_lshl_add_u64 v[166:167], s[18:19], 0, v[130:131]
	v_readfirstlane_b32 s15, v146
	s_mov_b32 m0, s15
	global_load_lds_dwordx4 v[166:167], off
	s_waitcnt vmcnt(6)
	s_barrier
	s_setprio 1
	v_mfma_f32_16x16x32_bf16 v[30:33], v[216:219], v[182:185], v[30:33]
	v_mfma_f32_16x16x32_bf16 v[26:29], v[224:227], v[182:185], v[26:29]
	v_mfma_f32_16x16x32_bf16 v[22:25], v[216:219], v[190:193], v[22:25]
	v_mfma_f32_16x16x32_bf16 v[18:21], v[224:227], v[190:193], v[18:21]
	v_mfma_f32_16x16x32_bf16 v[14:17], v[216:219], v[200:203], v[14:17]
	v_mfma_f32_16x16x32_bf16 v[10:13], v[224:227], v[200:203], v[10:13]
	v_mfma_f32_16x16x32_bf16 v[6:9], v[216:219], v[208:211], v[6:9]
	v_mfma_f32_16x16x32_bf16 v[2:5], v[224:227], v[208:211], v[2:5]
	v_mfma_f32_16x16x32_bf16 v[30:33], v[220:223], v[186:189], v[30:33]
	v_mfma_f32_16x16x32_bf16 v[26:29], v[228:231], v[186:189], v[26:29]
	v_mfma_f32_16x16x32_bf16 v[22:25], v[220:223], v[196:199], v[22:25]
	v_mfma_f32_16x16x32_bf16 v[18:21], v[228:231], v[196:199], v[18:21]
	v_mfma_f32_16x16x32_bf16 v[14:17], v[220:223], v[204:207], v[14:17]
	v_mfma_f32_16x16x32_bf16 v[10:13], v[228:231], v[204:207], v[10:13]
	v_mfma_f32_16x16x32_bf16 v[6:9], v[220:223], v[212:215], v[6:9]
	v_mfma_f32_16x16x32_bf16 v[2:5], v[228:231], v[212:215], v[2:5]
	s_setprio 0
	s_add_i32 s14, s14, 2
	s_add_u32 s0, s0, 0x100
	s_addc_u32 s1, s1, 0
	s_cmpk_lt_u32 s14, 0x7c
	s_barrier
	s_cbranch_scc1 .LBB0_620
	ds_read_b128 v[152:155], v149
	ds_read_b128 v[156:159], v149 offset:1024
	ds_read_b128 v[160:163], v149 offset:2048
	ds_read_b128 v[164:167], v149 offset:3072
	ds_read_b128 v[168:171], v141
	ds_read_b128 v[172:175], v141 offset:1024
	ds_read_b128 v[176:179], v139
	ds_read_b128 v[180:183], v139 offset:1024
	ds_read_b128 v[184:187], v137
	ds_read_b128 v[188:191], v137 offset:1024
	ds_read_b128 v[196:199], v135
	ds_read_b128 v[200:203], v135 offset:1024
	s_add_u32 s0, s12, 0x203f80
	s_addc_u32 s1, s13, 0
	v_lshl_add_u64 v[132:133], s[0:1], 0, v[132:133]
	v_readfirstlane_b32 s12, v148
	s_mov_b32 m0, s12
	global_load_lds_dwordx4 v[132:133], off
	v_lshl_add_u64 v[130:131], s[0:1], 0, v[130:131]
	v_readfirstlane_b32 s0, v150
	s_mov_b32 m0, s0
	global_load_lds_dwordx4 v[130:131], off
	s_barrier
	s_waitcnt lgkmcnt(0)
	s_setprio 1
	v_mfma_f32_16x16x32_bf16 v[126:129], v[152:155], v[168:171], v[126:129]
	v_mfma_f32_16x16x32_bf16 v[122:125], v[160:163], v[168:171], v[122:125]
	v_mfma_f32_16x16x32_bf16 v[118:121], v[152:155], v[176:179], v[118:121]
	v_mfma_f32_16x16x32_bf16 v[114:117], v[160:163], v[176:179], v[114:117]
	v_mfma_f32_16x16x32_bf16 v[102:105], v[152:155], v[196:199], v[102:105]
	v_mfma_f32_16x16x32_bf16 v[98:101], v[160:163], v[196:199], v[98:101]
	v_mfma_f32_16x16x32_bf16 v[126:129], v[156:159], v[172:175], v[126:129]
	v_mfma_f32_16x16x32_bf16 v[122:125], v[164:167], v[172:175], v[122:125]
	v_mfma_f32_16x16x32_bf16 v[118:121], v[156:159], v[180:183], v[118:121]
	v_mfma_f32_16x16x32_bf16 v[114:117], v[164:167], v[180:183], v[114:117]
	v_mfma_f32_16x16x32_bf16 v[110:113], v[152:155], v[184:187], v[110:113]
	v_mfma_f32_16x16x32_bf16 v[106:109], v[160:163], v[184:187], v[106:109]
	v_mfma_f32_16x16x32_bf16 v[102:105], v[156:159], v[200:203], v[102:105]
	v_mfma_f32_16x16x32_bf16 v[98:101], v[164:167], v[200:203], v[98:101]
	v_mfma_f32_16x16x32_bf16 v[130:133], v[156:159], v[188:191], v[110:113]
	v_mfma_f32_16x16x32_bf16 v[148:151], v[164:167], v[188:191], v[106:109]
	s_setprio 0
	s_barrier
	s_nop 0
	ds_read_b128 v[106:109], v147
	ds_read_b128 v[110:113], v147 offset:1024
	ds_read_b128 v[204:207], v147 offset:2048
	ds_read_b128 v[208:211], v147 offset:3072
	s_barrier
	s_waitcnt lgkmcnt(0)
	s_setprio 1
	v_mfma_f32_16x16x32_bf16 v[86:89], v[106:109], v[176:179], v[86:89]
	v_mfma_f32_16x16x32_bf16 v[82:85], v[204:207], v[176:179], v[82:85]
	v_mfma_f32_16x16x32_bf16 v[70:73], v[106:109], v[196:199], v[70:73]
	v_mfma_f32_16x16x32_bf16 v[66:69], v[204:207], v[196:199], v[66:69]
	v_mfma_f32_16x16x32_bf16 v[94:97], v[106:109], v[168:171], v[94:97]
	v_mfma_f32_16x16x32_bf16 v[90:93], v[204:207], v[168:171], v[90:93]
	v_mfma_f32_16x16x32_bf16 v[86:89], v[110:113], v[180:183], v[86:89]
	v_mfma_f32_16x16x32_bf16 v[82:85], v[208:211], v[180:183], v[82:85]
	v_mfma_f32_16x16x32_bf16 v[78:81], v[106:109], v[184:187], v[78:81]
	v_mfma_f32_16x16x32_bf16 v[74:77], v[204:207], v[184:187], v[74:77]
	v_mfma_f32_16x16x32_bf16 v[70:73], v[110:113], v[200:203], v[70:73]
	v_mfma_f32_16x16x32_bf16 v[66:69], v[208:211], v[200:203], v[66:69]
	v_mfma_f32_16x16x32_bf16 v[212:215], v[110:113], v[172:175], v[94:97]
	v_mfma_f32_16x16x32_bf16 v[168:171], v[208:211], v[172:175], v[90:93]
	v_mfma_f32_16x16x32_bf16 v[172:175], v[110:113], v[188:191], v[78:81]
	v_mfma_f32_16x16x32_bf16 v[176:179], v[208:211], v[188:191], v[74:77]
	s_setprio 0
	s_barrier
;   #define LDA(dst,b,h) for(int m=0;m<4;++m)for(int k=0;k<2;++k) \
;     dst[m][k]=*reinterpret_cast<const bf16x8*>((char*)SA(b,h)+lds_byte(wr*64+m*16+fr,k*32+fq*8))
;   #define LDB(dst,b,h) for(int n=0;n<2;++n)for(int k=0;k<2;++k) \
;     dst[n][k]=*reinterpret_cast<const bf16x8*>((char*)SB(b,h)+lds_byte(wc*32+n*16+fr,k*32+fq*8))
;   #define MMA(ai,bj,At,Bt_) do{__builtin_amdgcn_s_setprio(1); \
;     for(int m=0;m<4;++m)for(int n=0;n<2;++n)for(int k=0;k<2;++k) \
;       acc[ai][bj][m][n]=__builtin_amdgcn_mfma_f32_16x16x32_bf16(Bt_[n][k],At[m][k],acc[ai][bj][m][n],0,0,0); \
;     __builtin_amdgcn_s_setprio(0);}while(0)
;   #define WAIT_V(n) asm volatile("s_waitcnt vmcnt(" #n ")":::"memory")
;   #define WAIT_L(n) asm volatile("s_waitcnt lgkmcnt(" #n ")":::"memory")
;   #define BAR __builtin_amdgcn_s_barrier()
; template <bool TWO, class MID> ...
;     ...
;     LDA(At,0,1); WAIT_V(4); BAR; WAIT_L(0); MMA(1,0,At,B0); MMA(1,1,At,B1); BAR; }
;   { LDB(B0,1,0); LDA(At,1,0); WAIT_V(2); BAR; WAIT_L(0); MMA(0,0,At,B0); BAR;
;     LDB(B1,1,1); WAIT_V(0); BAR; WAIT_L(0); MMA(0,1,At,B1); BAR;
;     LDA(At,1,1); BAR; WAIT_L(0); MMA(1,0,At,B0); MMA(1,1,At,B1); BAR; }
	s_nop 0
	ds_read_b128 v[74:77], v141 offset:16384
	ds_read_b128 v[78:81], v141 offset:17408
	ds_read_b128 v[90:93], v139 offset:16384
	ds_read_b128 v[94:97], v139 offset:17408
	ds_read_b128 v[180:183], v137 offset:16384
	ds_read_b128 v[184:187], v137 offset:17408
	ds_read_b128 v[188:191], v135 offset:16384
	ds_read_b128 v[196:199], v135 offset:17408
	s_waitcnt vmcnt(4)
	s_barrier
	s_waitcnt lgkmcnt(0)
	s_setprio 1
	v_mfma_f32_16x16x32_bf16 v[62:65], v[152:155], v[74:77], v[62:65]
	v_mfma_f32_16x16x32_bf16 v[58:61], v[160:163], v[74:77], v[58:61]
	v_mfma_f32_16x16x32_bf16 v[54:57], v[152:155], v[90:93], v[54:57]
	v_mfma_f32_16x16x32_bf16 v[50:53], v[160:163], v[90:93], v[50:53]
	v_mfma_f32_16x16x32_bf16 v[38:41], v[152:155], v[188:191], v[38:41]
	v_mfma_f32_16x16x32_bf16 v[34:37], v[160:163], v[188:191], v[34:37]
	v_mfma_f32_16x16x32_bf16 v[62:65], v[156:159], v[78:81], v[62:65]
	v_mfma_f32_16x16x32_bf16 v[58:61], v[164:167], v[78:81], v[58:61]
	v_mfma_f32_16x16x32_bf16 v[54:57], v[156:159], v[94:97], v[54:57]
	v_mfma_f32_16x16x32_bf16 v[50:53], v[164:167], v[94:97], v[50:53]
	v_mfma_f32_16x16x32_bf16 v[46:49], v[152:155], v[180:183], v[46:49]
	v_mfma_f32_16x16x32_bf16 v[42:45], v[160:163], v[180:183], v[42:45]
	v_mfma_f32_16x16x32_bf16 v[38:41], v[156:159], v[196:199], v[38:41]
	v_mfma_f32_16x16x32_bf16 v[34:37], v[164:167], v[196:199], v[34:37]
	v_mfma_f32_16x16x32_bf16 v[200:203], v[156:159], v[184:187], v[46:49]
	v_mfma_f32_16x16x32_bf16 v[216:219], v[164:167], v[184:187], v[42:45]
	s_setprio 0
	s_setprio 1
	v_mfma_f32_16x16x32_bf16 v[22:25], v[106:109], v[90:93], v[22:25]
	v_mfma_f32_16x16x32_bf16 v[18:21], v[204:207], v[90:93], v[18:21]
	v_mfma_f32_16x16x32_bf16 v[6:9], v[106:109], v[188:191], v[6:9]
	v_mfma_f32_16x16x32_bf16 v[2:5], v[204:207], v[188:191], v[2:5]
	v_mfma_f32_16x16x32_bf16 v[30:33], v[106:109], v[74:77], v[30:33]
	v_mfma_f32_16x16x32_bf16 v[26:29], v[204:207], v[74:77], v[26:29]
	v_mfma_f32_16x16x32_bf16 v[22:25], v[110:113], v[94:97], v[22:25]
	v_mfma_f32_16x16x32_bf16 v[18:21], v[208:211], v[94:97], v[18:21]
	v_mfma_f32_16x16x32_bf16 v[14:17], v[106:109], v[180:183], v[14:17]
	v_mfma_f32_16x16x32_bf16 v[10:13], v[204:207], v[180:183], v[10:13]
	v_mfma_f32_16x16x32_bf16 v[6:9], v[110:113], v[196:199], v[6:9]
	v_mfma_f32_16x16x32_bf16 v[2:5], v[208:211], v[196:199], v[2:5]
	v_mfma_f32_16x16x32_bf16 v[152:155], v[110:113], v[78:81], v[30:33]
	v_mfma_f32_16x16x32_bf16 v[156:159], v[208:211], v[78:81], v[26:29]
	v_mfma_f32_16x16x32_bf16 v[160:163], v[110:113], v[184:187], v[14:17]
	v_mfma_f32_16x16x32_bf16 v[164:167], v[208:211], v[184:187], v[10:13]
	s_setprio 0
	s_barrier
	s_nop 0
	ds_read_b128 v[10:13], v145
	ds_read_b128 v[14:17], v145 offset:1024
	ds_read_b128 v[180:183], v145 offset:2048
	ds_read_b128 v[144:147], v145 offset:3072
	ds_read_b128 v[26:29], v141 offset:32768
	ds_read_b128 v[30:33], v141 offset:33792
	ds_read_b128 v[42:45], v139 offset:32768
	ds_read_b128 v[46:49], v139 offset:33792
	ds_read_b128 v[184:187], v137 offset:32768
	ds_read_b128 v[188:191], v137 offset:33792
	ds_read_b128 v[196:199], v135 offset:32768
	ds_read_b128 v[204:207], v135 offset:33792
	s_waitcnt vmcnt(2)
	s_barrier
	s_waitcnt lgkmcnt(0)
	s_setprio 1
	v_mfma_f32_16x16x32_bf16 v[74:77], v[10:13], v[26:29], v[126:129]
	v_mfma_f32_16x16x32_bf16 v[126:129], v[14:17], v[30:33], v[74:77]
	v_mfma_f32_16x16x32_bf16 v[74:77], v[180:183], v[26:29], v[122:125]
	v_mfma_f32_16x16x32_bf16 v[122:125], v[144:147], v[30:33], v[74:77]
	v_mfma_f32_16x16x32_bf16 v[74:77], v[10:13], v[42:45], v[118:121]
	v_mfma_f32_16x16x32_bf16 v[110:113], v[14:17], v[46:49], v[74:77]
	v_mfma_f32_16x16x32_bf16 v[74:77], v[180:183], v[42:45], v[114:117]
	v_mfma_f32_16x16x32_bf16 v[106:109], v[144:147], v[46:49], v[74:77]
	v_mfma_f32_16x16x32_bf16 v[74:77], v[10:13], v[184:187], v[130:133]
	v_mfma_f32_16x16x32_bf16 v[94:97], v[14:17], v[188:191], v[74:77]
	v_mfma_f32_16x16x32_bf16 v[74:77], v[180:183], v[184:187], v[148:151]
	v_mfma_f32_16x16x32_bf16 v[90:93], v[144:147], v[188:191], v[74:77]
	v_mfma_f32_16x16x32_bf16 v[74:77], v[10:13], v[196:199], v[102:105]
	v_mfma_f32_16x16x32_bf16 v[78:81], v[14:17], v[204:207], v[74:77]
	v_mfma_f32_16x16x32_bf16 v[74:77], v[180:183], v[196:199], v[98:101]
	v_mfma_f32_16x16x32_bf16 v[74:77], v[144:147], v[204:207], v[74:77]
	s_setprio 0
	s_barrier
;   #define LDA(dst,b,h) for(int m=0;m<4;++m)for(int k=0;k<2;++k) \
;     dst[m][k]=*reinterpret_cast<const bf16x8*>((char*)SA(b,h)+lds_byte(wr*64+m*16+fr,k*32+fq*8))
;   #define LDB(dst,b,h) for(int n=0;n<2;++n)for(int k=0;k<2;++k) \
;     dst[n][k]=*reinterpret_cast<const bf16x8*>((char*)SB(b,h)+lds_byte(wc*32+n*16+fr,k*32+fq*8))
;   #define MMA(ai,bj,At,Bt_) do{__builtin_amdgcn_s_setprio(1); \
;     for(int m=0;m<4;++m)for(int n=0;n<2;++n)for(int k=0;k<2;++k) \
;       acc[ai][bj][m][n]=__builtin_amdgcn_mfma_f32_16x16x32_bf16(Bt_[n][k],At[m][k],acc[ai][bj][m][n],0,0,0); \
;     __builtin_amdgcn_s_setprio(0);}while(0)
;   #define WAIT_V(n) asm volatile("s_waitcnt vmcnt(" #n ")":::"memory")
;   #define WAIT_L(n) asm volatile("s_waitcnt lgkmcnt(" #n ")":::"memory")
;   #define BAR __builtin_amdgcn_s_barrier()
; template <bool TWO, class MID> ...
;     ...
;     LDB(B1,1,1); WAIT_V(0); BAR; WAIT_L(0); MMA(0,1,At,B1); BAR;
;     LDA(At,1,1); BAR; WAIT_L(0); MMA(1,0,At,B0); MMA(1,1,At,B1); BAR; }
;   if(wr==0)BAR;
	ds_read_b128 v[130:133], v143
	ds_read_b128 v[148:151], v143 offset:1024
	ds_read_b128 v[208:211], v143 offset:2048
	ds_read_b128 v[220:223], v143 offset:3072
	s_waitcnt vmcnt(0)
	s_barrier
	s_waitcnt lgkmcnt(0)
	s_setprio 1
	v_mfma_f32_16x16x32_bf16 v[98:101], v[130:133], v[26:29], v[212:215]
	v_mfma_f32_16x16x32_bf16 v[26:29], v[208:211], v[26:29], v[168:171]
	v_mfma_f32_16x16x32_bf16 v[114:117], v[220:223], v[30:33], v[26:29]
	v_mfma_f32_16x16x32_bf16 v[26:29], v[130:133], v[42:45], v[86:89]
	v_mfma_f32_16x16x32_bf16 v[102:105], v[148:151], v[46:49], v[26:29]
	v_mfma_f32_16x16x32_bf16 v[26:29], v[208:211], v[42:45], v[82:85]
	v_mfma_f32_16x16x32_bf16 v[118:121], v[148:151], v[30:33], v[98:101]
	v_mfma_f32_16x16x32_bf16 v[98:101], v[220:223], v[46:49], v[26:29]
	v_mfma_f32_16x16x32_bf16 v[26:29], v[130:133], v[184:187], v[172:175]
	v_mfma_f32_16x16x32_bf16 v[86:89], v[148:151], v[188:191], v[26:29]
	v_mfma_f32_16x16x32_bf16 v[26:29], v[208:211], v[184:187], v[176:179]
	v_mfma_f32_16x16x32_bf16 v[82:85], v[220:223], v[188:191], v[26:29]
	v_mfma_f32_16x16x32_bf16 v[26:29], v[130:133], v[196:199], v[70:73]
	v_mfma_f32_16x16x32_bf16 v[70:73], v[148:151], v[204:207], v[26:29]
	v_mfma_f32_16x16x32_bf16 v[26:29], v[208:211], v[196:199], v[66:69]
	v_mfma_f32_16x16x32_bf16 v[66:69], v[220:223], v[204:207], v[26:29]
	s_setprio 0
	s_barrier
	ds_read_b128 v[168:171], v141 offset:49152
	ds_read_b128 v[140:143], v141 offset:50176
	ds_read_b128 v[172:175], v139 offset:49152
	ds_read_b128 v[176:179], v139 offset:50176
	ds_read_b128 v[184:187], v137 offset:49152
	ds_read_b128 v[136:139], v137 offset:50176
	ds_read_b128 v[188:191], v135 offset:49152
	ds_read_b128 v[196:199], v135 offset:50176
	s_barrier
	s_waitcnt lgkmcnt(0)
	s_setprio 1
	v_mfma_f32_16x16x32_bf16 v[26:29], v[10:13], v[168:171], v[62:65]
	v_mfma_f32_16x16x32_bf16 v[62:65], v[14:17], v[140:143], v[26:29]
	v_mfma_f32_16x16x32_bf16 v[26:29], v[180:183], v[168:171], v[58:61]
	v_mfma_f32_16x16x32_bf16 v[58:61], v[144:147], v[140:143], v[26:29]
	v_mfma_f32_16x16x32_bf16 v[26:29], v[10:13], v[172:175], v[54:57]
	v_mfma_f32_16x16x32_bf16 v[46:49], v[14:17], v[176:179], v[26:29]
	v_mfma_f32_16x16x32_bf16 v[26:29], v[180:183], v[172:175], v[50:53]
	v_mfma_f32_16x16x32_bf16 v[42:45], v[144:147], v[176:179], v[26:29]
	v_mfma_f32_16x16x32_bf16 v[26:29], v[10:13], v[184:187], v[200:203]
	v_mfma_f32_16x16x32_bf16 v[10:13], v[10:13], v[188:191], v[38:41]
	v_mfma_f32_16x16x32_bf16 v[30:33], v[14:17], v[136:139], v[26:29]
	v_mfma_f32_16x16x32_bf16 v[26:29], v[180:183], v[184:187], v[216:219]
	v_mfma_f32_16x16x32_bf16 v[14:17], v[14:17], v[196:199], v[10:13]
	v_mfma_f32_16x16x32_bf16 v[10:13], v[180:183], v[188:191], v[34:37]
	v_mfma_f32_16x16x32_bf16 v[26:29], v[144:147], v[136:139], v[26:29]
	v_mfma_f32_16x16x32_bf16 v[10:13], v[144:147], v[196:199], v[10:13]
	s_setprio 0
	s_setprio 1
	v_mfma_f32_16x16x32_bf16 v[34:37], v[130:133], v[168:171], v[152:155]
	v_mfma_f32_16x16x32_bf16 v[54:57], v[148:151], v[140:143], v[34:37]
	v_mfma_f32_16x16x32_bf16 v[34:37], v[208:211], v[168:171], v[156:159]
	v_mfma_f32_16x16x32_bf16 v[18:21], v[208:211], v[172:175], v[18:21]
	v_mfma_f32_16x16x32_bf16 v[50:53], v[220:223], v[140:143], v[34:37]
	v_mfma_f32_16x16x32_bf16 v[22:25], v[130:133], v[172:175], v[22:25]
	v_mfma_f32_16x16x32_bf16 v[34:37], v[220:223], v[176:179], v[18:21]
	v_mfma_f32_16x16x32_bf16 v[18:21], v[130:133], v[184:187], v[160:163]
	v_mfma_f32_16x16x32_bf16 v[38:41], v[148:151], v[176:179], v[22:25]
	v_mfma_f32_16x16x32_bf16 v[22:25], v[148:151], v[136:139], v[18:21]
	v_mfma_f32_16x16x32_bf16 v[18:21], v[208:211], v[184:187], v[164:167]
	v_mfma_f32_16x16x32_bf16 v[6:9], v[130:133], v[188:191], v[6:9]
	v_mfma_f32_16x16x32_bf16 v[2:5], v[208:211], v[188:191], v[2:5]
	v_mfma_f32_16x16x32_bf16 v[18:21], v[220:223], v[136:139], v[18:21]
	v_mfma_f32_16x16x32_bf16 v[6:9], v[148:151], v[196:199], v[6:9]
	v_mfma_f32_16x16x32_bf16 v[2:5], v[220:223], v[196:199], v[2:5]
	s_setprio 0
	v_cmp_gt_u32_e32 vcc, s30, v1
	s_barrier
	s_and_saveexec_b64 s[0:1], vcc
	s_cbranch_execz .LBB0_623
	s_barrier
